# scan operands Ktd/Vt/P stored fragment-major (coalesced scan loads + contiguous producer stores), on top of NSA coalesced loads
# speedup vs baseline: 1.0447x; 1.0290x over previous
.LBB0_208:
	s_add_i32 s27, s5, 64
	s_min_u32 s30, s27, 0x3e0
	s_lshl_b32 s30, s30, 1
	v_lshl_add_u64 v[180:181], v[154:155], 0, s[30:31]
	v_lshl_add_u64 v[184:185], v[158:159], 0, s[30:31]
	v_lshl_add_u64 v[188:189], v[160:161], 0, s[30:31]
	v_lshl_add_u64 v[192:193], v[162:163], 0, s[30:31]
	v_lshl_add_u64 v[196:197], v[156:157], 0, s[30:31]
	v_lshl_add_u64 v[200:201], v[164:165], 0, s[30:31]
	global_load_dwordx4 v[180:183], v[180:181], off
	ds_read_b128 v[204:207], v178 offset:32768
	global_load_dwordx4 v[184:187], v[184:185], off
	ds_read_b128 v[208:211], v178 offset:33792
	global_load_dwordx4 v[188:191], v[188:189], off
	ds_read_b128 v[212:215], v178 offset:34816
	global_load_dwordx4 v[192:195], v[192:193], off
	ds_read_b128 v[216:219], v178 offset:35840
	global_load_dwordx4 v[196:199], v[196:197], off
	ds_read_b128 v[222:225], v176
	global_load_dwordx4 v[200:203], v[200:201], off
	ds_read_b128 v[226:229], v176 offset:1024
	ds_read_b128 v[230:233], v176 offset:2048
	ds_read_b128 v[234:237], v176 offset:3072
	ds_read_b128 v[238:241], v176 offset:4096
	ds_read_b128 v[242:245], v176 offset:5120
	ds_read_b128 v[246:249], v176 offset:6144
	ds_read_b128 v[250:253], v176 offset:7168
	s_setprio 1
	s_waitcnt lgkmcnt(7)
	v_mfma_f32_16x16x32_bf16 v[124:127], v[222:225], v[204:207], v[124:127]
	v_mfma_f32_16x16x32_bf16 v[120:123], v[222:225], v[208:211], v[120:123]
	v_mfma_f32_16x16x32_bf16 v[60:63], v[222:225], v[212:215], v[60:63]
	v_mfma_f32_16x16x32_bf16 v[56:59], v[222:225], v[216:219], v[56:59]
	s_waitcnt lgkmcnt(6)
	v_mfma_f32_16x16x32_bf16 v[116:119], v[226:229], v[204:207], v[116:119]
	v_mfma_f32_16x16x32_bf16 v[112:115], v[226:229], v[208:211], v[112:115]
	v_mfma_f32_16x16x32_bf16 v[52:55], v[226:229], v[212:215], v[52:55]
	v_mfma_f32_16x16x32_bf16 v[48:51], v[226:229], v[216:219], v[48:51]
	s_waitcnt lgkmcnt(5)
	v_mfma_f32_16x16x32_bf16 v[108:111], v[230:233], v[204:207], v[108:111]
	v_mfma_f32_16x16x32_bf16 v[104:107], v[230:233], v[208:211], v[104:107]
	v_mfma_f32_16x16x32_bf16 v[44:47], v[230:233], v[212:215], v[44:47]
	v_mfma_f32_16x16x32_bf16 v[40:43], v[230:233], v[216:219], v[40:43]
	s_waitcnt lgkmcnt(4)
	v_mfma_f32_16x16x32_bf16 v[100:103], v[234:237], v[204:207], v[100:103]
	v_mfma_f32_16x16x32_bf16 v[96:99], v[234:237], v[208:211], v[96:99]
	v_mfma_f32_16x16x32_bf16 v[36:39], v[234:237], v[212:215], v[36:39]
	v_mfma_f32_16x16x32_bf16 v[32:35], v[234:237], v[216:219], v[32:35]
	s_waitcnt lgkmcnt(3)
	v_mfma_f32_16x16x32_bf16 v[92:95], v[238:241], v[204:207], v[92:95]
	v_mfma_f32_16x16x32_bf16 v[88:91], v[238:241], v[208:211], v[88:91]
	v_mfma_f32_16x16x32_bf16 v[28:31], v[238:241], v[212:215], v[28:31]
	v_mfma_f32_16x16x32_bf16 v[24:27], v[238:241], v[216:219], v[24:27]
	s_waitcnt lgkmcnt(2)
	v_mfma_f32_16x16x32_bf16 v[84:87], v[242:245], v[204:207], v[84:87]
	v_mfma_f32_16x16x32_bf16 v[80:83], v[242:245], v[208:211], v[80:83]
	v_mfma_f32_16x16x32_bf16 v[20:23], v[242:245], v[212:215], v[20:23]
	v_mfma_f32_16x16x32_bf16 v[16:19], v[242:245], v[216:219], v[16:19]
	s_waitcnt lgkmcnt(1)
	v_mfma_f32_16x16x32_bf16 v[76:79], v[246:249], v[204:207], v[76:79]
	v_mfma_f32_16x16x32_bf16 v[72:75], v[246:249], v[208:211], v[72:75]
	v_mfma_f32_16x16x32_bf16 v[12:15], v[246:249], v[212:215], v[12:15]
	v_mfma_f32_16x16x32_bf16 v[8:11], v[246:249], v[216:219], v[8:11]
	s_waitcnt lgkmcnt(0)
	v_mfma_f32_16x16x32_bf16 v[68:71], v[250:253], v[204:207], v[68:71]
	v_mfma_f32_16x16x32_bf16 v[64:67], v[250:253], v[208:211], v[64:67]
	v_mfma_f32_16x16x32_bf16 v[4:7], v[250:253], v[212:215], v[4:7]
	v_mfma_f32_16x16x32_bf16 v[0:3], v[250:253], v[216:219], v[0:3]
	s_setprio 0
	s_min_u32 s5, s5, 0x380
	s_lshl_b32 s30, s5, 1
	s_mov_b32 s53, s31
	s_add_i32 s52, s30, 0xc0
	s_waitcnt vmcnt(11)
	ds_write_b128 v152, v[128:131] offset:16384
	s_waitcnt vmcnt(9)
	ds_write_b128 v152, v[136:139] offset:20480
	s_waitcnt vmcnt(8)
	ds_write_b128 v152, v[140:143] offset:24576
	s_waitcnt vmcnt(7)
	ds_write_b128 v152, v[144:147] offset:28672
	s_waitcnt vmcnt(7)
	ds_write_b128 v152, v[132:135] offset:40960
	s_waitcnt vmcnt(6)
	ds_write_b128 v152, v[148:151] offset:45056
	v_lshl_add_u64 v[128:129], v[154:155], 0, s[30:31]
	v_lshl_add_u64 v[132:133], v[156:157], 0, s[30:31]
	v_lshl_add_u64 v[136:137], v[158:159], 0, s[52:53]
	v_lshl_add_u64 v[140:141], v[160:161], 0, s[52:53]
	v_lshl_add_u64 v[144:145], v[162:163], 0, s[52:53]
	v_lshl_add_u64 v[148:149], v[164:165], 0, s[52:53]
	s_waitcnt lgkmcnt(0)
	s_barrier
	global_load_dwordx4 v[128:131], v[128:129], off offset:192
	ds_read_b128 v[204:207], v175 offset:40960
	global_load_dwordx4 v[132:135], v[132:133], off offset:192
	ds_read_b128 v[208:211], v175 offset:41984
	global_load_dwordx4 v[136:139], v[136:137], off
	ds_read_b128 v[212:215], v175 offset:43008
	global_load_dwordx4 v[140:143], v[140:141], off
	ds_read_b128 v[216:219], v175 offset:44032
	global_load_dwordx4 v[144:147], v[144:145], off
	ds_read_b128 v[222:225], v177
	global_load_dwordx4 v[148:151], v[148:149], off
	ds_read_b128 v[226:229], v177 offset:1024
	ds_read_b128 v[230:233], v177 offset:2048
	ds_read_b128 v[234:237], v177 offset:3072
	ds_read_b128 v[238:241], v177 offset:4096
	ds_read_b128 v[242:245], v177 offset:5120
	ds_read_b128 v[246:249], v177 offset:6144
	ds_read_b128 v[250:253], v177 offset:7168
	s_setprio 1
	s_waitcnt lgkmcnt(7)
	v_mfma_f32_16x16x32_bf16 v[124:127], v[222:225], v[204:207], v[124:127]
	v_mfma_f32_16x16x32_bf16 v[120:123], v[222:225], v[208:211], v[120:123]
	v_mfma_f32_16x16x32_bf16 v[60:63], v[222:225], v[212:215], v[60:63]
	v_mfma_f32_16x16x32_bf16 v[56:59], v[222:225], v[216:219], v[56:59]
	s_waitcnt lgkmcnt(6)
	v_mfma_f32_16x16x32_bf16 v[116:119], v[226:229], v[204:207], v[116:119]
	v_mfma_f32_16x16x32_bf16 v[112:115], v[226:229], v[208:211], v[112:115]
	v_mfma_f32_16x16x32_bf16 v[52:55], v[226:229], v[212:215], v[52:55]
	v_mfma_f32_16x16x32_bf16 v[48:51], v[226:229], v[216:219], v[48:51]
	s_waitcnt lgkmcnt(5)
	v_mfma_f32_16x16x32_bf16 v[108:111], v[230:233], v[204:207], v[108:111]
	v_mfma_f32_16x16x32_bf16 v[104:107], v[230:233], v[208:211], v[104:107]
	v_mfma_f32_16x16x32_bf16 v[44:47], v[230:233], v[212:215], v[44:47]
	v_mfma_f32_16x16x32_bf16 v[40:43], v[230:233], v[216:219], v[40:43]
	s_waitcnt lgkmcnt(4)
	v_mfma_f32_16x16x32_bf16 v[100:103], v[234:237], v[204:207], v[100:103]
	v_mfma_f32_16x16x32_bf16 v[96:99], v[234:237], v[208:211], v[96:99]
	v_mfma_f32_16x16x32_bf16 v[36:39], v[234:237], v[212:215], v[36:39]
	v_mfma_f32_16x16x32_bf16 v[32:35], v[234:237], v[216:219], v[32:35]
	s_waitcnt lgkmcnt(3)
	v_mfma_f32_16x16x32_bf16 v[92:95], v[238:241], v[204:207], v[92:95]
	v_mfma_f32_16x16x32_bf16 v[88:91], v[238:241], v[208:211], v[88:91]
	v_mfma_f32_16x16x32_bf16 v[28:31], v[238:241], v[212:215], v[28:31]
	v_mfma_f32_16x16x32_bf16 v[24:27], v[238:241], v[216:219], v[24:27]
	s_waitcnt lgkmcnt(2)
	v_mfma_f32_16x16x32_bf16 v[84:87], v[242:245], v[204:207], v[84:87]
	v_mfma_f32_16x16x32_bf16 v[80:83], v[242:245], v[208:211], v[80:83]
	v_mfma_f32_16x16x32_bf16 v[20:23], v[242:245], v[212:215], v[20:23]
	v_mfma_f32_16x16x32_bf16 v[16:19], v[242:245], v[216:219], v[16:19]
	s_waitcnt lgkmcnt(1)
	v_mfma_f32_16x16x32_bf16 v[76:79], v[246:249], v[204:207], v[76:79]
	v_mfma_f32_16x16x32_bf16 v[72:75], v[246:249], v[208:211], v[72:75]
	v_mfma_f32_16x16x32_bf16 v[12:15], v[246:249], v[212:215], v[12:15]
	v_mfma_f32_16x16x32_bf16 v[8:11], v[246:249], v[216:219], v[8:11]
	s_waitcnt lgkmcnt(0)
	v_mfma_f32_16x16x32_bf16 v[68:71], v[250:253], v[204:207], v[68:71]
	v_mfma_f32_16x16x32_bf16 v[64:67], v[250:253], v[208:211], v[64:67]
	v_mfma_f32_16x16x32_bf16 v[4:7], v[250:253], v[212:215], v[4:7]
	v_mfma_f32_16x16x32_bf16 v[0:3], v[250:253], v[216:219], v[0:3]
	s_setprio 0
	s_add_i32 s1, s1, 2
	s_cmp_lt_u32 s1, 30
	s_mov_b32 s5, s27
	s_waitcnt vmcnt(11)
	ds_write_b128 v152, v[180:183]
	s_waitcnt vmcnt(10)
	ds_write_b128 v152, v[184:187] offset:4096
	s_waitcnt vmcnt(9)
	ds_write_b128 v152, v[188:191] offset:8192
	s_waitcnt vmcnt(8)
	ds_write_b128 v152, v[192:195] offset:12288
	s_waitcnt vmcnt(7)
	ds_write_b128 v152, v[196:199] offset:32768
	s_waitcnt vmcnt(6)
	ds_write_b128 v152, v[200:203] offset:36864
	s_waitcnt lgkmcnt(0)
	s_barrier
	s_cbranch_scc1 .LBB0_208
	s_waitcnt vmcnt(5)
	v_mov_b32_e32 v128, v220
	s_cmp_gt_i32 s26, 15
	v_and_b32_e32 v158, 15, v128
	v_and_b32_e32 v160, 64, v128
	v_and_b32_e32 v129, 0xffffff80, v128
	v_lshrrev_b32_e32 v128, 2, v128
	v_add_u32_e32 v130, s4, v129
	v_and_b32_e32 v159, 12, v128
	s_waitcnt vmcnt(3)
	v_or_b32_e32 v136, v130, v159
	v_ashrrev_i32_e32 v128, 14, v130
	s_waitcnt vmcnt(0)
	v_or_b32_e32 v150, 16, v136
	v_or_b32_e32 v148, 32, v136
	v_or_b32_e32 v146, 48, v136
	v_or_b32_e32 v142, 64, v136
	v_or_b32_e32 v140, 0x50, v136
	v_or_b32_e32 v138, 0x60, v136
	v_or_b32_e32 v134, 0x70, v136
	s_mov_b64 s[4:5], -1
	v_ashrrev_i32_e32 v137, 31, v136
	v_lshlrev_b32_e32 v132, 1, v159
	v_and_b32_e32 v252, 8, v159
	v_lshlrev_b32_e32 v252, 5, v252
	v_and_b32_e32 v253, 4, v159
	v_lshl_or_b32 v252, v253, 1, v252
	v_lshl_or_b32 v252, v158, 4, v252
	v_mov_b32_e32 v253, 0
	v_ashrrev_i32_e32 v129, 31, v128
	v_ashrrev_i32_e32 v151, 31, v150
	v_ashrrev_i32_e32 v149, 31, v148
	v_ashrrev_i32_e32 v147, 31, v146
	v_ashrrev_i32_e32 v143, 31, v142
	v_ashrrev_i32_e32 v141, 31, v140
	v_ashrrev_i32_e32 v139, 31, v138
	v_ashrrev_i32_e32 v135, 31, v134
	s_cbranch_scc0 .LBB0_211
	v_lshl_add_u64 v[144:145], v[136:137], 2, s[8:9]
	global_load_dwordx4 v[162:165], v[144:145], off
	s_add_i32 s1, s0, 0xfffff800
	s_and_b32 s5, s0, 0x180
	s_ashr_i32 s4, s1, 9
	v_or_b32_e32 v154, s5, v160
	s_ashr_i32 s5, s4, 31
	v_lshlrev_b64 v[144:145], 9, v[128:129]
	s_lshl_b64 s[4:5], s[4:5], 7
	v_lshrrev_b32_e32 v152, 7, v130
	v_lshl_add_u64 v[130:131], v[144:145], 0, s[4:5]
	v_and_or_b32 v130, v152, s38, v130
	v_lshlrev_b64 v[130:131], 16, v[130:131]
	v_mov_b32_e32 v133, v153
	v_lshl_or_b32 v130, v154, 7, v130
	v_lshl_add_u64 v[178:179], s[12:13], 0, v[252:253]
	v_mov_b32_e32 v145, v131
	v_mov_b32_e32 v181, v131
	v_lshlrev_b64 v[156:157], 1, v[130:131]
	v_or_b32_e32 v144, 0x800, v130
	v_or_b32_e32 v180, 0x1000, v130
	v_or_b32_e32 v130, 0x1800, v130
	v_lshl_add_u64 v[182:183], v[178:179], 0, v[156:157]
	v_lshlrev_b64 v[154:155], 1, v[144:145]
	v_lshlrev_b64 v[144:145], 1, v[180:181]
	v_lshlrev_b64 v[130:131], 1, v[130:131]
	v_lshl_add_u64 v[176:177], v[150:151], 2, s[8:9]
	v_lshl_add_u64 v[180:181], v[178:179], 0, v[154:155]
	v_lshl_add_u64 v[184:185], v[178:179], 0, v[144:145]
	v_lshl_add_u64 v[178:179], v[178:179], 0, v[130:131]
	s_waitcnt vmcnt(0)
	v_mul_f32_e32 v133, v124, v162
	v_mul_f32_e32 v152, v125, v163
	v_mul_f32_e32 v161, v126, v164
	v_mul_f32_e32 v175, v127, v165
	v_mul_f32_e32 v186, v120, v162
	v_mul_f32_e32 v187, v121, v163
	v_mul_f32_e32 v188, v122, v164
	v_mul_f32_e32 v189, v123, v165
	v_mul_f32_e32 v190, v60, v162
	v_mul_f32_e32 v191, v61, v163
	v_mul_f32_e32 v194, v56, v162
	v_mul_f32_e32 v195, v57, v163
	v_cvt_pk_bf16_f32 v162, v133, v152
	v_cvt_pk_bf16_f32 v163, v161, v175
	v_mul_f32_e32 v192, v62, v164
	v_mul_f32_e32 v193, v63, v165
	v_mul_f32_e32 v196, v58, v164
	v_mul_f32_e32 v197, v59, v165
	v_cvt_pk_bf16_f32 v164, v186, v187
	v_cvt_pk_bf16_f32 v165, v188, v189
	v_cvt_pk_bf16_f32 v186, v190, v191
	v_cvt_pk_bf16_f32 v187, v192, v193
	v_cvt_pk_bf16_f32 v188, v194, v195
	v_cvt_pk_bf16_f32 v189, v196, v197
	global_store_dwordx2 v[182:183], v[162:163], off
	global_store_dwordx2 v[180:181], v[164:165], off
	global_store_dwordx2 v[184:185], v[186:187], off
	global_store_dwordx2 v[178:179], v[188:189], off
	global_load_dwordx4 v[162:165], v[176:177], off
	v_bitop3_b32 v133, v136, 28, 16 bitop3:0xc8
	v_lshlrev_b32_e32 v152, 1, v133
	v_lshl_add_u64 v[178:179], s[12:13], 0, v[252:253]
	v_lshl_add_u64 v[180:181], v[178:179], 0, v[156:157]
	v_lshl_add_u64 v[176:177], v[148:149], 2, s[8:9]
	v_lshl_add_u64 v[182:183], v[178:179], 0, v[154:155]
	v_lshl_add_u64 v[184:185], v[178:179], 0, v[144:145]
	v_lshl_add_u64 v[178:179], v[178:179], 0, v[130:131]
	s_waitcnt vmcnt(0)
	v_mul_f32_e32 v133, v116, v162
	v_mul_f32_e32 v152, v117, v163
	v_mul_f32_e32 v161, v118, v164
	v_mul_f32_e32 v175, v119, v165
	v_mul_f32_e32 v186, v112, v162
	v_mul_f32_e32 v187, v113, v163
	v_mul_f32_e32 v188, v114, v164
	v_mul_f32_e32 v189, v115, v165
	v_mul_f32_e32 v190, v52, v162
	v_mul_f32_e32 v191, v53, v163
	v_mul_f32_e32 v194, v48, v162
	v_mul_f32_e32 v195, v49, v163
	v_cvt_pk_bf16_f32 v162, v133, v152
	v_cvt_pk_bf16_f32 v163, v161, v175
	v_mul_f32_e32 v192, v54, v164
	v_mul_f32_e32 v193, v55, v165
	v_mul_f32_e32 v196, v50, v164
	v_mul_f32_e32 v197, v51, v165
	v_cvt_pk_bf16_f32 v164, v186, v187
	v_cvt_pk_bf16_f32 v165, v188, v189
	v_cvt_pk_bf16_f32 v186, v190, v191
	v_cvt_pk_bf16_f32 v187, v192, v193
	v_cvt_pk_bf16_f32 v188, v194, v195
	v_cvt_pk_bf16_f32 v189, v196, v197
	global_store_dwordx2 v[180:181], v[162:163], off offset:512
	global_store_dwordx2 v[182:183], v[164:165], off offset:512
	global_store_dwordx2 v[184:185], v[186:187], off offset:512
	global_store_dwordx2 v[178:179], v[188:189], off offset:512
	global_load_dwordx4 v[162:165], v[176:177], off
	v_bitop3_b32 v133, v136, 44, 32 bitop3:0xc8
	v_lshlrev_b32_e32 v152, 1, v133
	v_lshl_add_u64 v[178:179], s[12:13], 0, v[252:253]
	v_lshl_add_u64 v[180:181], v[178:179], 0, v[156:157]
	v_lshl_add_u64 v[176:177], v[146:147], 2, s[8:9]
	v_lshl_add_u64 v[182:183], v[178:179], 0, v[154:155]
	v_lshl_add_u64 v[184:185], v[178:179], 0, v[144:145]
	v_lshl_add_u64 v[178:179], v[178:179], 0, v[130:131]
	s_waitcnt vmcnt(0)
	v_mul_f32_e32 v133, v108, v162
	v_mul_f32_e32 v152, v109, v163
	v_mul_f32_e32 v161, v110, v164
	v_mul_f32_e32 v175, v111, v165
	v_mul_f32_e32 v186, v104, v162
	v_mul_f32_e32 v187, v105, v163
	v_mul_f32_e32 v188, v106, v164
	v_mul_f32_e32 v189, v107, v165
	v_mul_f32_e32 v190, v44, v162
	v_mul_f32_e32 v191, v45, v163
	v_mul_f32_e32 v194, v40, v162
	v_mul_f32_e32 v195, v41, v163
	v_cvt_pk_bf16_f32 v162, v133, v152
	v_cvt_pk_bf16_f32 v163, v161, v175
	v_mul_f32_e32 v192, v46, v164
	v_mul_f32_e32 v193, v47, v165
	v_mul_f32_e32 v196, v42, v164
	v_mul_f32_e32 v197, v43, v165
	v_cvt_pk_bf16_f32 v164, v186, v187
	v_cvt_pk_bf16_f32 v165, v188, v189
	v_cvt_pk_bf16_f32 v186, v190, v191
	v_cvt_pk_bf16_f32 v187, v192, v193
	v_cvt_pk_bf16_f32 v188, v194, v195
	v_cvt_pk_bf16_f32 v189, v196, v197
	global_store_dwordx2 v[180:181], v[162:163], off offset:1024
	global_store_dwordx2 v[182:183], v[164:165], off offset:1024
	global_store_dwordx2 v[184:185], v[186:187], off offset:1024
	global_store_dwordx2 v[178:179], v[188:189], off offset:1024
	global_load_dwordx4 v[162:165], v[176:177], off
	v_bitop3_b32 v133, v136, 60, 48 bitop3:0xc8
	v_lshlrev_b32_e32 v152, 1, v133
	v_lshl_add_u64 v[178:179], s[12:13], 0, v[252:253]
	v_lshl_add_u64 v[180:181], v[178:179], 0, v[156:157]
	v_lshl_add_u64 v[176:177], v[142:143], 2, s[8:9]
	v_lshl_add_u64 v[182:183], v[178:179], 0, v[154:155]
	v_lshl_add_u64 v[184:185], v[178:179], 0, v[144:145]
	v_lshl_add_u64 v[178:179], v[178:179], 0, v[130:131]
	s_waitcnt vmcnt(0)
	v_mul_f32_e32 v133, v100, v162
	v_mul_f32_e32 v152, v101, v163
	v_mul_f32_e32 v161, v102, v164
	v_mul_f32_e32 v175, v103, v165
	v_mul_f32_e32 v186, v96, v162
	v_mul_f32_e32 v187, v97, v163
	v_mul_f32_e32 v188, v98, v164
	v_mul_f32_e32 v189, v99, v165
	v_mul_f32_e32 v190, v36, v162
	v_mul_f32_e32 v191, v37, v163
	v_mul_f32_e32 v194, v32, v162
	v_mul_f32_e32 v195, v33, v163
	v_cvt_pk_bf16_f32 v162, v133, v152
	v_cvt_pk_bf16_f32 v163, v161, v175
	v_mul_f32_e32 v192, v38, v164
	v_mul_f32_e32 v193, v39, v165
	v_mul_f32_e32 v196, v34, v164
	v_mul_f32_e32 v197, v35, v165
	v_cvt_pk_bf16_f32 v164, v186, v187
	v_cvt_pk_bf16_f32 v165, v188, v189
	v_cvt_pk_bf16_f32 v186, v190, v191
	v_cvt_pk_bf16_f32 v187, v192, v193
	v_cvt_pk_bf16_f32 v188, v194, v195
	v_cvt_pk_bf16_f32 v189, v196, v197
	global_store_dwordx2 v[180:181], v[162:163], off offset:1536
	global_store_dwordx2 v[182:183], v[164:165], off offset:1536
	global_store_dwordx2 v[184:185], v[186:187], off offset:1536
	global_store_dwordx2 v[178:179], v[188:189], off offset:1536
	global_load_dwordx4 v[162:165], v[176:177], off
	v_bitop3_b32 v133, v136, s39, 64 bitop3:0xc8
	v_lshlrev_b32_e32 v152, 1, v133
	v_lshl_add_u64 v[178:179], s[12:13], 0, v[252:253]
	v_lshl_add_u64 v[180:181], v[178:179], 0, v[156:157]
	v_lshl_add_u64 v[176:177], v[140:141], 2, s[8:9]
	v_lshl_add_u64 v[182:183], v[178:179], 0, v[154:155]
	v_lshl_add_u64 v[184:185], v[178:179], 0, v[144:145]
	v_lshl_add_u64 v[178:179], v[178:179], 0, v[130:131]
	s_waitcnt vmcnt(0)
	v_mul_f32_e32 v133, v92, v162
	v_mul_f32_e32 v152, v93, v163
	v_mul_f32_e32 v161, v94, v164
	v_mul_f32_e32 v175, v95, v165
	v_mul_f32_e32 v186, v88, v162
	v_mul_f32_e32 v187, v89, v163
	v_mul_f32_e32 v188, v90, v164
	v_mul_f32_e32 v189, v91, v165
	v_mul_f32_e32 v190, v28, v162
	v_mul_f32_e32 v191, v29, v163
	v_mul_f32_e32 v194, v24, v162
	v_mul_f32_e32 v195, v25, v163
	v_cvt_pk_bf16_f32 v162, v133, v152
	v_cvt_pk_bf16_f32 v163, v161, v175
	v_mul_f32_e32 v192, v30, v164
	v_mul_f32_e32 v193, v31, v165
	v_mul_f32_e32 v196, v26, v164
	v_mul_f32_e32 v197, v27, v165
	v_cvt_pk_bf16_f32 v164, v186, v187
	v_cvt_pk_bf16_f32 v165, v188, v189
	v_cvt_pk_bf16_f32 v186, v190, v191
	v_cvt_pk_bf16_f32 v187, v192, v193
	v_cvt_pk_bf16_f32 v188, v194, v195
	v_cvt_pk_bf16_f32 v189, v196, v197
	global_store_dwordx2 v[180:181], v[162:163], off offset:2048
	global_store_dwordx2 v[182:183], v[164:165], off offset:2048
	global_store_dwordx2 v[184:185], v[186:187], off offset:2048
	global_store_dwordx2 v[178:179], v[188:189], off offset:2048
	global_load_dwordx4 v[162:165], v[176:177], off
	v_bitop3_b32 v133, v136, s40, v166 bitop3:0xc8
	v_lshlrev_b32_e32 v152, 1, v133
	v_lshl_add_u64 v[178:179], s[12:13], 0, v[252:253]
	v_lshl_add_u64 v[180:181], v[178:179], 0, v[156:157]
	v_lshl_add_u64 v[176:177], v[138:139], 2, s[8:9]
	v_lshl_add_u64 v[182:183], v[178:179], 0, v[154:155]
	v_lshl_add_u64 v[184:185], v[178:179], 0, v[144:145]
	v_lshl_add_u64 v[178:179], v[178:179], 0, v[130:131]
	s_waitcnt vmcnt(0)
	v_mul_f32_e32 v133, v84, v162
	v_mul_f32_e32 v152, v85, v163
	v_mul_f32_e32 v161, v86, v164
	v_mul_f32_e32 v175, v87, v165
	v_mul_f32_e32 v186, v80, v162
	v_mul_f32_e32 v187, v81, v163
	v_mul_f32_e32 v188, v82, v164
	v_mul_f32_e32 v189, v83, v165
	v_mul_f32_e32 v190, v20, v162
	v_mul_f32_e32 v191, v21, v163
	v_mul_f32_e32 v194, v16, v162
	v_mul_f32_e32 v195, v17, v163
	v_cvt_pk_bf16_f32 v162, v133, v152
	v_cvt_pk_bf16_f32 v163, v161, v175
	v_mul_f32_e32 v192, v22, v164
	v_mul_f32_e32 v193, v23, v165
	v_mul_f32_e32 v196, v18, v164
	v_mul_f32_e32 v197, v19, v165
	v_cvt_pk_bf16_f32 v164, v186, v187
	v_cvt_pk_bf16_f32 v165, v188, v189
	v_cvt_pk_bf16_f32 v186, v190, v191
	v_cvt_pk_bf16_f32 v187, v192, v193
	v_cvt_pk_bf16_f32 v188, v194, v195
	v_cvt_pk_bf16_f32 v189, v196, v197
	global_store_dwordx2 v[180:181], v[162:163], off offset:2560
	global_store_dwordx2 v[182:183], v[164:165], off offset:2560
	global_store_dwordx2 v[184:185], v[186:187], off offset:2560
	global_store_dwordx2 v[178:179], v[188:189], off offset:2560
	global_load_dwordx4 v[162:165], v[176:177], off
	v_bitop3_b32 v133, v136, s41, v167 bitop3:0xc8
	v_lshlrev_b32_e32 v152, 1, v133
	v_lshl_add_u64 v[178:179], s[12:13], 0, v[252:253]
	v_lshl_add_u64 v[180:181], v[178:179], 0, v[156:157]
	v_lshl_add_u64 v[176:177], v[134:135], 2, s[8:9]
	v_lshl_add_u64 v[182:183], v[178:179], 0, v[154:155]
	v_lshl_add_u64 v[184:185], v[178:179], 0, v[144:145]
	v_lshl_add_u64 v[178:179], v[178:179], 0, v[130:131]
	s_waitcnt vmcnt(0)
	v_mul_f32_e32 v133, v76, v162
	v_mul_f32_e32 v152, v77, v163
	v_mul_f32_e32 v161, v78, v164
	v_mul_f32_e32 v175, v79, v165
	v_mul_f32_e32 v186, v72, v162
	v_mul_f32_e32 v187, v73, v163
	v_mul_f32_e32 v188, v74, v164
	v_mul_f32_e32 v189, v75, v165
	v_mul_f32_e32 v190, v12, v162
	v_mul_f32_e32 v191, v13, v163
	v_mul_f32_e32 v194, v8, v162
	v_mul_f32_e32 v195, v9, v163
	v_cvt_pk_bf16_f32 v162, v133, v152
	v_cvt_pk_bf16_f32 v163, v161, v175
	v_mul_f32_e32 v192, v14, v164
	v_mul_f32_e32 v193, v15, v165
	v_mul_f32_e32 v196, v10, v164
	v_mul_f32_e32 v197, v11, v165
	v_cvt_pk_bf16_f32 v164, v186, v187
	v_cvt_pk_bf16_f32 v165, v188, v189
	v_cvt_pk_bf16_f32 v186, v190, v191
	v_cvt_pk_bf16_f32 v187, v192, v193
	v_cvt_pk_bf16_f32 v188, v194, v195
	v_cvt_pk_bf16_f32 v189, v196, v197
	global_store_dwordx2 v[180:181], v[162:163], off offset:3072
	global_store_dwordx2 v[182:183], v[164:165], off offset:3072
	global_store_dwordx2 v[184:185], v[186:187], off offset:3072
	global_store_dwordx2 v[178:179], v[188:189], off offset:3072
	global_load_dwordx4 v[162:165], v[176:177], off
	v_bitop3_b32 v133, v136, s42, v168 bitop3:0xc8
	v_lshlrev_b32_e32 v152, 1, v133
	v_lshl_add_u64 v[176:177], s[12:13], 0, v[252:253]
	v_lshl_add_u64 v[156:157], v[176:177], 0, v[156:157]
	v_lshl_add_u64 v[154:155], v[176:177], 0, v[154:155]
	v_lshl_add_u64 v[144:145], v[176:177], 0, v[144:145]
	v_lshl_add_u64 v[130:131], v[176:177], 0, v[130:131]
	s_waitcnt vmcnt(0)
	v_mul_f32_e32 v133, v68, v162
	v_mul_f32_e32 v152, v69, v163
	v_mul_f32_e32 v161, v70, v164
	v_mul_f32_e32 v175, v71, v165
	v_mul_f32_e32 v176, v64, v162
	v_mul_f32_e32 v177, v65, v163
	v_mul_f32_e32 v178, v66, v164
	v_mul_f32_e32 v179, v67, v165
	v_mul_f32_e32 v180, v4, v162
	v_mul_f32_e32 v181, v5, v163
	v_mul_f32_e32 v184, v0, v162
	v_mul_f32_e32 v185, v1, v163
	v_cvt_pk_bf16_f32 v162, v133, v152
	v_cvt_pk_bf16_f32 v163, v161, v175
	v_mul_f32_e32 v182, v6, v164
	v_mul_f32_e32 v183, v7, v165
	v_mul_f32_e32 v186, v2, v164
	v_mul_f32_e32 v187, v3, v165
	v_cvt_pk_bf16_f32 v164, v176, v177
	v_cvt_pk_bf16_f32 v165, v178, v179
	v_cvt_pk_bf16_f32 v176, v180, v181
	v_cvt_pk_bf16_f32 v177, v182, v183
	v_cvt_pk_bf16_f32 v178, v184, v185
	v_cvt_pk_bf16_f32 v179, v186, v187
	global_store_dwordx2 v[156:157], v[162:163], off offset:3584
	global_store_dwordx2 v[154:155], v[164:165], off offset:3584
	global_store_dwordx2 v[144:145], v[176:177], off offset:3584
	global_store_dwordx2 v[130:131], v[178:179], off offset:3584
	s_cbranch_execnz .LBB0_206
	s_branch .LBB0_212

.LBB0_212:
	s_bfe_u32 s1, s0, 0x20008
	v_cvt_f32_ubyte0_e32 v130, s1
	v_sub_f32_e32 v130, 0xc0a00000, v130
	v_cmp_gt_f32_e32 vcc, s43, v130
	s_and_b32 s0, s0, 0x80
	s_and_b64 s[4:5], vcc, exec
	v_cndmask_b32_e32 v131, 0, v169, vcc
	v_add_f32_e32 v130, v130, v131
	v_exp_f32_e32 v130, v130
	s_cselect_b32 s4, 0xffffffc0, 0
	v_lshlrev_b64 v[128:129], 2, v[128:129]
	v_or_b32_e32 v128, s1, v128
	v_ldexp_f32 v133, v130, s4
	v_sub_f32_e32 v144, 1.0, v133
	v_add_f32_e32 v130, -1.0, v144
	v_sub_f32_e32 v131, v130, v144
	v_add_f32_e32 v131, 1.0, v131
	v_sub_f32_e64 v130, -v133, v130
	v_add_f32_e32 v145, v130, v131
	v_frexp_mant_f32_e32 v152, v144
	v_cvt_f64_f32_e32 v[130:131], v144
	v_frexp_exp_i32_f64_e32 v130, v[130:131]
	v_cmp_gt_f32_e32 vcc, s44, v152
	s_cmp_gt_u32 s26, 7
	s_mov_b64 s[4:5], -1
	v_subbrev_co_u32_e32 v152, vcc, 0, v130, vcc
	v_sub_u32_e32 v130, 0, v152
	v_ldexp_f32 v131, v144, v130
	v_add_f32_e32 v144, -1.0, v131
	v_add_f32_e32 v155, 1.0, v131
	v_ldexp_f32 v130, v145, v130
	v_add_f32_e32 v145, 1.0, v144
	v_add_f32_e32 v156, -1.0, v155
	v_sub_f32_e32 v145, v131, v145
	v_sub_f32_e32 v131, v131, v156
	v_add_f32_e32 v145, v130, v145
	v_add_f32_e32 v130, v130, v131
	v_add_f32_e32 v131, v155, v130
	v_rcp_f32_e32 v156, v131
	v_add_f32_e32 v154, v144, v145
	v_sub_f32_e32 v144, v154, v144
	v_sub_f32_e32 v144, v145, v144
	v_sub_f32_e32 v145, v131, v155
	v_sub_f32_e32 v130, v130, v145
	v_mul_f32_e32 v145, v154, v156
	v_mul_f32_e32 v155, v131, v145
	v_fma_f32 v157, v145, v131, -v155
	v_fmac_f32_e32 v157, v145, v130
	v_add_f32_e32 v161, v155, v157
	v_sub_f32_e32 v162, v154, v161
	v_sub_f32_e32 v154, v154, v162
	v_sub_f32_e32 v155, v161, v155
	v_sub_f32_e32 v154, v154, v161
	v_add_f32_e32 v144, v144, v154
	v_sub_f32_e32 v154, v155, v157
	v_add_f32_e32 v144, v154, v144
	v_add_f32_e32 v154, v162, v144
	v_mul_f32_e32 v155, v156, v154
	v_mul_f32_e32 v157, v131, v155
	v_fma_f32 v131, v155, v131, -v157
	v_fmac_f32_e32 v131, v155, v130
	v_sub_f32_e32 v130, v162, v154
	v_add_f32_e32 v130, v144, v130
	v_add_f32_e32 v144, v157, v131
	v_sub_f32_e32 v161, v154, v144
	v_sub_f32_e32 v154, v154, v161
	v_sub_f32_e32 v157, v144, v157
	v_sub_f32_e32 v144, v154, v144
	v_add_f32_e32 v130, v130, v144
	v_sub_f32_e32 v131, v157, v131
	v_add_f32_e32 v130, v131, v130
	v_add_f32_e32 v130, v161, v130
	v_mul_f32_e32 v144, v156, v130
	v_lshl_add_u64 v[130:131], v[136:137], 2, s[8:9]
	global_load_dwordx4 v[180:183], v[130:131], off
	v_add_f32_e32 v154, v145, v155
	v_sub_f32_e32 v137, v154, v145
	v_cvt_f32_i32_e32 v145, v152
	v_sub_f32_e32 v137, v155, v137
	v_add_f32_e32 v137, v137, v144
	v_add_f32_e32 v144, v154, v137
	v_mul_f32_e32 v156, 0x3f317218, v145
	v_fma_f32 v157, v145, s45, -v156
	v_mul_f32_e32 v152, v144, v144
	v_mov_b32_e32 v155, 0x3ecc95a3
	v_fmac_f32_e32 v157, 0xb102e308, v145
	v_sub_f32_e32 v145, v144, v154
	v_fmamk_f32 v155, v152, 0x3e9b6dac, v155
	v_sub_f32_e32 v137, v137, v145
	v_add_f32_e32 v145, v156, v157
	v_fmaak_f32 v155, v152, v155, 0x3f2aaada
	v_sub_f32_e32 v154, v145, v156
	v_ldexp_f32 v156, v144, 1
	v_mul_f32_e32 v144, v144, v152
	v_mul_f32_e32 v144, v144, v155
	v_add_f32_e32 v152, v156, v144
	v_sub_f32_e32 v155, v152, v156
	v_ldexp_f32 v137, v137, 1
	v_sub_f32_e32 v144, v144, v155
	v_add_f32_e32 v137, v137, v144
	v_add_f32_e32 v144, v152, v137
	v_sub_f32_e32 v152, v144, v152
	v_sub_f32_e32 v137, v137, v152
	v_add_f32_e32 v152, v145, v144
	v_sub_f32_e32 v155, v152, v145
	v_sub_f32_e32 v156, v152, v155
	v_sub_f32_e32 v154, v157, v154
	v_sub_f32_e32 v145, v145, v156
	v_sub_f32_e32 v144, v144, v155
	v_add_f32_e32 v144, v144, v145
	v_add_f32_e32 v145, v154, v137
	v_sub_f32_e32 v155, v145, v154
	v_add_f32_e32 v144, v145, v144
	v_sub_f32_e32 v156, v145, v155
	v_add_f32_e32 v145, v152, v144
	v_sub_f32_e32 v154, v154, v156
	v_sub_f32_e32 v137, v137, v155
	v_sub_f32_e32 v152, v145, v152
	v_add_f32_e32 v137, v137, v154
	v_sub_f32_e32 v144, v144, v152
	v_add_f32_e32 v137, v137, v144
	v_add_f32_e32 v137, v145, v137
	v_mov_b32_e32 v144, 0x7fc00000
	v_cmp_nlt_f32_e32 vcc, 1.0, v133
	v_or_b32_e32 v154, s0, v160
	s_cselect_b64 s[0:1], -1, 0
	v_cndmask_b32_e32 v137, v144, v137, vcc
	v_mov_b32_e32 v144, 0xff800000
	v_cmp_neq_f32_e32 vcc, 1.0, v133
	v_or_b32_e32 v197, v154, v158
	v_or_b32_e32 v195, 16, v197
	v_cndmask_b32_e32 v137, v144, v137, vcc
	v_cmp_gt_f32_e32 vcc, s46, v133
	v_lshlrev_b64 v[144:145], 14, v[128:129]
	v_lshlrev_b64 v[128:129], 15, v[128:129]
	v_cndmask_b32_e64 v137, v137, -v133, vcc
	v_lshrrev_b32_e32 v133, 1, v154
	v_or_b32_e32 v133, v133, v158
	v_cvt_f32_ubyte0_e32 v133, v133
	v_mul_f32_e32 v152, 0xbdd49a78, v133
	v_cmp_gt_f32_e32 vcc, s43, v152
	s_waitcnt vmcnt(0)
	v_mul_f32_e32 v120, v120, v180
	v_cndmask_b32_e32 v152, 0, v169, vcc
	v_fmac_f32_e32 v152, 0xbdd49a78, v133
	v_exp_f32_e32 v133, v152
	v_and_b32_e32 v152, 0x3f8c, v136
	v_cvt_f32_u32_e32 v160, v152
	v_cndmask_b32_e32 v155, 0, v170, vcc
	v_ldexp_f32 v133, v133, v155
	v_mul_f32_e32 v218, 0.15915494, v133
	v_mul_f32_e32 v133, v218, v160
	v_fma_f32 v155, v160, v218, -v133
	v_floor_f32_e32 v133, v133
	v_fma_f32 v133, v218, v160, -v133
	v_add_f32_e32 v133, v155, v133
	v_sin_f32_e32 v156, v133
	v_or_b32_e32 v157, 1, v152
	v_cos_f32_e32 v133, v133
	v_cvt_f32_u32_e32 v165, v157
	v_mul_f32_e32 v124, v124, v180
	v_mul_f32_e32 v155, v156, v120
	v_fma_f32 v157, v133, v124, -v155
	v_mul_f32_e32 v155, v133, v120
	v_mul_f32_e32 v120, v218, v165
	v_fmac_f32_e32 v155, v156, v124
	v_fma_f32 v124, v165, v218, -v120
	v_floor_f32_e32 v120, v120
	v_fma_f32 v120, v218, v165, -v120
	v_add_f32_e32 v120, v124, v120
	v_sin_f32_e32 v124, v120
	v_or_b32_e32 v156, 2, v152
	v_cos_f32_e32 v120, v120
	v_cvt_f32_u32_e32 v178, v156
	v_mul_f32_e32 v121, v121, v181
	v_mul_f32_e32 v125, v125, v181
	v_mul_f32_e32 v133, v124, v121
	v_fma_f32 v163, v120, v125, -v133
	v_mul_f32_e32 v161, v120, v121
	v_mul_f32_e32 v120, v218, v178
	v_fma_f32 v121, v178, v218, -v120
	v_floor_f32_e32 v120, v120
	v_fma_f32 v120, v218, v178, -v120
	v_add_f32_e32 v120, v121, v120
	v_fmac_f32_e32 v161, v124, v125
	v_sin_f32_e32 v121, v120
	v_mul_f32_e32 v124, v126, v182
	v_or_b32_e32 v126, 3, v152
	v_cos_f32_e32 v120, v120
	v_cvt_f32_u32_e32 v181, v126
	v_mul_f32_e32 v122, v122, v182
	v_mul_f32_e32 v125, v121, v122
	v_fma_f32 v176, v120, v124, -v125
	v_mul_f32_e32 v126, v120, v122
	v_mul_f32_e32 v120, v218, v181
	v_fmac_f32_e32 v126, v121, v124
	v_fma_f32 v121, v181, v218, -v120
	v_floor_f32_e32 v120, v120
	v_fma_f32 v120, v218, v181, -v120
	v_add_f32_e32 v120, v121, v120
	v_sin_f32_e32 v121, v120
	v_cos_f32_e32 v120, v120
	v_mul_f32_e32 v123, v123, v183
	v_mul_f32_e32 v122, v127, v183
	v_mul_f32_e32 v124, v121, v123
	v_mul_f32_e32 v127, v120, v123
	v_fma_f32 v179, v120, v122, -v124
	v_fmac_f32_e32 v127, v121, v122
	v_or_b32_e32 v120, v144, v152
	v_mov_b32_e32 v121, v145
	v_xor_b32_e32 v124, 0x7f, v159
	v_lshlrev_b64 v[120:121], 9, v[120:121]
	v_sub_u32_e32 v125, 0x7e, v159
	v_sub_u32_e32 v133, 0x7d, v159
	v_sub_u32_e32 v156, 0x7c, v159
	v_lshlrev_b32_e32 v159, 1, v152
	s_and_b64 vcc, exec, s[0:1]
	v_lshl_add_u64 v[122:123], s[16:17], 0, v[120:121]
	v_lshlrev_b32_e32 v152, 1, v197
	v_cvt_f32_ubyte0_e32 v177, v124
	v_cvt_f32_ubyte0_e32 v175, v125
	v_cvt_f32_ubyte0_e32 v164, v133
	v_cvt_f32_ubyte0_e32 v162, v156
	v_and_or_b32 v156, v159, s50, v128
	s_cbranch_vccz .LBB0_214
	v_mul_f32_e32 v133, 0x3d800000, v157
	v_mul_f32_e32 v182, 0x3d800000, v163
	v_bfe_u32 v124, v133, 16, 1
	v_bfe_u32 v183, v182, 16, 1
	v_add3_u32 v180, v133, v124, s47
	v_lshl_add_u64 v[124:125], v[122:123], 0, v[152:153]
	v_mul_f32_e32 v184, 0x3d800000, v161
	v_add3_u32 v183, v182, v183, s47
	global_store_short_d16_hi v[124:125], v183, off offset:512
	v_bfe_u32 v183, v184, 16, 1
	v_add3_u32 v183, v184, v183, s47
	global_store_short_d16_hi v[124:125], v183, off offset:544
	v_mul_f32_e32 v183, v137, v175
	v_mul_f32_e32 v183, 0x3fb8aa3b, v183
	v_exp_f32_e32 v185, v183
	v_mul_f32_e32 v183, 0x3d800000, v176
	v_mul_f32_e32 v188, 0x3d800000, v179
	v_bfe_u32 v187, v183, 16, 1
	v_bfe_u32 v190, v188, 16, 1
	v_mul_f32_e32 v159, 0x3d800000, v155
	v_mul_f32_e32 v186, 0x3d800000, v126
	v_add3_u32 v187, v183, v187, s47
	v_mul_f32_e32 v189, 0x3d800000, v127
	v_add3_u32 v190, v188, v190, s47
	global_store_short_d16_hi v[124:125], v180, off
	v_bfe_u32 v180, v159, 16, 1
	global_store_short_d16_hi v[124:125], v187, off offset:1024
	v_bfe_u32 v187, v186, 16, 1
	global_store_short_d16_hi v[124:125], v190, off offset:1536
	v_bfe_u32 v190, v189, 16, 1
	v_add3_u32 v180, v159, v180, s47
	v_add3_u32 v187, v186, v187, s47
	v_add3_u32 v190, v189, v190, s47
	global_store_short_d16_hi v[124:125], v180, off offset:32
	v_mul_f32_e32 v180, v137, v177
	global_store_short_d16_hi v[124:125], v187, off offset:1056
	global_store_short_d16_hi v[124:125], v190, off offset:1568
	v_mul_f32_e32 v124, v137, v162
	v_mul_f32_e32 v180, 0x3fb8aa3b, v180
	v_mul_f32_e32 v187, v137, v164
	v_mul_f32_e32 v124, 0x3fb8aa3b, v124
	v_exp_f32_e32 v180, v180
	v_mul_f32_e32 v187, 0x3fb8aa3b, v187
	v_exp_f32_e32 v190, v124
	v_exp_f32_e32 v187, v187
	v_mul_f32_e32 v124, v180, v133
	v_mul_f32_e32 v125, v185, v182
	v_mul_f32_e32 v182, v190, v188
	v_mul_f32_e32 v133, v187, v183
	v_cvt_pk_bf16_f32 v124, v124, v125
	v_cvt_pk_bf16_f32 v125, v133, v182
	v_or_b32_e32 v182, v156, v197
	v_mov_b32_e32 v183, v129
	v_and_b32_e32 v182, -16, v182
	v_lshlrev_b64 v[182:183], 8, v[182:183]
	v_lshl_add_u64 v[182:183], s[20:21], 0, v[182:183]
	v_mov_b32_e32 v133, v153
	v_lshl_add_u64 v[182:183], v[182:183], 0, v[252:253]
	global_store_dwordx2 v[182:183], v[124:125], off
	v_or_b32_e32 v182, v156, v195
	v_mov_b32_e32 v183, v129
	v_and_b32_e32 v182, -16, v182
	v_lshlrev_b64 v[182:183], 8, v[182:183]
	v_lshl_add_u64 v[182:183], s[20:21], 0, v[182:183]
	v_mul_f32_e32 v124, v180, v159
	v_mul_f32_e32 v125, v185, v184
	v_lshl_add_u64 v[182:183], v[182:183], 0, v[252:253]
	v_mul_f32_e32 v159, v187, v186
	v_mul_f32_e32 v180, v190, v189
	v_cvt_pk_bf16_f32 v124, v124, v125
	v_cvt_pk_bf16_f32 v125, v159, v180
	global_store_dwordx2 v[182:183], v[124:125], off
	s_mov_b64 s[4:5], 0

.LBB0_216:
	v_lshl_add_u64 v[126:127], v[150:151], 2, s[8:9]
	global_load_dword v133, v[126:127], off
	global_load_dwordx3 v[188:190], v[130:131], off offset:68
	v_bitop3_b32 v151, v136, s51, 16 bitop3:0xc8
	v_and_b32_e32 v182, 28, v150
	v_bitop3_b32 v163, v150, s38, 28 bitop3:0x6c
	v_bitop3_b32 v161, v150, s48, 28 bitop3:0x6c
	v_bitop3_b32 v159, v150, s49, 28 bitop3:0x6c
	v_bitop3_b32 v157, v150, s42, 28 bitop3:0x6c
	v_cvt_f32_u32_e32 v183, v151
	v_or_b32_e32 v150, 1, v151
	v_or_b32_e32 v176, 2, v151
	v_or_b32_e32 v179, 3, v151
	v_cvt_f32_u32_e32 v184, v150
	v_cvt_f32_u32_e32 v185, v176
	v_cvt_f32_u32_e32 v186, v179
	v_mul_f32_e32 v176, v218, v183
	v_fma_f32 v179, v183, v218, -v176
	v_floor_f32_e32 v176, v176
	v_mul_f32_e32 v180, v218, v184
	v_mul_f32_e32 v187, v218, v185
	v_mul_f32_e32 v191, v218, v186
	v_fma_f32 v176, v218, v183, -v176
	v_fma_f32 v192, v184, v218, -v180
	v_floor_f32_e32 v180, v180
	v_fma_f32 v193, v185, v218, -v187
	v_floor_f32_e32 v187, v187
	v_fma_f32 v194, v186, v218, -v191
	v_floor_f32_e32 v191, v191
	v_add_f32_e32 v176, v179, v176
	v_fma_f32 v179, v218, v184, -v180
	v_fma_f32 v180, v218, v185, -v187
	v_fma_f32 v187, v218, v186, -v191
	v_add_f32_e32 v179, v192, v179
	v_add_f32_e32 v180, v193, v180
	v_add_f32_e32 v187, v194, v187
	v_sin_f32_e32 v191, v176
	v_cos_f32_e32 v176, v176
	v_sin_f32_e32 v192, v179
	v_cos_f32_e32 v179, v179
	v_sin_f32_e32 v193, v180
	v_cos_f32_e32 v194, v180
	v_sin_f32_e32 v196, v187
	v_cos_f32_e32 v187, v187
	v_mov_b32_e32 v121, v145
	v_cndmask_b32_e64 v155, 0, 1, s[0:1]
	v_or_b32_e32 v120, v144, v151
	v_cmp_ne_u32_e64 s[4:5], 1, v155
	v_lshlrev_b32_e32 v155, 1, v151
	v_lshlrev_b64 v[150:151], 9, v[120:121]
	s_mov_b64 s[26:27], -1
	s_andn2_b64 vcc, exec, s[0:1]
	v_and_or_b32 v155, v155, s50, v128
	v_lshl_add_u64 v[120:121], s[16:17], 0, v[150:151]
	s_waitcnt vmcnt(1)
	v_mul_f32_e32 v112, v112, v133
	s_waitcnt vmcnt(0)
	v_mul_f32_e32 v117, v117, v188
	v_mul_f32_e32 v113, v113, v188
	v_mul_f32_e32 v188, v118, v189
	v_mul_f32_e32 v114, v114, v189
	v_mul_f32_e32 v189, v119, v190
	v_mul_f32_e32 v119, v115, v190
	v_mul_f32_e32 v116, v116, v133
	v_mul_f32_e32 v180, v191, v112
	v_mul_f32_e32 v133, v176, v112
	v_mul_f32_e32 v112, v192, v113
	v_mul_f32_e32 v118, v179, v113
	v_mul_f32_e32 v113, v193, v114
	v_mul_f32_e32 v115, v194, v114
	v_mul_f32_e32 v190, v196, v119
	v_mul_f32_e32 v114, v187, v119
	v_fma_f32 v180, v176, v116, -v180
	v_fmac_f32_e32 v133, v191, v116
	v_fma_f32 v179, v179, v117, -v112
	v_fmac_f32_e32 v118, v192, v117
	v_fma_f32 v176, v194, v188, -v113
	v_fmac_f32_e32 v115, v193, v188
	v_fma_f32 v119, v187, v189, -v190
	v_fmac_f32_e32 v114, v196, v189
	v_lshlrev_b32_e32 v112, 1, v182
	s_cbranch_vccnz .LBB0_218
	v_mul_f32_e32 v113, 0x3d800000, v180
	v_mul_f32_e32 v188, 0x3d800000, v179
	v_bfe_u32 v116, v113, 16, 1
	v_bfe_u32 v189, v188, 16, 1
	v_add3_u32 v187, v113, v116, s47
	v_lshl_add_u64 v[116:117], v[120:121], 0, v[152:153]
	v_mul_f32_e32 v190, 0x3d800000, v118
	v_add3_u32 v189, v188, v189, s47
	global_store_short_d16_hi v[116:117], v189, off offset:512
	v_bfe_u32 v189, v190, 16, 1
	v_add3_u32 v189, v190, v189, s47
	global_store_short_d16_hi v[116:117], v189, off offset:544
	v_cvt_f32_ubyte0_e32 v189, v161
	v_mul_f32_e32 v189, v137, v189
	v_mul_f32_e32 v189, 0x3fb8aa3b, v189
	v_exp_f32_e32 v191, v189
	v_mul_f32_e32 v189, 0x3d800000, v176
	v_mul_f32_e32 v194, 0x3d800000, v119
	v_bfe_u32 v193, v189, 16, 1
	v_bfe_u32 v198, v194, 16, 1
	v_mul_f32_e32 v182, 0x3d800000, v133
	v_mul_f32_e32 v192, 0x3d800000, v115
	v_add3_u32 v193, v189, v193, s47
	v_mul_f32_e32 v196, 0x3d800000, v114
	v_add3_u32 v198, v194, v198, s47
	global_store_short_d16_hi v[116:117], v187, off
	v_bfe_u32 v187, v182, 16, 1
	global_store_short_d16_hi v[116:117], v193, off offset:1024
	v_bfe_u32 v193, v192, 16, 1
	global_store_short_d16_hi v[116:117], v198, off offset:1536
	v_bfe_u32 v198, v196, 16, 1
	v_add3_u32 v187, v182, v187, s47
	v_add3_u32 v193, v192, v193, s47
	v_add3_u32 v198, v196, v198, s47
	global_store_short_d16_hi v[116:117], v187, off offset:32
	global_store_short_d16_hi v[116:117], v193, off offset:1056
	v_cvt_f32_ubyte0_e32 v193, v159
	global_store_short_d16_hi v[116:117], v198, off offset:1568
	v_cvt_f32_ubyte0_e32 v116, v157
	v_mul_f32_e32 v193, v137, v193
	v_mul_f32_e32 v116, v137, v116
	v_cvt_f32_ubyte0_e32 v187, v163
	v_mul_f32_e32 v193, 0x3fb8aa3b, v193
	v_mul_f32_e32 v116, 0x3fb8aa3b, v116
	v_mul_f32_e32 v187, v137, v187
	v_exp_f32_e32 v193, v193
	v_exp_f32_e32 v198, v116
	v_mul_f32_e32 v187, 0x3fb8aa3b, v187
	v_exp_f32_e32 v187, v187
	v_mul_f32_e32 v116, v191, v188
	v_mul_f32_e32 v117, v193, v189
	v_mul_f32_e32 v188, v198, v194
	v_cvt_pk_bf16_f32 v117, v117, v188
	v_or_b32_e32 v188, v155, v197
	v_mov_b32_e32 v189, v129
	v_mul_f32_e32 v113, v187, v113
	v_and_b32_e32 v188, -16, v188
	v_lshlrev_b64 v[188:189], 8, v[188:189]
	v_cvt_pk_bf16_f32 v116, v113, v116
	v_lshl_add_u64 v[188:189], s[20:21], 0, v[188:189]
	v_mov_b32_e32 v113, v153
	v_lshl_add_u64 v[188:189], v[188:189], 0, v[252:253]
	global_store_dwordx2 v[188:189], v[116:117], off offset:512
	v_or_b32_e32 v188, v155, v195
	v_mov_b32_e32 v189, v129
	v_and_b32_e32 v188, -16, v188
	v_lshlrev_b64 v[188:189], 8, v[188:189]
	v_lshl_add_u64 v[188:189], s[20:21], 0, v[188:189]
	v_mul_f32_e32 v116, v187, v182
	v_mul_f32_e32 v117, v191, v190
	v_lshl_add_u64 v[188:189], v[188:189], 0, v[252:253]
	s_mov_b64 s[26:27], 0
	v_mul_f32_e32 v182, v193, v192
	v_mul_f32_e32 v187, v198, v196
	v_cvt_pk_bf16_f32 v116, v116, v117
	v_cvt_pk_bf16_f32 v117, v182, v187
	global_store_dwordx2 v[188:189], v[116:117], off offset:512

.LBB0_220:
	v_lshl_add_u64 v[118:119], v[148:149], 2, s[8:9]
	global_load_dword v113, v[118:119], off
	global_load_dwordx3 v[198:200], v[130:131], off offset:132
	v_bitop3_b32 v133, v136, s56, 32 bitop3:0xc8
	v_and_b32_e32 v188, 44, v148
	v_bitop3_b32 v180, v148, s38, 44 bitop3:0x6c
	v_bitop3_b32 v179, v148, s48, 44 bitop3:0x6c
	v_bitop3_b32 v176, v148, s49, 44 bitop3:0x6c
	v_bitop3_b32 v151, v148, s42, 44 bitop3:0x6c
	v_cvt_f32_u32_e32 v190, v133
	v_or_b32_e32 v148, 1, v133
	v_or_b32_e32 v149, 2, v133
	v_or_b32_e32 v150, 3, v133
	v_cvt_f32_u32_e32 v191, v148
	v_cvt_f32_u32_e32 v192, v149
	v_cvt_f32_u32_e32 v193, v150
	v_or_b32_e32 v114, v144, v133
	v_lshlrev_b32_e32 v133, 1, v133
	v_and_or_b32 v150, v133, s50, v128
	v_mul_f32_e32 v133, v218, v190
	v_fma_f32 v182, v190, v218, -v133
	v_floor_f32_e32 v133, v133
	v_mul_f32_e32 v187, v218, v191
	v_mul_f32_e32 v189, v218, v192
	v_mul_f32_e32 v194, v218, v193
	v_fma_f32 v133, v218, v190, -v133
	v_fma_f32 v196, v191, v218, -v187
	v_floor_f32_e32 v187, v187
	v_fma_f32 v201, v192, v218, -v189
	v_floor_f32_e32 v189, v189
	v_fma_f32 v202, v193, v218, -v194
	v_floor_f32_e32 v194, v194
	v_add_f32_e32 v133, v182, v133
	v_fma_f32 v182, v218, v191, -v187
	v_fma_f32 v187, v218, v192, -v189
	v_fma_f32 v189, v218, v193, -v194
	v_add_f32_e32 v182, v196, v182
	v_add_f32_e32 v187, v201, v187
	v_add_f32_e32 v189, v202, v189
	v_sin_f32_e32 v194, v133
	v_cos_f32_e32 v133, v133
	v_sin_f32_e32 v196, v182
	v_cos_f32_e32 v182, v182
	v_sin_f32_e32 v201, v187
	v_cos_f32_e32 v202, v187
	v_sin_f32_e32 v203, v189
	v_cos_f32_e32 v189, v189
	v_mov_b32_e32 v115, v145
	v_lshlrev_b64 v[148:149], 9, v[114:115]
	s_mov_b64 s[0:1], -1
	s_and_b64 vcc, exec, s[4:5]
	v_lshl_add_u64 v[114:115], s[16:17], 0, v[148:149]
	s_waitcnt vmcnt(1)
	v_mul_f32_e32 v104, v104, v113
	s_waitcnt vmcnt(0)
	v_mul_f32_e32 v109, v109, v198
	v_mul_f32_e32 v105, v105, v198
	v_mul_f32_e32 v198, v110, v199
	v_mul_f32_e32 v106, v106, v199
	v_mul_f32_e32 v199, v111, v200
	v_mul_f32_e32 v111, v107, v200
	v_mul_f32_e32 v108, v108, v113
	v_mul_f32_e32 v187, v194, v104
	v_mul_f32_e32 v113, v133, v104
	v_mul_f32_e32 v104, v196, v105
	v_mul_f32_e32 v110, v182, v105
	v_mul_f32_e32 v105, v201, v106
	v_mul_f32_e32 v107, v202, v106
	v_mul_f32_e32 v200, v203, v111
	v_mul_f32_e32 v106, v189, v111
	v_fma_f32 v187, v133, v108, -v187
	v_fmac_f32_e32 v113, v194, v108
	v_fma_f32 v182, v182, v109, -v104
	v_fmac_f32_e32 v110, v196, v109
	v_fma_f32 v133, v202, v198, -v105
	v_fmac_f32_e32 v107, v201, v198
	v_fma_f32 v111, v189, v199, -v200
	v_fmac_f32_e32 v106, v203, v199
	v_lshlrev_b32_e32 v104, 1, v188
	s_cbranch_vccnz .LBB0_222
	v_mul_f32_e32 v105, 0x3d800000, v187
	v_bfe_u32 v108, v105, 16, 1
	v_mul_f32_e32 v194, 0x3d800000, v113
	v_add3_u32 v188, v105, v108, s47
	v_lshl_add_u64 v[108:109], v[114:115], 0, v[152:153]
	global_store_short_d16_hi v[108:109], v188, off
	v_bfe_u32 v188, v194, 16, 1
	v_add3_u32 v188, v194, v188, s47
	global_store_short_d16_hi v[108:109], v188, off offset:32
	v_cvt_f32_ubyte0_e32 v188, v180
	v_mul_f32_e32 v188, v137, v188
	v_mul_f32_e32 v188, 0x3fb8aa3b, v188
	v_exp_f32_e32 v196, v188
	v_mul_f32_e32 v188, 0x3d800000, v182
	v_bfe_u32 v189, v188, 16, 1
	v_mul_f32_e32 v198, 0x3d800000, v110
	v_add3_u32 v189, v188, v189, s47
	global_store_short_d16_hi v[108:109], v189, off offset:512
	v_bfe_u32 v189, v198, 16, 1
	v_add3_u32 v189, v198, v189, s47
	global_store_short_d16_hi v[108:109], v189, off offset:544
	v_cvt_f32_ubyte0_e32 v189, v179
	v_mul_f32_e32 v189, v137, v189
	v_mul_f32_e32 v189, 0x3fb8aa3b, v189
	v_exp_f32_e32 v199, v189
	v_mul_f32_e32 v189, 0x3d800000, v133
	v_mul_f32_e32 v202, 0x3d800000, v111
	v_bfe_u32 v201, v189, 16, 1
	v_bfe_u32 v204, v202, 16, 1
	v_mul_f32_e32 v200, 0x3d800000, v107
	v_add3_u32 v201, v189, v201, s47
	v_mul_f32_e32 v203, 0x3d800000, v106
	v_add3_u32 v204, v202, v204, s47
	global_store_short_d16_hi v[108:109], v201, off offset:1024
	v_bfe_u32 v201, v200, 16, 1
	global_store_short_d16_hi v[108:109], v204, off offset:1536
	v_bfe_u32 v204, v203, 16, 1
	v_add3_u32 v201, v200, v201, s47
	v_add3_u32 v204, v203, v204, s47
	global_store_short_d16_hi v[108:109], v201, off offset:1056
	v_cvt_f32_ubyte0_e32 v201, v176
	global_store_short_d16_hi v[108:109], v204, off offset:1568
	v_cvt_f32_ubyte0_e32 v108, v151
	v_mul_f32_e32 v201, v137, v201
	v_mul_f32_e32 v108, v137, v108
	v_mul_f32_e32 v201, 0x3fb8aa3b, v201
	v_mul_f32_e32 v108, 0x3fb8aa3b, v108
	v_exp_f32_e32 v201, v201
	v_exp_f32_e32 v204, v108
	v_mul_f32_e32 v108, v199, v188
	v_mul_f32_e32 v105, v196, v105
	v_mul_f32_e32 v109, v201, v189
	v_mul_f32_e32 v188, v204, v202
	v_cvt_pk_bf16_f32 v109, v109, v188
	v_or_b32_e32 v188, v150, v197
	v_mov_b32_e32 v189, v129
	v_and_b32_e32 v188, -16, v188
	v_lshlrev_b64 v[188:189], 8, v[188:189]
	v_cvt_pk_bf16_f32 v108, v105, v108
	v_lshl_add_u64 v[188:189], s[20:21], 0, v[188:189]
	v_mov_b32_e32 v105, v153
	v_lshl_add_u64 v[188:189], v[188:189], 0, v[252:253]
	global_store_dwordx2 v[188:189], v[108:109], off offset:1024
	v_mul_f32_e32 v108, v196, v194
	v_mul_f32_e32 v109, v199, v198
	v_mul_f32_e32 v188, v201, v200
	v_mul_f32_e32 v189, v204, v203
	v_cvt_pk_bf16_f32 v108, v108, v109
	v_cvt_pk_bf16_f32 v109, v188, v189
	v_or_b32_e32 v188, v150, v195
	v_mov_b32_e32 v189, v129
	v_and_b32_e32 v188, -16, v188
	v_lshlrev_b64 v[188:189], 8, v[188:189]
	v_lshl_add_u64 v[188:189], s[20:21], 0, v[188:189]
	v_lshl_add_u64 v[188:189], v[188:189], 0, v[252:253]
	s_mov_b64 s[0:1], 0
	global_store_dwordx2 v[188:189], v[108:109], off offset:1024

.LBB0_224:
	v_lshl_add_u64 v[110:111], v[146:147], 2, s[8:9]
	global_load_dword v105, v[110:111], off
	global_load_dwordx3 v[204:206], v[130:131], off offset:196
	v_bitop3_b32 v113, v136, s57, 48 bitop3:0xc8
	v_and_b32_e32 v194, 60, v146
	v_bitop3_b32 v188, v146, s38, 60 bitop3:0x6c
	v_bitop3_b32 v187, v146, s48, 60 bitop3:0x6c
	v_bitop3_b32 v182, v146, s49, 60 bitop3:0x6c
	v_bitop3_b32 v149, v146, s42, 60 bitop3:0x6c
	v_cvt_f32_u32_e32 v199, v113
	v_or_b32_e32 v133, 1, v113
	v_or_b32_e32 v146, 2, v113
	v_or_b32_e32 v147, 3, v113
	v_cvt_f32_u32_e32 v200, v133
	v_cvt_f32_u32_e32 v201, v146
	v_cvt_f32_u32_e32 v202, v147
	v_or_b32_e32 v106, v144, v113
	v_lshlrev_b32_e32 v113, 1, v113
	v_and_or_b32 v148, v113, s50, v128
	v_mul_f32_e32 v113, v218, v199
	v_fma_f32 v133, v199, v218, -v113
	v_floor_f32_e32 v113, v113
	v_mul_f32_e32 v189, v218, v200
	v_mul_f32_e32 v196, v218, v201
	v_mul_f32_e32 v198, v218, v202
	v_fma_f32 v113, v218, v199, -v113
	v_fma_f32 v203, v200, v218, -v189
	v_floor_f32_e32 v189, v189
	v_fma_f32 v207, v201, v218, -v196
	v_floor_f32_e32 v196, v196
	v_fma_f32 v208, v202, v218, -v198
	v_floor_f32_e32 v198, v198
	v_add_f32_e32 v113, v133, v113
	v_fma_f32 v133, v218, v200, -v189
	v_fma_f32 v189, v218, v201, -v196
	v_fma_f32 v196, v218, v202, -v198
	v_add_f32_e32 v133, v203, v133
	v_add_f32_e32 v189, v207, v189
	v_add_f32_e32 v196, v208, v196
	v_sin_f32_e32 v198, v113
	v_cos_f32_e32 v113, v113
	v_sin_f32_e32 v203, v133
	v_cos_f32_e32 v133, v133
	v_sin_f32_e32 v207, v189
	v_cos_f32_e32 v208, v189
	v_sin_f32_e32 v209, v196
	v_cos_f32_e32 v196, v196
	v_mov_b32_e32 v107, v145
	v_lshlrev_b64 v[146:147], 9, v[106:107]
	s_mov_b64 s[0:1], -1
	s_and_b64 vcc, exec, s[4:5]
	v_lshl_add_u64 v[106:107], s[16:17], 0, v[146:147]
	s_waitcnt vmcnt(1)
	v_mul_f32_e32 v96, v96, v105
	s_waitcnt vmcnt(0)
	v_mul_f32_e32 v101, v101, v204
	v_mul_f32_e32 v97, v97, v204
	v_mul_f32_e32 v204, v102, v205
	v_mul_f32_e32 v98, v98, v205
	v_mul_f32_e32 v205, v103, v206
	v_mul_f32_e32 v103, v99, v206
	v_mul_f32_e32 v100, v100, v105
	v_mul_f32_e32 v189, v198, v96
	v_mul_f32_e32 v105, v113, v96
	v_mul_f32_e32 v96, v203, v97
	v_mul_f32_e32 v102, v133, v97
	v_mul_f32_e32 v97, v207, v98
	v_mul_f32_e32 v99, v208, v98
	v_mul_f32_e32 v206, v209, v103
	v_mul_f32_e32 v98, v196, v103
	v_fma_f32 v189, v113, v100, -v189
	v_fmac_f32_e32 v105, v198, v100
	v_fma_f32 v133, v133, v101, -v96
	v_fmac_f32_e32 v102, v203, v101
	v_fma_f32 v113, v208, v204, -v97
	v_fmac_f32_e32 v99, v207, v204
	v_fma_f32 v103, v196, v205, -v206
	v_fmac_f32_e32 v98, v209, v205
	v_lshlrev_b32_e32 v96, 1, v194
	s_cbranch_vccnz .LBB0_226
	v_mul_f32_e32 v97, 0x3d800000, v189
	v_mul_f32_e32 v198, 0x3d800000, v133
	v_bfe_u32 v100, v97, 16, 1
	v_bfe_u32 v204, v198, 16, 1
	v_add3_u32 v196, v97, v100, s47
	v_lshl_add_u64 v[100:101], v[106:107], 0, v[152:153]
	v_mul_f32_e32 v203, 0x3d800000, v102
	v_add3_u32 v204, v198, v204, s47
	global_store_short_d16_hi v[100:101], v204, off offset:512
	v_bfe_u32 v204, v203, 16, 1
	v_add3_u32 v204, v203, v204, s47
	global_store_short_d16_hi v[100:101], v204, off offset:544
	v_cvt_f32_ubyte0_e32 v204, v187
	v_mul_f32_e32 v204, v137, v204
	v_mul_f32_e32 v204, 0x3fb8aa3b, v204
	v_exp_f32_e32 v206, v204
	v_mul_f32_e32 v204, 0x3d800000, v113
	v_bfe_u32 v205, v204, 16, 1
	v_mul_f32_e32 v207, 0x3d800000, v99
	v_add3_u32 v205, v204, v205, s47
	global_store_short_d16_hi v[100:101], v205, off offset:1024
	v_bfe_u32 v205, v207, 16, 1
	v_add3_u32 v205, v207, v205, s47
	global_store_short_d16_hi v[100:101], v205, off offset:1056
	v_cvt_f32_ubyte0_e32 v205, v182
	v_mul_f32_e32 v205, v137, v205
	v_mul_f32_e32 v205, 0x3fb8aa3b, v205
	v_exp_f32_e32 v208, v205
	v_mul_f32_e32 v205, 0x3d800000, v103
	v_bfe_u32 v210, v205, 16, 1
	v_mul_f32_e32 v194, 0x3d800000, v105
	v_mul_f32_e32 v209, 0x3d800000, v98
	v_add3_u32 v210, v205, v210, s47
	global_store_short_d16_hi v[100:101], v196, off
	v_bfe_u32 v196, v194, 16, 1
	global_store_short_d16_hi v[100:101], v210, off offset:1536
	v_bfe_u32 v210, v209, 16, 1
	v_add3_u32 v196, v194, v196, s47
	v_add3_u32 v210, v209, v210, s47
	global_store_short_d16_hi v[100:101], v196, off offset:32
	global_store_short_d16_hi v[100:101], v210, off offset:1568
	v_cvt_f32_ubyte0_e32 v100, v149
	v_cvt_f32_ubyte0_e32 v196, v188
	v_mul_f32_e32 v100, v137, v100
	v_mul_f32_e32 v196, v137, v196
	v_mul_f32_e32 v100, 0x3fb8aa3b, v100
	v_mul_f32_e32 v196, 0x3fb8aa3b, v196
	v_exp_f32_e32 v210, v100
	v_exp_f32_e32 v196, v196
	v_mul_f32_e32 v100, v206, v198
	v_mul_f32_e32 v101, v208, v204
	v_mul_f32_e32 v198, v210, v205
	v_or_b32_e32 v204, v148, v197
	v_mov_b32_e32 v205, v129
	v_mul_f32_e32 v97, v196, v97
	v_and_b32_e32 v204, -16, v204
	v_lshlrev_b64 v[204:205], 8, v[204:205]
	v_cvt_pk_bf16_f32 v100, v97, v100
	v_lshl_add_u64 v[204:205], s[20:21], 0, v[204:205]
	v_mov_b32_e32 v97, v153
	v_lshl_add_u64 v[204:205], v[204:205], 0, v[252:253]
	v_cvt_pk_bf16_f32 v101, v101, v198
	global_store_dwordx2 v[204:205], v[100:101], off offset:1536
	v_or_b32_e32 v204, v148, v195
	v_mov_b32_e32 v205, v129
	v_and_b32_e32 v204, -16, v204
	v_lshlrev_b64 v[204:205], 8, v[204:205]
	v_lshl_add_u64 v[204:205], s[20:21], 0, v[204:205]
	v_mul_f32_e32 v100, v196, v194
	v_mul_f32_e32 v101, v206, v203
	v_lshl_add_u64 v[204:205], v[204:205], 0, v[252:253]
	s_mov_b64 s[0:1], 0
	v_mul_f32_e32 v194, v208, v207
	v_mul_f32_e32 v196, v210, v209
	v_cvt_pk_bf16_f32 v100, v100, v101
	v_cvt_pk_bf16_f32 v101, v194, v196
	global_store_dwordx2 v[204:205], v[100:101], off offset:1536

.LBB0_228:
	v_lshl_add_u64 v[102:103], v[142:143], 2, s[8:9]
	global_load_dword v97, v[102:103], off
	global_load_dwordx3 v[210:212], v[130:131], off offset:260
	v_bitop3_b32 v105, v136, s58, 64 bitop3:0xc8
	v_and_b32_e32 v198, 0x4c, v142
	v_bitop3_b32 v196, v142, s38, v171 bitop3:0x6c
	v_bitop3_b32 v194, v142, s48, v171 bitop3:0x6c
	v_bitop3_b32 v189, v142, s49, v171 bitop3:0x6c
	v_bitop3_b32 v147, v142, s42, v171 bitop3:0x6c
	v_cvt_f32_u32_e32 v206, v105
	v_or_b32_e32 v113, 1, v105
	v_or_b32_e32 v133, 2, v105
	v_or_b32_e32 v142, 3, v105
	v_cvt_f32_u32_e32 v207, v113
	v_cvt_f32_u32_e32 v208, v133
	v_cvt_f32_u32_e32 v209, v142
	v_or_b32_e32 v98, v144, v105
	v_lshlrev_b32_e32 v105, 1, v105
	v_and_or_b32 v146, v105, s50, v128
	v_mul_f32_e32 v105, v218, v206
	v_fma_f32 v113, v206, v218, -v105
	v_floor_f32_e32 v105, v105
	v_mul_f32_e32 v133, v218, v207
	v_mul_f32_e32 v203, v218, v208
	v_mul_f32_e32 v204, v218, v209
	v_fma_f32 v105, v218, v206, -v105
	v_fma_f32 v205, v207, v218, -v133
	v_floor_f32_e32 v133, v133
	v_fma_f32 v213, v208, v218, -v203
	v_floor_f32_e32 v203, v203
	v_fma_f32 v214, v209, v218, -v204
	v_floor_f32_e32 v204, v204
	v_add_f32_e32 v105, v113, v105
	v_fma_f32 v113, v218, v207, -v133
	v_fma_f32 v133, v218, v208, -v203
	v_fma_f32 v203, v218, v209, -v204
	v_add_f32_e32 v113, v205, v113
	v_add_f32_e32 v133, v213, v133
	v_add_f32_e32 v203, v214, v203
	v_sin_f32_e32 v204, v105
	v_cos_f32_e32 v105, v105
	v_sin_f32_e32 v205, v113
	v_cos_f32_e32 v113, v113
	v_sin_f32_e32 v213, v133
	v_cos_f32_e32 v214, v133
	v_sin_f32_e32 v215, v203
	v_cos_f32_e32 v203, v203
	v_mov_b32_e32 v99, v145
	v_lshlrev_b64 v[142:143], 9, v[98:99]
	s_mov_b64 s[0:1], -1
	s_and_b64 vcc, exec, s[4:5]
	v_lshl_add_u64 v[98:99], s[16:17], 0, v[142:143]
	s_waitcnt vmcnt(1)
	v_mul_f32_e32 v88, v88, v97
	s_waitcnt vmcnt(0)
	v_mul_f32_e32 v93, v93, v210
	v_mul_f32_e32 v89, v89, v210
	v_mul_f32_e32 v210, v94, v211
	v_mul_f32_e32 v90, v90, v211
	v_mul_f32_e32 v211, v95, v212
	v_mul_f32_e32 v95, v91, v212
	v_mul_f32_e32 v92, v92, v97
	v_mul_f32_e32 v133, v204, v88
	v_mul_f32_e32 v97, v105, v88
	v_mul_f32_e32 v88, v205, v89
	v_mul_f32_e32 v94, v113, v89
	v_mul_f32_e32 v89, v213, v90
	v_mul_f32_e32 v91, v214, v90
	v_mul_f32_e32 v212, v215, v95
	v_mul_f32_e32 v90, v203, v95
	v_fma_f32 v133, v105, v92, -v133
	v_fmac_f32_e32 v97, v204, v92
	v_fma_f32 v113, v113, v93, -v88
	v_fmac_f32_e32 v94, v205, v93
	v_fma_f32 v105, v214, v210, -v89
	v_fmac_f32_e32 v91, v213, v210
	v_fma_f32 v95, v203, v211, -v212
	v_fmac_f32_e32 v90, v215, v211
	v_lshlrev_b32_e32 v88, 1, v198
	s_cbranch_vccnz .LBB0_230
	v_mul_f32_e32 v89, 0x3d800000, v133
	v_mul_f32_e32 v204, 0x3d800000, v113
	v_bfe_u32 v92, v89, 16, 1
	v_bfe_u32 v205, v204, 16, 1
	v_add3_u32 v203, v89, v92, s47
	v_lshl_add_u64 v[92:93], v[98:99], 0, v[152:153]
	v_mul_f32_e32 v210, 0x3d800000, v94
	v_add3_u32 v205, v204, v205, s47
	global_store_short_d16_hi v[92:93], v205, off offset:512
	v_bfe_u32 v205, v210, 16, 1
	v_add3_u32 v205, v210, v205, s47
	global_store_short_d16_hi v[92:93], v205, off offset:544
	v_cvt_f32_ubyte0_e32 v205, v194
	v_mul_f32_e32 v205, v137, v205
	v_mul_f32_e32 v205, 0x3fb8aa3b, v205
	v_exp_f32_e32 v211, v205
	v_mul_f32_e32 v205, 0x3d800000, v105
	v_mul_f32_e32 v214, 0x3d800000, v95
	v_bfe_u32 v213, v205, 16, 1
	v_bfe_u32 v216, v214, 16, 1
	v_mul_f32_e32 v198, 0x3d800000, v97
	v_mul_f32_e32 v212, 0x3d800000, v91
	v_add3_u32 v213, v205, v213, s47
	v_mul_f32_e32 v215, 0x3d800000, v90
	v_add3_u32 v216, v214, v216, s47
	global_store_short_d16_hi v[92:93], v203, off
	v_bfe_u32 v203, v198, 16, 1
	global_store_short_d16_hi v[92:93], v213, off offset:1024
	v_bfe_u32 v213, v212, 16, 1
	global_store_short_d16_hi v[92:93], v216, off offset:1536
	v_bfe_u32 v216, v215, 16, 1
	v_add3_u32 v203, v198, v203, s47
	v_add3_u32 v213, v212, v213, s47
	v_add3_u32 v216, v215, v216, s47
	global_store_short_d16_hi v[92:93], v203, off offset:32
	global_store_short_d16_hi v[92:93], v213, off offset:1056
	v_cvt_f32_ubyte0_e32 v213, v189
	global_store_short_d16_hi v[92:93], v216, off offset:1568
	v_cvt_f32_ubyte0_e32 v92, v147
	v_mul_f32_e32 v213, v137, v213
	v_mul_f32_e32 v92, v137, v92
	v_cvt_f32_ubyte0_e32 v203, v196
	v_mul_f32_e32 v213, 0x3fb8aa3b, v213
	v_mul_f32_e32 v92, 0x3fb8aa3b, v92
	v_mul_f32_e32 v203, v137, v203
	v_exp_f32_e32 v213, v213
	v_exp_f32_e32 v216, v92
	v_mul_f32_e32 v203, 0x3fb8aa3b, v203
	v_exp_f32_e32 v203, v203
	v_mul_f32_e32 v92, v211, v204
	v_mul_f32_e32 v93, v213, v205
	v_mul_f32_e32 v204, v216, v214
	v_cvt_pk_bf16_f32 v93, v93, v204
	v_or_b32_e32 v204, v146, v197
	v_mov_b32_e32 v205, v129
	v_mul_f32_e32 v89, v203, v89
	v_and_b32_e32 v204, -16, v204
	v_lshlrev_b64 v[204:205], 8, v[204:205]
	v_cvt_pk_bf16_f32 v92, v89, v92
	v_lshl_add_u64 v[204:205], s[20:21], 0, v[204:205]
	v_mov_b32_e32 v89, v153
	v_lshl_add_u64 v[204:205], v[204:205], 0, v[252:253]
	global_store_dwordx2 v[204:205], v[92:93], off offset:2048
	v_or_b32_e32 v204, v146, v195
	v_mov_b32_e32 v205, v129
	v_and_b32_e32 v204, -16, v204
	v_lshlrev_b64 v[204:205], 8, v[204:205]
	v_lshl_add_u64 v[204:205], s[20:21], 0, v[204:205]
	v_mul_f32_e32 v92, v203, v198
	v_mul_f32_e32 v93, v211, v210
	v_lshl_add_u64 v[204:205], v[204:205], 0, v[252:253]
	s_mov_b64 s[0:1], 0
	v_mul_f32_e32 v198, v213, v212
	v_mul_f32_e32 v203, v216, v215
	v_cvt_pk_bf16_f32 v92, v92, v93
	v_cvt_pk_bf16_f32 v93, v198, v203
	global_store_dwordx2 v[204:205], v[92:93], off offset:2048

.LBB0_232:
	v_lshl_add_u64 v[94:95], v[140:141], 2, s[8:9]
	global_load_dword v89, v[94:95], off
	global_load_dwordx3 v[222:224], v[130:131], off offset:324
	v_bitop3_b32 v97, v136, s59, v166 bitop3:0xc8
	v_and_b32_e32 v133, 0x5c, v140
	v_bitop3_b32 v204, v140, s38, v172 bitop3:0x6c
	v_bitop3_b32 v203, v140, s48, v172 bitop3:0x6c
	v_bitop3_b32 v198, v140, s49, v172 bitop3:0x6c
	v_bitop3_b32 v143, v140, s42, v172 bitop3:0x6c
	v_cvt_f32_u32_e32 v212, v97
	v_or_b32_e32 v105, 1, v97
	v_or_b32_e32 v113, 2, v97
	v_or_b32_e32 v140, 3, v97
	v_cvt_f32_u32_e32 v213, v105
	v_cvt_f32_u32_e32 v214, v113
	v_cvt_f32_u32_e32 v215, v140
	v_or_b32_e32 v90, v144, v97
	v_lshlrev_b32_e32 v97, 1, v97
	v_and_or_b32 v142, v97, s50, v128
	v_mul_f32_e32 v97, v218, v212
	v_fma_f32 v105, v212, v218, -v97
	v_floor_f32_e32 v97, v97
	v_mul_f32_e32 v113, v218, v213
	v_mul_f32_e32 v205, v218, v214
	v_mul_f32_e32 v210, v218, v215
	v_fma_f32 v97, v218, v212, -v97
	v_fma_f32 v211, v213, v218, -v113
	v_floor_f32_e32 v113, v113
	v_fma_f32 v216, v214, v218, -v205
	v_floor_f32_e32 v205, v205
	v_fma_f32 v217, v215, v218, -v210
	v_floor_f32_e32 v210, v210
	v_add_f32_e32 v97, v105, v97
	v_fma_f32 v105, v218, v213, -v113
	v_fma_f32 v113, v218, v214, -v205
	v_fma_f32 v205, v218, v215, -v210
	v_add_f32_e32 v105, v211, v105
	v_add_f32_e32 v113, v216, v113
	v_add_f32_e32 v205, v217, v205
	v_sin_f32_e32 v210, v97
	v_cos_f32_e32 v97, v97
	v_sin_f32_e32 v211, v105
	v_cos_f32_e32 v105, v105
	v_sin_f32_e32 v216, v113
	v_cos_f32_e32 v217, v113
	v_sin_f32_e32 v219, v205
	v_cos_f32_e32 v205, v205
	v_mov_b32_e32 v91, v145
	v_lshlrev_b64 v[140:141], 9, v[90:91]
	s_mov_b64 s[0:1], -1
	s_and_b64 vcc, exec, s[4:5]
	v_lshl_add_u64 v[90:91], s[16:17], 0, v[140:141]
	s_waitcnt vmcnt(1)
	v_mul_f32_e32 v80, v80, v89
	s_waitcnt vmcnt(0)
	v_mul_f32_e32 v85, v85, v222
	v_mul_f32_e32 v81, v81, v222
	v_mul_f32_e32 v222, v86, v223
	v_mul_f32_e32 v82, v82, v223
	v_mul_f32_e32 v223, v87, v224
	v_mul_f32_e32 v87, v83, v224
	v_mul_f32_e32 v84, v84, v89
	v_mul_f32_e32 v113, v210, v80
	v_mul_f32_e32 v89, v97, v80
	v_mul_f32_e32 v80, v211, v81
	v_mul_f32_e32 v86, v105, v81
	v_mul_f32_e32 v81, v216, v82
	v_mul_f32_e32 v83, v217, v82
	v_mul_f32_e32 v224, v219, v87
	v_mul_f32_e32 v82, v205, v87
	v_fma_f32 v113, v97, v84, -v113
	v_fmac_f32_e32 v89, v210, v84
	v_fma_f32 v105, v105, v85, -v80
	v_fmac_f32_e32 v86, v211, v85
	v_fma_f32 v97, v217, v222, -v81
	v_fmac_f32_e32 v83, v216, v222
	v_fma_f32 v87, v205, v223, -v224
	v_fmac_f32_e32 v82, v219, v223
	v_lshlrev_b32_e32 v80, 1, v133
	s_cbranch_vccnz .LBB0_234
	v_mul_f32_e32 v81, 0x3d800000, v113
	v_mul_f32_e32 v210, 0x3d800000, v105
	v_bfe_u32 v84, v81, 16, 1
	v_bfe_u32 v211, v210, 16, 1
	v_add3_u32 v205, v81, v84, s47
	v_lshl_add_u64 v[84:85], v[90:91], 0, v[152:153]
	v_mul_f32_e32 v216, 0x3d800000, v86
	v_add3_u32 v211, v210, v211, s47
	global_store_short_d16_hi v[84:85], v211, off offset:512
	v_bfe_u32 v211, v216, 16, 1
	v_add3_u32 v211, v216, v211, s47
	global_store_short_d16_hi v[84:85], v211, off offset:544
	v_cvt_f32_ubyte0_e32 v211, v203
	v_mul_f32_e32 v211, v137, v211
	v_mul_f32_e32 v211, 0x3fb8aa3b, v211
	v_exp_f32_e32 v217, v211
	v_mul_f32_e32 v211, 0x3d800000, v97
	v_mul_f32_e32 v223, 0x3d800000, v87
	v_bfe_u32 v222, v211, 16, 1
	v_bfe_u32 v225, v223, 16, 1
	v_mul_f32_e32 v133, 0x3d800000, v89
	v_mul_f32_e32 v219, 0x3d800000, v83
	v_add3_u32 v222, v211, v222, s47
	v_mul_f32_e32 v224, 0x3d800000, v82
	v_add3_u32 v225, v223, v225, s47
	global_store_short_d16_hi v[84:85], v205, off
	v_bfe_u32 v205, v133, 16, 1
	global_store_short_d16_hi v[84:85], v222, off offset:1024
	v_bfe_u32 v222, v219, 16, 1
	global_store_short_d16_hi v[84:85], v225, off offset:1536
	v_bfe_u32 v225, v224, 16, 1
	v_add3_u32 v205, v133, v205, s47
	v_add3_u32 v222, v219, v222, s47
	v_add3_u32 v225, v224, v225, s47
	global_store_short_d16_hi v[84:85], v205, off offset:32
	global_store_short_d16_hi v[84:85], v222, off offset:1056
	v_cvt_f32_ubyte0_e32 v222, v198
	global_store_short_d16_hi v[84:85], v225, off offset:1568
	v_cvt_f32_ubyte0_e32 v84, v143
	v_mul_f32_e32 v222, v137, v222
	v_mul_f32_e32 v84, v137, v84
	v_cvt_f32_ubyte0_e32 v205, v204
	v_mul_f32_e32 v222, 0x3fb8aa3b, v222
	v_mul_f32_e32 v84, 0x3fb8aa3b, v84
	v_mul_f32_e32 v205, v137, v205
	v_exp_f32_e32 v222, v222
	v_exp_f32_e32 v225, v84
	v_mul_f32_e32 v205, 0x3fb8aa3b, v205
	v_exp_f32_e32 v205, v205
	v_mul_f32_e32 v84, v217, v210
	v_mul_f32_e32 v85, v222, v211
	v_mul_f32_e32 v210, v225, v223
	v_cvt_pk_bf16_f32 v85, v85, v210
	v_or_b32_e32 v210, v142, v197
	v_mov_b32_e32 v211, v129
	v_mul_f32_e32 v81, v205, v81
	v_and_b32_e32 v210, -16, v210
	v_lshlrev_b64 v[210:211], 8, v[210:211]
	v_cvt_pk_bf16_f32 v84, v81, v84
	v_lshl_add_u64 v[210:211], s[20:21], 0, v[210:211]
	v_mov_b32_e32 v81, v153
	v_lshl_add_u64 v[210:211], v[210:211], 0, v[252:253]
	global_store_dwordx2 v[210:211], v[84:85], off offset:2560
	v_or_b32_e32 v210, v142, v195
	v_mov_b32_e32 v211, v129
	v_and_b32_e32 v210, -16, v210
	v_lshlrev_b64 v[210:211], 8, v[210:211]
	v_lshl_add_u64 v[210:211], s[20:21], 0, v[210:211]
	v_mul_f32_e32 v84, v205, v133
	v_mul_f32_e32 v85, v217, v216
	v_lshl_add_u64 v[210:211], v[210:211], 0, v[252:253]
	s_mov_b64 s[0:1], 0
	v_mul_f32_e32 v133, v222, v219
	v_mul_f32_e32 v205, v225, v224
	v_cvt_pk_bf16_f32 v84, v84, v85
	v_cvt_pk_bf16_f32 v85, v133, v205
	global_store_dwordx2 v[210:211], v[84:85], off offset:2560

.LBB0_236:
	v_lshl_add_u64 v[86:87], v[138:139], 2, s[8:9]
	global_load_dword v81, v[86:87], off
	global_load_dwordx3 v[226:228], v[130:131], off offset:388
	v_bitop3_b32 v89, v136, s62, v167 bitop3:0xc8
	v_cvt_f32_u32_e32 v219, v89
	v_or_b32_e32 v97, 1, v89
	v_or_b32_e32 v105, 2, v89
	v_or_b32_e32 v133, 3, v89
	v_cvt_f32_u32_e32 v222, v97
	v_cvt_f32_u32_e32 v223, v105
	v_cvt_f32_u32_e32 v224, v133
	v_or_b32_e32 v82, v144, v89
	v_lshlrev_b32_e32 v89, 1, v89
	v_and_or_b32 v140, v89, s50, v128
	v_mul_f32_e32 v89, v218, v219
	v_fma_f32 v97, v219, v218, -v89
	v_floor_f32_e32 v89, v89
	v_mul_f32_e32 v105, v218, v222
	v_mul_f32_e32 v133, v218, v223
	v_mul_f32_e32 v216, v218, v224
	v_fma_f32 v89, v218, v219, -v89
	v_fma_f32 v217, v222, v218, -v105
	v_floor_f32_e32 v105, v105
	v_fma_f32 v225, v223, v218, -v133
	v_floor_f32_e32 v133, v133
	v_fma_f32 v229, v224, v218, -v216
	v_floor_f32_e32 v216, v216
	v_add_f32_e32 v89, v97, v89
	v_fma_f32 v97, v218, v222, -v105
	v_fma_f32 v105, v218, v223, -v133
	v_fma_f32 v133, v218, v224, -v216
	v_add_f32_e32 v97, v217, v97
	v_add_f32_e32 v105, v225, v105
	v_add_f32_e32 v133, v229, v133
	v_sin_f32_e32 v216, v89
	v_cos_f32_e32 v89, v89
	v_sin_f32_e32 v217, v97
	v_cos_f32_e32 v97, v97
	v_sin_f32_e32 v225, v105
	v_cos_f32_e32 v229, v105
	v_sin_f32_e32 v230, v133
	v_cos_f32_e32 v133, v133
	v_mov_b32_e32 v83, v145
	v_and_b32_e32 v113, 0x6c, v138
	v_bitop3_b32 v211, v138, s38, v173 bitop3:0x6c
	v_bitop3_b32 v210, v138, s48, v173 bitop3:0x6c
	v_bitop3_b32 v205, v138, s49, v173 bitop3:0x6c
	v_bitop3_b32 v141, v138, s42, v173 bitop3:0x6c
	v_lshlrev_b64 v[138:139], 9, v[82:83]
	s_mov_b64 s[0:1], -1
	s_and_b64 vcc, exec, s[4:5]
	v_lshl_add_u64 v[82:83], s[16:17], 0, v[138:139]
	s_waitcnt vmcnt(1)
	v_mul_f32_e32 v72, v72, v81
	s_waitcnt vmcnt(0)
	v_mul_f32_e32 v77, v77, v226
	v_mul_f32_e32 v73, v73, v226
	v_mul_f32_e32 v226, v78, v227
	v_mul_f32_e32 v74, v74, v227
	v_mul_f32_e32 v227, v79, v228
	v_mul_f32_e32 v79, v75, v228
	v_mul_f32_e32 v76, v76, v81
	v_mul_f32_e32 v105, v216, v72
	v_mul_f32_e32 v81, v89, v72
	v_mul_f32_e32 v72, v217, v73
	v_mul_f32_e32 v78, v97, v73
	v_mul_f32_e32 v73, v225, v74
	v_mul_f32_e32 v75, v229, v74
	v_mul_f32_e32 v228, v230, v79
	v_mul_f32_e32 v74, v133, v79
	v_fma_f32 v105, v89, v76, -v105
	v_fmac_f32_e32 v81, v216, v76
	v_fma_f32 v97, v97, v77, -v72
	v_fmac_f32_e32 v78, v217, v77
	v_fma_f32 v89, v229, v226, -v73
	v_fmac_f32_e32 v75, v225, v226
	v_fma_f32 v79, v133, v227, -v228
	v_fmac_f32_e32 v74, v230, v227
	v_lshlrev_b32_e32 v72, 1, v113
	s_cbranch_vccnz .LBB0_238
	v_mul_f32_e32 v73, 0x3d800000, v105
	v_mul_f32_e32 v216, 0x3d800000, v97
	v_bfe_u32 v76, v73, 16, 1
	v_bfe_u32 v217, v216, 16, 1
	v_add3_u32 v133, v73, v76, s47
	v_lshl_add_u64 v[76:77], v[82:83], 0, v[152:153]
	v_mul_f32_e32 v225, 0x3d800000, v78
	v_add3_u32 v217, v216, v217, s47
	global_store_short_d16_hi v[76:77], v217, off offset:512
	v_bfe_u32 v217, v225, 16, 1
	v_add3_u32 v217, v225, v217, s47
	global_store_short_d16_hi v[76:77], v217, off offset:544
	v_cvt_f32_ubyte0_e32 v217, v210
	v_mul_f32_e32 v217, v137, v217
	v_mul_f32_e32 v217, 0x3fb8aa3b, v217
	v_exp_f32_e32 v226, v217
	v_mul_f32_e32 v217, 0x3d800000, v89
	v_mul_f32_e32 v229, 0x3d800000, v79
	v_bfe_u32 v228, v217, 16, 1
	v_bfe_u32 v231, v229, 16, 1
	v_mul_f32_e32 v113, 0x3d800000, v81
	v_mul_f32_e32 v227, 0x3d800000, v75
	v_add3_u32 v228, v217, v228, s47
	v_mul_f32_e32 v230, 0x3d800000, v74
	v_add3_u32 v231, v229, v231, s47
	global_store_short_d16_hi v[76:77], v133, off
	v_bfe_u32 v133, v113, 16, 1
	global_store_short_d16_hi v[76:77], v228, off offset:1024
	v_bfe_u32 v228, v227, 16, 1
	global_store_short_d16_hi v[76:77], v231, off offset:1536
	v_bfe_u32 v231, v230, 16, 1
	v_add3_u32 v133, v113, v133, s47
	v_add3_u32 v228, v227, v228, s47
	v_add3_u32 v231, v230, v231, s47
	global_store_short_d16_hi v[76:77], v133, off offset:32
	global_store_short_d16_hi v[76:77], v228, off offset:1056
	v_cvt_f32_ubyte0_e32 v228, v205
	global_store_short_d16_hi v[76:77], v231, off offset:1568
	v_cvt_f32_ubyte0_e32 v76, v141
	v_mul_f32_e32 v228, v137, v228
	v_mul_f32_e32 v76, v137, v76
	v_cvt_f32_ubyte0_e32 v133, v211
	v_mul_f32_e32 v228, 0x3fb8aa3b, v228
	v_mul_f32_e32 v76, 0x3fb8aa3b, v76
	v_mul_f32_e32 v133, v137, v133
	v_exp_f32_e32 v228, v228
	v_exp_f32_e32 v231, v76
	v_mul_f32_e32 v133, 0x3fb8aa3b, v133
	v_exp_f32_e32 v133, v133
	v_mul_f32_e32 v76, v226, v216
	v_mul_f32_e32 v77, v228, v217
	v_mul_f32_e32 v216, v231, v229
	v_cvt_pk_bf16_f32 v77, v77, v216
	v_or_b32_e32 v216, v140, v197
	v_mov_b32_e32 v217, v129
	v_mul_f32_e32 v73, v133, v73
	v_and_b32_e32 v216, -16, v216
	v_lshlrev_b64 v[216:217], 8, v[216:217]
	v_cvt_pk_bf16_f32 v76, v73, v76
	v_lshl_add_u64 v[216:217], s[20:21], 0, v[216:217]
	v_mov_b32_e32 v73, v153
	v_lshl_add_u64 v[216:217], v[216:217], 0, v[252:253]
	global_store_dwordx2 v[216:217], v[76:77], off offset:3072
	v_or_b32_e32 v216, v140, v195
	v_mov_b32_e32 v217, v129
	v_and_b32_e32 v216, -16, v216
	v_lshlrev_b64 v[216:217], 8, v[216:217]
	v_lshl_add_u64 v[216:217], s[20:21], 0, v[216:217]
	v_mul_f32_e32 v76, v133, v113
	v_mul_f32_e32 v77, v226, v225
	v_lshl_add_u64 v[216:217], v[216:217], 0, v[252:253]
	s_mov_b64 s[0:1], 0
	v_mul_f32_e32 v113, v228, v227
	v_mul_f32_e32 v133, v231, v230
	v_cvt_pk_bf16_f32 v76, v76, v77
	v_cvt_pk_bf16_f32 v77, v113, v133
	global_store_dwordx2 v[216:217], v[76:77], off offset:3072

.LBB0_240:
	v_lshl_add_u64 v[78:79], v[134:135], 2, s[8:9]
	global_load_dword v73, v[78:79], off
	global_load_dwordx3 v[230:232], v[130:131], off offset:452
	v_bitop3_b32 v74, v136, s63, v168 bitop3:0xc8
	v_cvt_f32_u32_e32 v225, v74
	v_or_b32_e32 v81, 1, v74
	v_or_b32_e32 v89, 2, v74
	v_or_b32_e32 v97, 3, v74
	v_cvt_f32_u32_e32 v226, v81
	v_cvt_f32_u32_e32 v227, v89
	v_cvt_f32_u32_e32 v228, v97
	v_or_b32_e32 v144, v144, v74
	v_lshlrev_b32_e32 v74, 1, v74
	v_mul_f32_e32 v81, v218, v225
	v_and_or_b32 v136, v74, s50, v128
	v_fma_f32 v89, v225, v218, -v81
	v_floor_f32_e32 v81, v81
	v_mul_f32_e32 v97, v218, v226
	v_mul_f32_e32 v113, v218, v227
	v_mul_f32_e32 v128, v218, v228
	v_and_b32_e32 v105, 0x7c, v134
	v_bitop3_b32 v75, v134, s42, v134 bitop3:0xc
	v_bitop3_b32 v217, v134, s38, v174 bitop3:0x6c
	v_bitop3_b32 v216, v134, s48, v174 bitop3:0x6c
	v_bitop3_b32 v139, v134, s49, v174 bitop3:0x6c
	v_lshlrev_b64 v[134:135], 9, v[144:145]
	v_fma_f32 v81, v218, v225, -v81
	v_fma_f32 v133, v226, v218, -v97
	v_floor_f32_e32 v97, v97
	v_fma_f32 v144, v227, v218, -v113
	v_floor_f32_e32 v113, v113
	v_fma_f32 v145, v228, v218, -v128
	v_floor_f32_e32 v128, v128
	v_add_f32_e32 v81, v89, v81
	v_fma_f32 v89, v218, v226, -v97
	v_fma_f32 v97, v218, v227, -v113
	v_fma_f32 v113, v218, v228, -v128
	v_add_f32_e32 v89, v133, v89
	v_add_f32_e32 v97, v144, v97
	v_add_f32_e32 v113, v145, v113
	v_sin_f32_e32 v128, v81
	v_cos_f32_e32 v81, v81
	v_sin_f32_e32 v133, v89
	v_cos_f32_e32 v89, v89
	v_sin_f32_e32 v144, v97
	v_cos_f32_e32 v145, v97
	v_sin_f32_e32 v218, v113
	v_cos_f32_e32 v113, v113
	s_mov_b64 s[0:1], -1
	s_and_b64 vcc, exec, s[4:5]
	v_cvt_f32_ubyte0_e32 v138, v75
	v_lshl_add_u64 v[74:75], s[16:17], 0, v[134:135]
	s_waitcnt vmcnt(1)
	v_mul_f32_e32 v64, v64, v73
	s_waitcnt vmcnt(0)
	v_mul_f32_e32 v65, v65, v230
	v_mul_f32_e32 v66, v66, v231
	v_mul_f32_e32 v67, v67, v232
	v_mul_f32_e32 v229, v68, v73
	v_mul_f32_e32 v233, v69, v230
	v_mul_f32_e32 v230, v70, v231
	v_mul_f32_e32 v231, v71, v232
	v_mul_f32_e32 v71, v128, v64
	v_mul_f32_e32 v73, v81, v64
	v_mul_f32_e32 v64, v133, v65
	v_mul_f32_e32 v70, v89, v65
	v_mul_f32_e32 v65, v144, v66
	v_mul_f32_e32 v69, v145, v66
	v_mul_f32_e32 v66, v218, v67
	v_mul_f32_e32 v68, v113, v67
	v_fma_f32 v97, v81, v229, -v71
	v_fmac_f32_e32 v73, v128, v229
	v_fma_f32 v89, v89, v233, -v64
	v_fmac_f32_e32 v70, v133, v233
	v_fma_f32 v81, v145, v230, -v65
	v_fmac_f32_e32 v69, v144, v230
	v_fma_f32 v71, v113, v231, -v66
	v_fmac_f32_e32 v68, v218, v231
	v_lshlrev_b32_e32 v64, 1, v105
	s_cbranch_vccnz .LBB0_242
	v_mul_f32_e32 v65, 0x3d800000, v97
	v_mul_f32_e32 v128, 0x3d800000, v89
	v_bfe_u32 v66, v65, 16, 1
	v_bfe_u32 v144, v128, 16, 1
	v_add3_u32 v113, v65, v66, s47
	v_lshl_add_u64 v[66:67], v[74:75], 0, v[152:153]
	v_mul_f32_e32 v133, 0x3d800000, v70
	v_add3_u32 v144, v128, v144, s47
	global_store_short_d16_hi v[66:67], v144, off offset:512
	v_bfe_u32 v144, v133, 16, 1
	v_add3_u32 v144, v133, v144, s47
	global_store_short_d16_hi v[66:67], v144, off offset:544
	v_cvt_f32_ubyte0_e32 v144, v216
	v_mul_f32_e32 v144, v137, v144
	v_mul_f32_e32 v144, 0x3fb8aa3b, v144
	v_exp_f32_e32 v218, v144
	v_mul_f32_e32 v144, 0x3d800000, v81
	v_bfe_u32 v145, v144, 16, 1
	v_mul_f32_e32 v229, 0x3d800000, v69
	v_add3_u32 v145, v144, v145, s47
	global_store_short_d16_hi v[66:67], v145, off offset:1024
	v_bfe_u32 v145, v229, 16, 1
	v_add3_u32 v145, v229, v145, s47
	global_store_short_d16_hi v[66:67], v145, off offset:1056
	v_cvt_f32_ubyte0_e32 v145, v139
	v_mul_f32_e32 v145, v137, v145
	v_mul_f32_e32 v145, 0x3fb8aa3b, v145
	v_exp_f32_e32 v230, v145
	v_mul_f32_e32 v145, 0x3d800000, v71
	v_bfe_u32 v232, v145, 16, 1
	v_mul_f32_e32 v105, 0x3d800000, v73
	v_mul_f32_e32 v231, 0x3d800000, v68
	v_add3_u32 v232, v145, v232, s47
	global_store_short_d16_hi v[66:67], v113, off
	v_bfe_u32 v113, v105, 16, 1
	global_store_short_d16_hi v[66:67], v232, off offset:1536
	v_bfe_u32 v232, v231, 16, 1
	v_add3_u32 v113, v105, v113, s47
	v_add3_u32 v232, v231, v232, s47
	global_store_short_d16_hi v[66:67], v113, off offset:32
	global_store_short_d16_hi v[66:67], v232, off offset:1568
	v_mul_f32_e32 v66, v137, v138
	v_cvt_f32_ubyte0_e32 v113, v217
	v_mul_f32_e32 v66, 0x3fb8aa3b, v66
	v_mul_f32_e32 v113, v137, v113
	v_exp_f32_e32 v232, v66
	v_mul_f32_e32 v113, 0x3fb8aa3b, v113
	v_exp_f32_e32 v113, v113
	v_mul_f32_e32 v66, v218, v128
	v_mul_f32_e32 v67, v230, v144
	v_mul_f32_e32 v128, v232, v145
	v_cvt_pk_bf16_f32 v67, v67, v128
	v_or_b32_e32 v128, v136, v197
	v_mul_f32_e32 v65, v113, v65
	v_and_b32_e32 v128, -16, v128
	v_lshlrev_b64 v[144:145], 8, v[128:129]
	v_cvt_pk_bf16_f32 v66, v65, v66
	v_lshl_add_u64 v[144:145], s[20:21], 0, v[144:145]
	v_mov_b32_e32 v65, v153
	v_lshl_add_u64 v[144:145], v[144:145], 0, v[252:253]
	v_or_b32_e32 v128, v136, v195
	global_store_dwordx2 v[144:145], v[66:67], off offset:3584
	v_and_b32_e32 v128, -16, v128
	v_lshlrev_b64 v[144:145], 8, v[128:129]
	v_lshl_add_u64 v[144:145], s[20:21], 0, v[144:145]
	v_mul_f32_e32 v66, v113, v105
	v_mul_f32_e32 v67, v218, v133
	v_lshl_add_u64 v[144:145], v[144:145], 0, v[252:253]
	s_mov_b64 s[0:1], 0
	v_mul_f32_e32 v105, v230, v229
	v_mul_f32_e32 v113, v232, v231
	v_cvt_pk_bf16_f32 v66, v66, v67
	v_cvt_pk_bf16_f32 v67, v105, v113
	global_store_dwordx2 v[144:145], v[66:67], off offset:3584

.LBB0_244:
	global_load_dwordx4 v[230:233], v[130:131], off
	v_or_b32_e32 v65, 32, v154
	v_lshrrev_b32_e32 v68, 1, v65
	v_or_b32_e32 v68, v68, v158
	v_cvt_f32_ubyte0_e32 v68, v68
	v_mul_f32_e32 v69, 0xbdd49a78, v68
	v_cmp_gt_f32_e64 s[0:1], s43, v69
	v_or_b32_e32 v65, v65, v158
	s_mov_b64 s[26:27], -1
	v_cndmask_b32_e64 v69, 0, v169, s[0:1]
	v_fmac_f32_e32 v69, 0xbdd49a78, v68
	v_exp_f32_e32 v69, v69
	v_cndmask_b32_e64 v70, 0, v170, s[0:1]
	s_and_b64 vcc, exec, s[4:5]
	v_or_b32_e32 v68, 16, v65
	v_ldexp_f32 v69, v69, v70
	v_mul_f32_e32 v69, 0.15915494, v69
	v_mul_f32_e32 v70, v69, v160
	v_mul_f32_e32 v71, v69, v165
	v_mul_f32_e32 v73, v69, v178
	v_mul_f32_e32 v81, v69, v181
	v_fma_f32 v89, v160, v69, -v70
	v_floor_f32_e32 v70, v70
	v_fma_f32 v97, v165, v69, -v71
	v_floor_f32_e32 v71, v71
	v_fma_f32 v105, v178, v69, -v73
	v_floor_f32_e32 v73, v73
	v_fma_f32 v113, v181, v69, -v81
	v_floor_f32_e32 v81, v81
	v_fma_f32 v70, v69, v160, -v70
	v_fma_f32 v71, v69, v165, -v71
	v_fma_f32 v73, v69, v178, -v73
	v_fma_f32 v81, v69, v181, -v81
	v_add_f32_e32 v70, v89, v70
	v_add_f32_e32 v71, v97, v71
	v_add_f32_e32 v73, v105, v73
	v_add_f32_e32 v81, v113, v81
	v_sin_f32_e32 v89, v70
	v_cos_f32_e32 v70, v70
	v_sin_f32_e32 v97, v71
	v_cos_f32_e32 v71, v71
	v_sin_f32_e32 v105, v73
	v_cos_f32_e32 v73, v73
	v_sin_f32_e32 v113, v81
	v_cos_f32_e32 v81, v81
	v_add_lshl_u32 v152, v154, v158, 1
	s_waitcnt vmcnt(0)
	v_mul_f32_e32 v56, v56, v230
	v_mul_f32_e32 v57, v57, v231
	v_mul_f32_e32 v133, v62, v232
	v_mul_f32_e32 v62, v58, v232
	v_mul_f32_e32 v59, v59, v233
	v_mul_f32_e32 v128, v60, v230
	v_mul_f32_e32 v61, v61, v231
	v_mul_f32_e32 v134, v63, v233
	v_mul_f32_e32 v63, v89, v56
	v_mul_f32_e32 v60, v70, v56
	v_mul_f32_e32 v135, v97, v57
	v_mul_f32_e32 v58, v71, v57
	v_mul_f32_e32 v144, v105, v62
	v_mul_f32_e32 v57, v73, v62
	v_mul_f32_e32 v145, v113, v59
	v_mul_f32_e32 v56, v81, v59
	v_fma_f32 v63, v70, v128, -v63
	v_fmac_f32_e32 v60, v89, v128
	v_fma_f32 v62, v71, v61, -v135
	v_fmac_f32_e32 v58, v97, v61
	v_fma_f32 v61, v73, v133, -v144
	v_fmac_f32_e32 v57, v105, v133
	v_fma_f32 v59, v81, v134, -v145
	v_fmac_f32_e32 v56, v113, v134
	s_cbranch_vccnz .LBB0_246
	v_mul_f32_e32 v73, 0x3d800000, v63
	v_bfe_u32 v70, v73, 16, 1
	v_add3_u32 v89, v73, v70, s47
	v_lshl_add_u64 v[70:71], v[122:123], 0, v[152:153]
	v_mul_f32_e32 v122, 0x3d800000, v61
	v_bfe_u32 v123, v122, 16, 1
	v_mul_f32_e32 v134, 0x3d800000, v57
	v_add3_u32 v123, v122, v123, s47
	global_store_short_d16_hi v[70:71], v123, off offset:1088
	v_bfe_u32 v123, v134, 16, 1
	v_add3_u32 v123, v134, v123, s47
	global_store_short_d16_hi v[70:71], v123, off offset:1120
	v_mul_f32_e32 v123, v137, v164
	v_mul_f32_e32 v123, 0x3fb8aa3b, v123
	v_mul_f32_e32 v97, 0x3d800000, v62
	v_exp_f32_e32 v135, v123
	v_mul_f32_e32 v123, 0x3d800000, v59
	v_bfe_u32 v113, v97, 16, 1
	v_bfe_u32 v128, v123, 16, 1
	v_mul_f32_e32 v81, 0x3d800000, v60
	v_mul_f32_e32 v105, 0x3d800000, v58
	v_add3_u32 v113, v97, v113, s47
	v_mul_f32_e32 v144, 0x3d800000, v56
	v_add3_u32 v128, v123, v128, s47
	global_store_short_d16_hi v[70:71], v89, off offset:64
	v_bfe_u32 v89, v81, 16, 1
	global_store_short_d16_hi v[70:71], v113, off offset:576
	v_bfe_u32 v113, v105, 16, 1
	global_store_short_d16_hi v[70:71], v128, off offset:1600
	v_bfe_u32 v128, v144, 16, 1
	v_add3_u32 v89, v81, v89, s47
	v_add3_u32 v113, v105, v113, s47
	v_add3_u32 v128, v144, v128, s47
	global_store_short_d16_hi v[70:71], v89, off offset:96
	v_mul_f32_e32 v89, v137, v177
	global_store_short_d16_hi v[70:71], v113, off offset:608
	v_mul_f32_e32 v113, v137, v175
	global_store_short_d16_hi v[70:71], v128, off offset:1632
	v_mul_f32_e32 v70, v137, v162
	v_mul_f32_e32 v89, 0x3fb8aa3b, v89
	v_mul_f32_e32 v113, 0x3fb8aa3b, v113
	v_mul_f32_e32 v70, 0x3fb8aa3b, v70
	v_exp_f32_e32 v89, v89
	v_exp_f32_e32 v113, v113
	v_exp_f32_e32 v145, v70
	v_or_b32_e32 v128, v156, v65
	v_mul_f32_e32 v70, v89, v73
	v_mul_f32_e32 v71, v113, v97
	v_mul_f32_e32 v73, v135, v122
	v_mul_f32_e32 v97, v145, v123
	v_and_b32_e32 v128, -16, v128
	v_lshlrev_b64 v[122:123], 8, v[128:129]
	v_lshl_add_u64 v[122:123], s[20:21], 0, v[122:123]
	v_mov_b32_e32 v133, v153
	v_lshl_add_u64 v[122:123], v[122:123], 0, v[252:253]
	v_or_b32_e32 v128, v156, v68
	v_cvt_pk_bf16_f32 v70, v70, v71
	v_cvt_pk_bf16_f32 v71, v73, v97
	global_store_dwordx2 v[122:123], v[70:71], off
	v_and_b32_e32 v128, -16, v128
	v_lshlrev_b64 v[122:123], 8, v[128:129]
	v_lshl_add_u64 v[122:123], s[20:21], 0, v[122:123]
	v_mul_f32_e32 v70, v89, v81
	v_mul_f32_e32 v71, v113, v105
	v_lshl_add_u64 v[122:123], v[122:123], 0, v[252:253]
	s_mov_b64 s[26:27], 0
	v_mul_f32_e32 v73, v135, v134
	v_mul_f32_e32 v81, v145, v144
	v_cvt_pk_bf16_f32 v70, v70, v71
	v_cvt_pk_bf16_f32 v71, v73, v81
	global_store_dwordx2 v[122:123], v[70:71], off

.LBB0_248:
	global_load_dword v59, v[126:127], off
	s_nop 0
	global_load_dwordx3 v[56:58], v[130:131], off offset:68
	v_mul_f32_e32 v60, v69, v183
	v_mul_f32_e32 v61, v69, v184
	v_mul_f32_e32 v62, v69, v185
	v_mul_f32_e32 v63, v69, v186
	v_fma_f32 v70, v183, v69, -v60
	v_floor_f32_e32 v60, v60
	v_fma_f32 v71, v184, v69, -v61
	v_floor_f32_e32 v61, v61
	v_fma_f32 v73, v185, v69, -v62
	v_floor_f32_e32 v62, v62
	v_fma_f32 v81, v186, v69, -v63
	v_floor_f32_e32 v63, v63
	v_fma_f32 v60, v69, v183, -v60
	v_fma_f32 v61, v69, v184, -v61
	v_fma_f32 v62, v69, v185, -v62
	v_fma_f32 v63, v69, v186, -v63
	v_add_f32_e32 v60, v70, v60
	v_add_f32_e32 v61, v71, v61
	v_add_f32_e32 v62, v73, v62
	v_add_f32_e32 v63, v81, v63
	v_sin_f32_e32 v70, v60
	v_cos_f32_e32 v60, v60
	v_sin_f32_e32 v71, v61
	v_cos_f32_e32 v61, v61
	v_sin_f32_e32 v73, v62
	v_cos_f32_e32 v62, v62
	v_sin_f32_e32 v81, v63
	v_cos_f32_e32 v63, v63
	s_and_b64 vcc, exec, s[4:5]
	s_mov_b64 s[0:1], -1
	s_waitcnt vmcnt(1)
	v_mul_f32_e32 v48, v48, v59
	s_waitcnt vmcnt(0)
	v_mul_f32_e32 v53, v53, v56
	v_mul_f32_e32 v49, v49, v56
	v_mul_f32_e32 v56, v54, v57
	v_mul_f32_e32 v54, v50, v57
	v_mul_f32_e32 v51, v51, v58
	v_mul_f32_e32 v89, v52, v59
	v_mul_f32_e32 v57, v55, v58
	v_mul_f32_e32 v55, v70, v48
	v_mul_f32_e32 v52, v60, v48
	v_mul_f32_e32 v58, v71, v49
	v_mul_f32_e32 v50, v61, v49
	v_mul_f32_e32 v59, v73, v54
	v_mul_f32_e32 v49, v62, v54
	v_mul_f32_e32 v97, v81, v51
	v_mul_f32_e32 v48, v63, v51
	v_fma_f32 v55, v60, v89, -v55
	v_fmac_f32_e32 v52, v70, v89
	v_fma_f32 v54, v61, v53, -v58
	v_fmac_f32_e32 v50, v71, v53
	v_fma_f32 v53, v62, v56, -v59
	v_fmac_f32_e32 v49, v73, v56
	v_fma_f32 v51, v63, v57, -v97
	v_fmac_f32_e32 v48, v81, v57
	s_cbranch_vccnz .LBB0_250
	v_mul_f32_e32 v58, 0x3d800000, v55
	v_bfe_u32 v56, v58, 16, 1
	v_mul_f32_e32 v60, 0x3d800000, v52
	v_add3_u32 v59, v58, v56, s47
	v_lshl_add_u64 v[56:57], v[120:121], 0, v[152:153]
	global_store_short_d16_hi v[56:57], v59, off offset:64
	v_bfe_u32 v59, v60, 16, 1
	v_add3_u32 v59, v60, v59, s47
	global_store_short_d16_hi v[56:57], v59, off offset:96
	v_cvt_f32_ubyte0_e32 v59, v163
	v_mul_f32_e32 v59, v137, v59
	v_mul_f32_e32 v59, 0x3fb8aa3b, v59
	v_exp_f32_e32 v61, v59
	v_mul_f32_e32 v59, 0x3d800000, v54
	v_mul_f32_e32 v70, 0x3d800000, v53
	v_mul_f32_e32 v81, 0x3d800000, v51
	v_bfe_u32 v63, v59, 16, 1
	v_bfe_u32 v73, v70, 16, 1
	v_bfe_u32 v97, v81, 16, 1
	v_mul_f32_e32 v62, 0x3d800000, v50
	v_add3_u32 v63, v59, v63, s47
	v_mul_f32_e32 v71, 0x3d800000, v49
	v_add3_u32 v73, v70, v73, s47
	v_mul_f32_e32 v89, 0x3d800000, v48
	v_add3_u32 v97, v81, v97, s47
	global_store_short_d16_hi v[56:57], v63, off offset:576
	v_bfe_u32 v63, v62, 16, 1
	global_store_short_d16_hi v[56:57], v73, off offset:1088
	v_bfe_u32 v73, v71, 16, 1
	global_store_short_d16_hi v[56:57], v97, off offset:1600
	v_bfe_u32 v97, v89, 16, 1
	v_add3_u32 v63, v62, v63, s47
	v_add3_u32 v73, v71, v73, s47
	v_add3_u32 v97, v89, v97, s47
	global_store_short_d16_hi v[56:57], v63, off offset:608
	v_cvt_f32_ubyte0_e32 v63, v161
	global_store_short_d16_hi v[56:57], v73, off offset:1120
	v_cvt_f32_ubyte0_e32 v73, v159
	global_store_short_d16_hi v[56:57], v97, off offset:1632
	v_cvt_f32_ubyte0_e32 v56, v157
	v_mul_f32_e32 v63, v137, v63
	v_mul_f32_e32 v73, v137, v73
	v_mul_f32_e32 v56, v137, v56
	v_mul_f32_e32 v63, 0x3fb8aa3b, v63
	v_mul_f32_e32 v73, 0x3fb8aa3b, v73
	v_mul_f32_e32 v56, 0x3fb8aa3b, v56
	v_exp_f32_e32 v63, v63
	v_exp_f32_e32 v73, v73
	v_exp_f32_e32 v97, v56
	v_mul_f32_e32 v56, v61, v58
	v_mul_f32_e32 v57, v63, v59
	v_mul_f32_e32 v58, v73, v70
	v_mul_f32_e32 v59, v97, v81
	v_or_b32_e32 v128, v155, v65
	v_cvt_pk_bf16_f32 v56, v56, v57
	v_cvt_pk_bf16_f32 v57, v58, v59
	v_and_b32_e32 v128, -16, v128
	v_lshlrev_b64 v[58:59], 8, v[128:129]
	v_lshl_add_u64 v[58:59], s[20:21], 0, v[58:59]
	v_mov_b32_e32 v113, v153
	v_lshl_add_u64 v[58:59], v[58:59], 0, v[252:253]
	global_store_dwordx2 v[58:59], v[56:57], off offset:512
	v_mul_f32_e32 v56, v61, v60
	v_mul_f32_e32 v57, v63, v62
	v_mul_f32_e32 v58, v73, v71
	v_mul_f32_e32 v59, v97, v89
	v_or_b32_e32 v128, v155, v68
	v_cvt_pk_bf16_f32 v56, v56, v57
	v_cvt_pk_bf16_f32 v57, v58, v59
	v_and_b32_e32 v128, -16, v128
	v_lshlrev_b64 v[58:59], 8, v[128:129]
	v_lshl_add_u64 v[58:59], s[20:21], 0, v[58:59]
	v_lshl_add_u64 v[58:59], v[58:59], 0, v[252:253]
	s_mov_b64 s[0:1], 0
	global_store_dwordx2 v[58:59], v[56:57], off offset:512

.LBB0_252:
	global_load_dword v51, v[118:119], off
	s_nop 0
	global_load_dwordx3 v[48:50], v[130:131], off offset:132
	v_mul_f32_e32 v52, v69, v190
	v_mul_f32_e32 v53, v69, v191
	v_mul_f32_e32 v54, v69, v192
	v_mul_f32_e32 v55, v69, v193
	v_fma_f32 v56, v190, v69, -v52
	v_floor_f32_e32 v52, v52
	v_fma_f32 v57, v191, v69, -v53
	v_floor_f32_e32 v53, v53
	v_fma_f32 v58, v192, v69, -v54
	v_floor_f32_e32 v54, v54
	v_fma_f32 v59, v193, v69, -v55
	v_floor_f32_e32 v55, v55
	v_fma_f32 v52, v69, v190, -v52
	v_fma_f32 v53, v69, v191, -v53
	v_fma_f32 v54, v69, v192, -v54
	v_fma_f32 v55, v69, v193, -v55
	v_add_f32_e32 v52, v56, v52
	v_add_f32_e32 v53, v57, v53
	v_add_f32_e32 v54, v58, v54
	v_add_f32_e32 v55, v59, v55
	v_sin_f32_e32 v56, v52
	v_cos_f32_e32 v52, v52
	v_sin_f32_e32 v57, v53
	v_cos_f32_e32 v53, v53
	v_sin_f32_e32 v58, v54
	v_cos_f32_e32 v54, v54
	v_sin_f32_e32 v59, v55
	v_cos_f32_e32 v55, v55
	s_and_b64 vcc, exec, s[4:5]
	s_mov_b64 s[0:1], -1
	s_waitcnt vmcnt(1)
	v_mul_f32_e32 v40, v40, v51
	s_waitcnt vmcnt(0)
	v_mul_f32_e32 v45, v45, v48
	v_mul_f32_e32 v41, v41, v48
	v_mul_f32_e32 v48, v46, v49
	v_mul_f32_e32 v46, v42, v49
	v_mul_f32_e32 v43, v43, v50
	v_mul_f32_e32 v60, v44, v51
	v_mul_f32_e32 v49, v47, v50
	v_mul_f32_e32 v47, v56, v40
	v_mul_f32_e32 v44, v52, v40
	v_mul_f32_e32 v50, v57, v41
	v_mul_f32_e32 v42, v53, v41
	v_mul_f32_e32 v51, v58, v46
	v_mul_f32_e32 v41, v54, v46
	v_mul_f32_e32 v61, v59, v43
	v_mul_f32_e32 v40, v55, v43
	v_fma_f32 v47, v52, v60, -v47
	v_fmac_f32_e32 v44, v56, v60
	v_fma_f32 v46, v53, v45, -v50
	v_fmac_f32_e32 v42, v57, v45
	v_fma_f32 v45, v54, v48, -v51
	v_fmac_f32_e32 v41, v58, v48
	v_fma_f32 v43, v55, v49, -v61
	v_fmac_f32_e32 v40, v59, v49
	s_cbranch_vccnz .LBB0_254
	v_mul_f32_e32 v50, 0x3d800000, v47
	v_bfe_u32 v48, v50, 16, 1
	v_mul_f32_e32 v52, 0x3d800000, v44
	v_add3_u32 v51, v50, v48, s47
	v_lshl_add_u64 v[48:49], v[114:115], 0, v[152:153]
	global_store_short_d16_hi v[48:49], v51, off offset:64
	v_bfe_u32 v51, v52, 16, 1
	v_add3_u32 v51, v52, v51, s47
	global_store_short_d16_hi v[48:49], v51, off offset:96
	v_cvt_f32_ubyte0_e32 v51, v180
	v_mul_f32_e32 v51, v137, v51
	v_mul_f32_e32 v51, 0x3fb8aa3b, v51
	v_exp_f32_e32 v53, v51
	v_mul_f32_e32 v51, 0x3d800000, v46
	v_mul_f32_e32 v56, 0x3d800000, v45
	v_mul_f32_e32 v59, 0x3d800000, v43
	v_bfe_u32 v55, v51, 16, 1
	v_bfe_u32 v58, v56, 16, 1
	v_bfe_u32 v61, v59, 16, 1
	v_mul_f32_e32 v54, 0x3d800000, v42
	v_add3_u32 v55, v51, v55, s47
	v_mul_f32_e32 v57, 0x3d800000, v41
	v_add3_u32 v58, v56, v58, s47
	v_mul_f32_e32 v60, 0x3d800000, v40
	v_add3_u32 v61, v59, v61, s47
	global_store_short_d16_hi v[48:49], v55, off offset:576
	v_bfe_u32 v55, v54, 16, 1
	global_store_short_d16_hi v[48:49], v58, off offset:1088
	v_bfe_u32 v58, v57, 16, 1
	global_store_short_d16_hi v[48:49], v61, off offset:1600
	v_bfe_u32 v61, v60, 16, 1
	v_add3_u32 v55, v54, v55, s47
	v_add3_u32 v58, v57, v58, s47
	v_add3_u32 v61, v60, v61, s47
	global_store_short_d16_hi v[48:49], v55, off offset:608
	v_cvt_f32_ubyte0_e32 v55, v179
	global_store_short_d16_hi v[48:49], v58, off offset:1120
	v_cvt_f32_ubyte0_e32 v58, v176
	global_store_short_d16_hi v[48:49], v61, off offset:1632
	v_cvt_f32_ubyte0_e32 v48, v151
	v_mul_f32_e32 v55, v137, v55
	v_mul_f32_e32 v58, v137, v58
	v_mul_f32_e32 v48, v137, v48
	v_mul_f32_e32 v55, 0x3fb8aa3b, v55
	v_mul_f32_e32 v58, 0x3fb8aa3b, v58
	v_mul_f32_e32 v48, 0x3fb8aa3b, v48
	v_exp_f32_e32 v55, v55
	v_exp_f32_e32 v58, v58
	v_exp_f32_e32 v61, v48
	v_mul_f32_e32 v48, v53, v50
	v_mul_f32_e32 v49, v55, v51
	v_mul_f32_e32 v50, v58, v56
	v_mul_f32_e32 v51, v61, v59
	v_or_b32_e32 v128, v150, v65
	v_cvt_pk_bf16_f32 v48, v48, v49
	v_cvt_pk_bf16_f32 v49, v50, v51
	v_and_b32_e32 v128, -16, v128
	v_lshlrev_b64 v[50:51], 8, v[128:129]
	v_lshl_add_u64 v[50:51], s[20:21], 0, v[50:51]
	v_mov_b32_e32 v105, v153
	v_lshl_add_u64 v[50:51], v[50:51], 0, v[252:253]
	global_store_dwordx2 v[50:51], v[48:49], off offset:1024
	v_mul_f32_e32 v48, v53, v52
	v_mul_f32_e32 v49, v55, v54
	v_mul_f32_e32 v50, v58, v57
	v_mul_f32_e32 v51, v61, v60
	v_or_b32_e32 v128, v150, v68
	v_cvt_pk_bf16_f32 v48, v48, v49
	v_cvt_pk_bf16_f32 v49, v50, v51
	v_and_b32_e32 v128, -16, v128
	v_lshlrev_b64 v[50:51], 8, v[128:129]
	v_lshl_add_u64 v[50:51], s[20:21], 0, v[50:51]
	v_lshl_add_u64 v[50:51], v[50:51], 0, v[252:253]
	s_mov_b64 s[0:1], 0
	global_store_dwordx2 v[50:51], v[48:49], off offset:1024

.LBB0_256:
	global_load_dword v43, v[110:111], off
	s_nop 0
	global_load_dwordx3 v[40:42], v[130:131], off offset:196
	v_mul_f32_e32 v44, v69, v199
	v_mul_f32_e32 v45, v69, v200
	v_mul_f32_e32 v46, v69, v201
	v_mul_f32_e32 v47, v69, v202
	v_fma_f32 v48, v199, v69, -v44
	v_floor_f32_e32 v44, v44
	v_fma_f32 v49, v200, v69, -v45
	v_floor_f32_e32 v45, v45
	v_fma_f32 v50, v201, v69, -v46
	v_floor_f32_e32 v46, v46
	v_fma_f32 v51, v202, v69, -v47
	v_floor_f32_e32 v47, v47
	v_fma_f32 v44, v69, v199, -v44
	v_fma_f32 v45, v69, v200, -v45
	v_fma_f32 v46, v69, v201, -v46
	v_fma_f32 v47, v69, v202, -v47
	v_add_f32_e32 v44, v48, v44
	v_add_f32_e32 v45, v49, v45
	v_add_f32_e32 v46, v50, v46
	v_add_f32_e32 v47, v51, v47
	v_sin_f32_e32 v48, v44
	v_cos_f32_e32 v44, v44
	v_sin_f32_e32 v49, v45
	v_cos_f32_e32 v45, v45
	v_sin_f32_e32 v50, v46
	v_cos_f32_e32 v46, v46
	v_sin_f32_e32 v51, v47
	v_cos_f32_e32 v47, v47
	s_and_b64 vcc, exec, s[4:5]
	s_mov_b64 s[0:1], -1
	s_waitcnt vmcnt(1)
	v_mul_f32_e32 v32, v32, v43
	s_waitcnt vmcnt(0)
	v_mul_f32_e32 v37, v37, v40
	v_mul_f32_e32 v33, v33, v40
	v_mul_f32_e32 v40, v38, v41
	v_mul_f32_e32 v38, v34, v41
	v_mul_f32_e32 v35, v35, v42
	v_mul_f32_e32 v52, v36, v43
	v_mul_f32_e32 v41, v39, v42
	v_mul_f32_e32 v39, v48, v32
	v_mul_f32_e32 v36, v44, v32
	v_mul_f32_e32 v42, v49, v33
	v_mul_f32_e32 v34, v45, v33
	v_mul_f32_e32 v43, v50, v38
	v_mul_f32_e32 v33, v46, v38
	v_mul_f32_e32 v53, v51, v35
	v_mul_f32_e32 v32, v47, v35
	v_fma_f32 v39, v44, v52, -v39
	v_fmac_f32_e32 v36, v48, v52
	v_fma_f32 v38, v45, v37, -v42
	v_fmac_f32_e32 v34, v49, v37
	v_fma_f32 v37, v46, v40, -v43
	v_fmac_f32_e32 v33, v50, v40
	v_fma_f32 v35, v47, v41, -v53
	v_fmac_f32_e32 v32, v51, v41
	s_cbranch_vccnz .LBB0_258
	v_mul_f32_e32 v42, 0x3d800000, v39
	v_bfe_u32 v40, v42, 16, 1
	v_mul_f32_e32 v44, 0x3d800000, v36
	v_add3_u32 v43, v42, v40, s47
	v_lshl_add_u64 v[40:41], v[106:107], 0, v[152:153]
	global_store_short_d16_hi v[40:41], v43, off offset:64
	v_bfe_u32 v43, v44, 16, 1
	v_add3_u32 v43, v44, v43, s47
	global_store_short_d16_hi v[40:41], v43, off offset:96
	v_cvt_f32_ubyte0_e32 v43, v188
	v_mul_f32_e32 v43, v137, v43
	v_mul_f32_e32 v43, 0x3fb8aa3b, v43
	v_exp_f32_e32 v45, v43
	v_mul_f32_e32 v43, 0x3d800000, v38
	v_mul_f32_e32 v48, 0x3d800000, v37
	v_mul_f32_e32 v51, 0x3d800000, v35
	v_bfe_u32 v47, v43, 16, 1
	v_bfe_u32 v50, v48, 16, 1
	v_bfe_u32 v53, v51, 16, 1
	v_mul_f32_e32 v46, 0x3d800000, v34
	v_add3_u32 v47, v43, v47, s47
	v_mul_f32_e32 v49, 0x3d800000, v33
	v_add3_u32 v50, v48, v50, s47
	v_mul_f32_e32 v52, 0x3d800000, v32
	v_add3_u32 v53, v51, v53, s47
	global_store_short_d16_hi v[40:41], v47, off offset:576
	v_bfe_u32 v47, v46, 16, 1
	global_store_short_d16_hi v[40:41], v50, off offset:1088
	v_bfe_u32 v50, v49, 16, 1
	global_store_short_d16_hi v[40:41], v53, off offset:1600
	v_bfe_u32 v53, v52, 16, 1
	v_add3_u32 v47, v46, v47, s47
	v_add3_u32 v50, v49, v50, s47
	v_add3_u32 v53, v52, v53, s47
	global_store_short_d16_hi v[40:41], v47, off offset:608
	v_cvt_f32_ubyte0_e32 v47, v187
	global_store_short_d16_hi v[40:41], v50, off offset:1120
	v_cvt_f32_ubyte0_e32 v50, v182
	global_store_short_d16_hi v[40:41], v53, off offset:1632
	v_cvt_f32_ubyte0_e32 v40, v149
	v_mul_f32_e32 v47, v137, v47
	v_mul_f32_e32 v50, v137, v50
	v_mul_f32_e32 v40, v137, v40
	v_mul_f32_e32 v47, 0x3fb8aa3b, v47
	v_mul_f32_e32 v50, 0x3fb8aa3b, v50
	v_mul_f32_e32 v40, 0x3fb8aa3b, v40
	v_exp_f32_e32 v47, v47
	v_exp_f32_e32 v50, v50
	v_exp_f32_e32 v53, v40
	v_mul_f32_e32 v40, v45, v42
	v_mul_f32_e32 v41, v47, v43
	v_mul_f32_e32 v42, v50, v48
	v_mul_f32_e32 v43, v53, v51
	v_or_b32_e32 v128, v148, v65
	v_cvt_pk_bf16_f32 v40, v40, v41
	v_cvt_pk_bf16_f32 v41, v42, v43
	v_and_b32_e32 v128, -16, v128
	v_lshlrev_b64 v[42:43], 8, v[128:129]
	v_lshl_add_u64 v[42:43], s[20:21], 0, v[42:43]
	v_mov_b32_e32 v97, v153
	v_lshl_add_u64 v[42:43], v[42:43], 0, v[252:253]
	global_store_dwordx2 v[42:43], v[40:41], off offset:1536
	v_mul_f32_e32 v40, v45, v44
	v_mul_f32_e32 v41, v47, v46
	v_mul_f32_e32 v42, v50, v49
	v_mul_f32_e32 v43, v53, v52
	v_or_b32_e32 v128, v148, v68
	v_cvt_pk_bf16_f32 v40, v40, v41
	v_cvt_pk_bf16_f32 v41, v42, v43
	v_and_b32_e32 v128, -16, v128
	v_lshlrev_b64 v[42:43], 8, v[128:129]
	v_lshl_add_u64 v[42:43], s[20:21], 0, v[42:43]
	v_lshl_add_u64 v[42:43], v[42:43], 0, v[252:253]
	s_mov_b64 s[0:1], 0
	global_store_dwordx2 v[42:43], v[40:41], off offset:1536

.LBB0_260:
	global_load_dword v35, v[102:103], off
	s_nop 0
	global_load_dwordx3 v[32:34], v[130:131], off offset:260
	v_mul_f32_e32 v36, v69, v206
	v_mul_f32_e32 v37, v69, v207
	v_mul_f32_e32 v38, v69, v208
	v_mul_f32_e32 v39, v69, v209
	v_fma_f32 v40, v206, v69, -v36
	v_floor_f32_e32 v36, v36
	v_fma_f32 v41, v207, v69, -v37
	v_floor_f32_e32 v37, v37
	v_fma_f32 v42, v208, v69, -v38
	v_floor_f32_e32 v38, v38
	v_fma_f32 v43, v209, v69, -v39
	v_floor_f32_e32 v39, v39
	v_fma_f32 v36, v69, v206, -v36
	v_fma_f32 v37, v69, v207, -v37
	v_fma_f32 v38, v69, v208, -v38
	v_fma_f32 v39, v69, v209, -v39
	v_add_f32_e32 v36, v40, v36
	v_add_f32_e32 v37, v41, v37
	v_add_f32_e32 v38, v42, v38
	v_add_f32_e32 v39, v43, v39
	v_sin_f32_e32 v40, v36
	v_cos_f32_e32 v36, v36
	v_sin_f32_e32 v41, v37
	v_cos_f32_e32 v37, v37
	v_sin_f32_e32 v42, v38
	v_cos_f32_e32 v38, v38
	v_sin_f32_e32 v43, v39
	v_cos_f32_e32 v39, v39
	s_and_b64 vcc, exec, s[4:5]
	s_mov_b64 s[0:1], -1
	s_waitcnt vmcnt(1)
	v_mul_f32_e32 v24, v24, v35
	s_waitcnt vmcnt(0)
	v_mul_f32_e32 v29, v29, v32
	v_mul_f32_e32 v25, v25, v32
	v_mul_f32_e32 v32, v30, v33
	v_mul_f32_e32 v30, v26, v33
	v_mul_f32_e32 v27, v27, v34
	v_mul_f32_e32 v44, v28, v35
	v_mul_f32_e32 v33, v31, v34
	v_mul_f32_e32 v31, v40, v24
	v_mul_f32_e32 v28, v36, v24
	v_mul_f32_e32 v34, v41, v25
	v_mul_f32_e32 v26, v37, v25
	v_mul_f32_e32 v35, v42, v30
	v_mul_f32_e32 v25, v38, v30
	v_mul_f32_e32 v45, v43, v27
	v_mul_f32_e32 v24, v39, v27
	v_fma_f32 v31, v36, v44, -v31
	v_fmac_f32_e32 v28, v40, v44
	v_fma_f32 v30, v37, v29, -v34
	v_fmac_f32_e32 v26, v41, v29
	v_fma_f32 v29, v38, v32, -v35
	v_fmac_f32_e32 v25, v42, v32
	v_fma_f32 v27, v39, v33, -v45
	v_fmac_f32_e32 v24, v43, v33
	s_cbranch_vccnz .LBB0_262
	v_mul_f32_e32 v34, 0x3d800000, v31
	v_bfe_u32 v32, v34, 16, 1
	v_mul_f32_e32 v36, 0x3d800000, v28
	v_add3_u32 v35, v34, v32, s47
	v_lshl_add_u64 v[32:33], v[98:99], 0, v[152:153]
	global_store_short_d16_hi v[32:33], v35, off offset:64
	v_bfe_u32 v35, v36, 16, 1
	v_add3_u32 v35, v36, v35, s47
	global_store_short_d16_hi v[32:33], v35, off offset:96
	v_cvt_f32_ubyte0_e32 v35, v196
	v_mul_f32_e32 v35, v137, v35
	v_mul_f32_e32 v35, 0x3fb8aa3b, v35
	v_exp_f32_e32 v37, v35
	v_mul_f32_e32 v35, 0x3d800000, v30
	v_mul_f32_e32 v40, 0x3d800000, v29
	v_mul_f32_e32 v43, 0x3d800000, v27
	v_bfe_u32 v39, v35, 16, 1
	v_bfe_u32 v42, v40, 16, 1
	v_bfe_u32 v45, v43, 16, 1
	v_mul_f32_e32 v38, 0x3d800000, v26
	v_add3_u32 v39, v35, v39, s47
	v_mul_f32_e32 v41, 0x3d800000, v25
	v_add3_u32 v42, v40, v42, s47
	v_mul_f32_e32 v44, 0x3d800000, v24
	v_add3_u32 v45, v43, v45, s47
	global_store_short_d16_hi v[32:33], v39, off offset:576
	v_bfe_u32 v39, v38, 16, 1
	global_store_short_d16_hi v[32:33], v42, off offset:1088
	v_bfe_u32 v42, v41, 16, 1
	global_store_short_d16_hi v[32:33], v45, off offset:1600
	v_bfe_u32 v45, v44, 16, 1
	v_add3_u32 v39, v38, v39, s47
	v_add3_u32 v42, v41, v42, s47
	v_add3_u32 v45, v44, v45, s47
	global_store_short_d16_hi v[32:33], v39, off offset:608
	v_cvt_f32_ubyte0_e32 v39, v194
	global_store_short_d16_hi v[32:33], v42, off offset:1120
	v_cvt_f32_ubyte0_e32 v42, v189
	global_store_short_d16_hi v[32:33], v45, off offset:1632
	v_cvt_f32_ubyte0_e32 v32, v147
	v_mul_f32_e32 v39, v137, v39
	v_mul_f32_e32 v42, v137, v42
	v_mul_f32_e32 v32, v137, v32
	v_mul_f32_e32 v39, 0x3fb8aa3b, v39
	v_mul_f32_e32 v42, 0x3fb8aa3b, v42
	v_mul_f32_e32 v32, 0x3fb8aa3b, v32
	v_exp_f32_e32 v39, v39
	v_exp_f32_e32 v42, v42
	v_exp_f32_e32 v45, v32
	v_mul_f32_e32 v32, v37, v34
	v_mul_f32_e32 v33, v39, v35
	v_mul_f32_e32 v34, v42, v40
	v_mul_f32_e32 v35, v45, v43
	v_or_b32_e32 v128, v146, v65
	v_cvt_pk_bf16_f32 v32, v32, v33
	v_cvt_pk_bf16_f32 v33, v34, v35
	v_and_b32_e32 v128, -16, v128
	v_lshlrev_b64 v[34:35], 8, v[128:129]
	v_lshl_add_u64 v[34:35], s[20:21], 0, v[34:35]
	v_mov_b32_e32 v89, v153
	v_lshl_add_u64 v[34:35], v[34:35], 0, v[252:253]
	global_store_dwordx2 v[34:35], v[32:33], off offset:2048
	v_mul_f32_e32 v32, v37, v36
	v_mul_f32_e32 v33, v39, v38
	v_mul_f32_e32 v34, v42, v41
	v_mul_f32_e32 v35, v45, v44
	v_or_b32_e32 v128, v146, v68
	v_cvt_pk_bf16_f32 v32, v32, v33
	v_cvt_pk_bf16_f32 v33, v34, v35
	v_and_b32_e32 v128, -16, v128
	v_lshlrev_b64 v[34:35], 8, v[128:129]
	v_lshl_add_u64 v[34:35], s[20:21], 0, v[34:35]
	v_lshl_add_u64 v[34:35], v[34:35], 0, v[252:253]
	s_mov_b64 s[0:1], 0
	global_store_dwordx2 v[34:35], v[32:33], off offset:2048

.LBB0_264:
	global_load_dword v27, v[94:95], off
	s_nop 0
	global_load_dwordx3 v[24:26], v[130:131], off offset:324
	v_mul_f32_e32 v28, v69, v212
	v_mul_f32_e32 v29, v69, v213
	v_mul_f32_e32 v30, v69, v214
	v_mul_f32_e32 v31, v69, v215
	v_fma_f32 v32, v212, v69, -v28
	v_floor_f32_e32 v28, v28
	v_fma_f32 v33, v213, v69, -v29
	v_floor_f32_e32 v29, v29
	v_fma_f32 v34, v214, v69, -v30
	v_floor_f32_e32 v30, v30
	v_fma_f32 v35, v215, v69, -v31
	v_floor_f32_e32 v31, v31
	v_fma_f32 v28, v69, v212, -v28
	v_fma_f32 v29, v69, v213, -v29
	v_fma_f32 v30, v69, v214, -v30
	v_fma_f32 v31, v69, v215, -v31
	v_add_f32_e32 v28, v32, v28
	v_add_f32_e32 v29, v33, v29
	v_add_f32_e32 v30, v34, v30
	v_add_f32_e32 v31, v35, v31
	v_sin_f32_e32 v32, v28
	v_cos_f32_e32 v28, v28
	v_sin_f32_e32 v33, v29
	v_cos_f32_e32 v29, v29
	v_sin_f32_e32 v34, v30
	v_cos_f32_e32 v30, v30
	v_sin_f32_e32 v35, v31
	v_cos_f32_e32 v31, v31
	s_and_b64 vcc, exec, s[4:5]
	s_mov_b64 s[0:1], -1
	s_waitcnt vmcnt(1)
	v_mul_f32_e32 v16, v16, v27
	s_waitcnt vmcnt(0)
	v_mul_f32_e32 v21, v21, v24
	v_mul_f32_e32 v17, v17, v24
	v_mul_f32_e32 v24, v22, v25
	v_mul_f32_e32 v22, v18, v25
	v_mul_f32_e32 v19, v19, v26
	v_mul_f32_e32 v36, v20, v27
	v_mul_f32_e32 v25, v23, v26
	v_mul_f32_e32 v23, v32, v16
	v_mul_f32_e32 v20, v28, v16
	v_mul_f32_e32 v26, v33, v17
	v_mul_f32_e32 v18, v29, v17
	v_mul_f32_e32 v27, v34, v22
	v_mul_f32_e32 v17, v30, v22
	v_mul_f32_e32 v37, v35, v19
	v_mul_f32_e32 v16, v31, v19
	v_fma_f32 v23, v28, v36, -v23
	v_fmac_f32_e32 v20, v32, v36
	v_fma_f32 v22, v29, v21, -v26
	v_fmac_f32_e32 v18, v33, v21
	v_fma_f32 v21, v30, v24, -v27
	v_fmac_f32_e32 v17, v34, v24
	v_fma_f32 v19, v31, v25, -v37
	v_fmac_f32_e32 v16, v35, v25
	s_cbranch_vccnz .LBB0_266
	v_mul_f32_e32 v26, 0x3d800000, v23
	v_bfe_u32 v24, v26, 16, 1
	v_mul_f32_e32 v28, 0x3d800000, v20
	v_add3_u32 v27, v26, v24, s47
	v_lshl_add_u64 v[24:25], v[90:91], 0, v[152:153]
	global_store_short_d16_hi v[24:25], v27, off offset:64
	v_bfe_u32 v27, v28, 16, 1
	v_add3_u32 v27, v28, v27, s47
	global_store_short_d16_hi v[24:25], v27, off offset:96
	v_cvt_f32_ubyte0_e32 v27, v204
	v_mul_f32_e32 v27, v137, v27
	v_mul_f32_e32 v27, 0x3fb8aa3b, v27
	v_exp_f32_e32 v29, v27
	v_mul_f32_e32 v27, 0x3d800000, v22
	v_mul_f32_e32 v32, 0x3d800000, v21
	v_mul_f32_e32 v35, 0x3d800000, v19
	v_bfe_u32 v31, v27, 16, 1
	v_bfe_u32 v34, v32, 16, 1
	v_bfe_u32 v37, v35, 16, 1
	v_mul_f32_e32 v30, 0x3d800000, v18
	v_add3_u32 v31, v27, v31, s47
	v_mul_f32_e32 v33, 0x3d800000, v17
	v_add3_u32 v34, v32, v34, s47
	v_mul_f32_e32 v36, 0x3d800000, v16
	v_add3_u32 v37, v35, v37, s47
	global_store_short_d16_hi v[24:25], v31, off offset:576
	v_bfe_u32 v31, v30, 16, 1
	global_store_short_d16_hi v[24:25], v34, off offset:1088
	v_bfe_u32 v34, v33, 16, 1
	global_store_short_d16_hi v[24:25], v37, off offset:1600
	v_bfe_u32 v37, v36, 16, 1
	v_add3_u32 v31, v30, v31, s47
	v_add3_u32 v34, v33, v34, s47
	v_add3_u32 v37, v36, v37, s47
	global_store_short_d16_hi v[24:25], v31, off offset:608
	v_cvt_f32_ubyte0_e32 v31, v203
	global_store_short_d16_hi v[24:25], v34, off offset:1120
	v_cvt_f32_ubyte0_e32 v34, v198
	global_store_short_d16_hi v[24:25], v37, off offset:1632
	v_cvt_f32_ubyte0_e32 v24, v143
	v_mul_f32_e32 v31, v137, v31
	v_mul_f32_e32 v34, v137, v34
	v_mul_f32_e32 v24, v137, v24
	v_mul_f32_e32 v31, 0x3fb8aa3b, v31
	v_mul_f32_e32 v34, 0x3fb8aa3b, v34
	v_mul_f32_e32 v24, 0x3fb8aa3b, v24
	v_exp_f32_e32 v31, v31
	v_exp_f32_e32 v34, v34
	v_exp_f32_e32 v37, v24
	v_mul_f32_e32 v24, v29, v26
	v_mul_f32_e32 v25, v31, v27
	v_mul_f32_e32 v26, v34, v32
	v_mul_f32_e32 v27, v37, v35
	v_or_b32_e32 v128, v142, v65
	v_cvt_pk_bf16_f32 v24, v24, v25
	v_cvt_pk_bf16_f32 v25, v26, v27
	v_and_b32_e32 v128, -16, v128
	v_lshlrev_b64 v[26:27], 8, v[128:129]
	v_lshl_add_u64 v[26:27], s[20:21], 0, v[26:27]
	v_mov_b32_e32 v81, v153
	v_lshl_add_u64 v[26:27], v[26:27], 0, v[252:253]
	global_store_dwordx2 v[26:27], v[24:25], off offset:2560
	v_mul_f32_e32 v24, v29, v28
	v_mul_f32_e32 v25, v31, v30
	v_mul_f32_e32 v26, v34, v33
	v_mul_f32_e32 v27, v37, v36
	v_or_b32_e32 v128, v142, v68
	v_cvt_pk_bf16_f32 v24, v24, v25
	v_cvt_pk_bf16_f32 v25, v26, v27
	v_and_b32_e32 v128, -16, v128
	v_lshlrev_b64 v[26:27], 8, v[128:129]
	v_lshl_add_u64 v[26:27], s[20:21], 0, v[26:27]
	v_lshl_add_u64 v[26:27], v[26:27], 0, v[252:253]
	s_mov_b64 s[0:1], 0
	global_store_dwordx2 v[26:27], v[24:25], off offset:2560

.LBB0_268:
	global_load_dword v19, v[86:87], off
	s_nop 0
	global_load_dwordx3 v[16:18], v[130:131], off offset:388
	v_mul_f32_e32 v20, v69, v219
	v_mul_f32_e32 v21, v69, v222
	v_mul_f32_e32 v22, v69, v223
	v_mul_f32_e32 v23, v69, v224
	v_fma_f32 v24, v219, v69, -v20
	v_floor_f32_e32 v20, v20
	v_fma_f32 v25, v222, v69, -v21
	v_floor_f32_e32 v21, v21
	v_fma_f32 v26, v223, v69, -v22
	v_floor_f32_e32 v22, v22
	v_fma_f32 v27, v224, v69, -v23
	v_floor_f32_e32 v23, v23
	v_fma_f32 v20, v69, v219, -v20
	v_fma_f32 v21, v69, v222, -v21
	v_fma_f32 v22, v69, v223, -v22
	v_fma_f32 v23, v69, v224, -v23
	v_add_f32_e32 v20, v24, v20
	v_add_f32_e32 v21, v25, v21
	v_add_f32_e32 v22, v26, v22
	v_add_f32_e32 v23, v27, v23
	v_sin_f32_e32 v24, v20
	v_cos_f32_e32 v20, v20
	v_sin_f32_e32 v25, v21
	v_cos_f32_e32 v21, v21
	v_sin_f32_e32 v26, v22
	v_cos_f32_e32 v22, v22
	v_sin_f32_e32 v27, v23
	v_cos_f32_e32 v23, v23
	s_and_b64 vcc, exec, s[4:5]
	s_mov_b64 s[0:1], -1
	s_waitcnt vmcnt(1)
	v_mul_f32_e32 v8, v8, v19
	s_waitcnt vmcnt(0)
	v_mul_f32_e32 v13, v13, v16
	v_mul_f32_e32 v9, v9, v16
	v_mul_f32_e32 v16, v14, v17
	v_mul_f32_e32 v14, v10, v17
	v_mul_f32_e32 v11, v11, v18
	v_mul_f32_e32 v28, v12, v19
	v_mul_f32_e32 v17, v15, v18
	v_mul_f32_e32 v15, v24, v8
	v_mul_f32_e32 v12, v20, v8
	v_mul_f32_e32 v18, v25, v9
	v_mul_f32_e32 v10, v21, v9
	v_mul_f32_e32 v19, v26, v14
	v_mul_f32_e32 v9, v22, v14
	v_mul_f32_e32 v29, v27, v11
	v_mul_f32_e32 v8, v23, v11
	v_fma_f32 v15, v20, v28, -v15
	v_fmac_f32_e32 v12, v24, v28
	v_fma_f32 v14, v21, v13, -v18
	v_fmac_f32_e32 v10, v25, v13
	v_fma_f32 v13, v22, v16, -v19
	v_fmac_f32_e32 v9, v26, v16
	v_fma_f32 v11, v23, v17, -v29
	v_fmac_f32_e32 v8, v27, v17
	s_cbranch_vccnz .LBB0_270
	v_mul_f32_e32 v18, 0x3d800000, v15
	v_bfe_u32 v16, v18, 16, 1
	v_mul_f32_e32 v20, 0x3d800000, v12
	v_add3_u32 v19, v18, v16, s47
	v_lshl_add_u64 v[16:17], v[82:83], 0, v[152:153]
	global_store_short_d16_hi v[16:17], v19, off offset:64
	v_bfe_u32 v19, v20, 16, 1
	v_add3_u32 v19, v20, v19, s47
	global_store_short_d16_hi v[16:17], v19, off offset:96
	v_cvt_f32_ubyte0_e32 v19, v211
	v_mul_f32_e32 v19, v137, v19
	v_mul_f32_e32 v19, 0x3fb8aa3b, v19
	v_exp_f32_e32 v21, v19
	v_mul_f32_e32 v19, 0x3d800000, v14
	v_mul_f32_e32 v24, 0x3d800000, v13
	v_mul_f32_e32 v27, 0x3d800000, v11
	v_bfe_u32 v23, v19, 16, 1
	v_bfe_u32 v26, v24, 16, 1
	v_bfe_u32 v29, v27, 16, 1
	v_mul_f32_e32 v22, 0x3d800000, v10
	v_add3_u32 v23, v19, v23, s47
	v_mul_f32_e32 v25, 0x3d800000, v9
	v_add3_u32 v26, v24, v26, s47
	v_mul_f32_e32 v28, 0x3d800000, v8
	v_add3_u32 v29, v27, v29, s47
	global_store_short_d16_hi v[16:17], v23, off offset:576
	v_bfe_u32 v23, v22, 16, 1
	global_store_short_d16_hi v[16:17], v26, off offset:1088
	v_bfe_u32 v26, v25, 16, 1
	global_store_short_d16_hi v[16:17], v29, off offset:1600
	v_bfe_u32 v29, v28, 16, 1
	v_add3_u32 v23, v22, v23, s47
	v_add3_u32 v26, v25, v26, s47
	v_add3_u32 v29, v28, v29, s47
	global_store_short_d16_hi v[16:17], v23, off offset:608
	v_cvt_f32_ubyte0_e32 v23, v210
	global_store_short_d16_hi v[16:17], v26, off offset:1120
	v_cvt_f32_ubyte0_e32 v26, v205
	global_store_short_d16_hi v[16:17], v29, off offset:1632
	v_cvt_f32_ubyte0_e32 v16, v141
	v_mul_f32_e32 v23, v137, v23
	v_mul_f32_e32 v26, v137, v26
	v_mul_f32_e32 v16, v137, v16
	v_mul_f32_e32 v23, 0x3fb8aa3b, v23
	v_mul_f32_e32 v26, 0x3fb8aa3b, v26
	v_mul_f32_e32 v16, 0x3fb8aa3b, v16
	v_exp_f32_e32 v23, v23
	v_exp_f32_e32 v26, v26
	v_exp_f32_e32 v29, v16
	v_mul_f32_e32 v16, v21, v18
	v_mul_f32_e32 v17, v23, v19
	v_mul_f32_e32 v18, v26, v24
	v_mul_f32_e32 v19, v29, v27
	v_or_b32_e32 v128, v140, v65
	v_cvt_pk_bf16_f32 v16, v16, v17
	v_cvt_pk_bf16_f32 v17, v18, v19
	v_and_b32_e32 v128, -16, v128
	v_lshlrev_b64 v[18:19], 8, v[128:129]
	v_lshl_add_u64 v[18:19], s[20:21], 0, v[18:19]
	v_mov_b32_e32 v73, v153
	v_lshl_add_u64 v[18:19], v[18:19], 0, v[252:253]
	global_store_dwordx2 v[18:19], v[16:17], off offset:3072
	v_mul_f32_e32 v16, v21, v20
	v_mul_f32_e32 v17, v23, v22
	v_mul_f32_e32 v18, v26, v25
	v_mul_f32_e32 v19, v29, v28
	v_or_b32_e32 v128, v140, v68
	v_cvt_pk_bf16_f32 v16, v16, v17
	v_cvt_pk_bf16_f32 v17, v18, v19
	v_and_b32_e32 v128, -16, v128
	v_lshlrev_b64 v[18:19], 8, v[128:129]
	v_lshl_add_u64 v[18:19], s[20:21], 0, v[18:19]
	v_lshl_add_u64 v[18:19], v[18:19], 0, v[252:253]
	s_mov_b64 s[0:1], 0
	global_store_dwordx2 v[18:19], v[16:17], off offset:3072

.LBB0_272:
	global_load_dword v11, v[78:79], off
	s_nop 0
	global_load_dwordx3 v[8:10], v[130:131], off offset:452
	v_mul_f32_e32 v12, v69, v225
	v_mul_f32_e32 v13, v69, v226
	v_mul_f32_e32 v14, v69, v227
	v_mul_f32_e32 v15, v69, v228
	v_fma_f32 v16, v225, v69, -v12
	v_floor_f32_e32 v12, v12
	v_fma_f32 v17, v226, v69, -v13
	v_floor_f32_e32 v13, v13
	v_fma_f32 v18, v227, v69, -v14
	v_floor_f32_e32 v14, v14
	v_fma_f32 v19, v228, v69, -v15
	v_floor_f32_e32 v15, v15
	v_fma_f32 v12, v69, v225, -v12
	v_fma_f32 v13, v69, v226, -v13
	v_fma_f32 v14, v69, v227, -v14
	v_fma_f32 v15, v69, v228, -v15
	v_add_f32_e32 v12, v16, v12
	v_add_f32_e32 v13, v17, v13
	v_add_f32_e32 v14, v18, v14
	v_add_f32_e32 v15, v19, v15
	v_sin_f32_e32 v16, v12
	v_cos_f32_e32 v12, v12
	v_sin_f32_e32 v17, v13
	v_cos_f32_e32 v13, v13
	v_sin_f32_e32 v18, v14
	v_cos_f32_e32 v14, v14
	v_sin_f32_e32 v19, v15
	v_cos_f32_e32 v15, v15
	s_and_b64 vcc, exec, s[4:5]
	s_mov_b64 s[0:1], -1
	s_waitcnt vmcnt(1)
	v_mul_f32_e32 v0, v0, v11
	s_waitcnt vmcnt(0)
	v_mul_f32_e32 v5, v5, v8
	v_mul_f32_e32 v1, v1, v8
	v_mul_f32_e32 v8, v6, v9
	v_mul_f32_e32 v6, v2, v9
	v_mul_f32_e32 v3, v3, v10
	v_mul_f32_e32 v20, v4, v11
	v_mul_f32_e32 v9, v7, v10
	v_mul_f32_e32 v7, v16, v0
	v_mul_f32_e32 v4, v12, v0
	v_mul_f32_e32 v10, v17, v1
	v_mul_f32_e32 v2, v13, v1
	v_mul_f32_e32 v11, v18, v6
	v_mul_f32_e32 v1, v14, v6
	v_mul_f32_e32 v21, v19, v3
	v_mul_f32_e32 v0, v15, v3
	v_fma_f32 v7, v12, v20, -v7
	v_fmac_f32_e32 v4, v16, v20
	v_fma_f32 v6, v13, v5, -v10
	v_fmac_f32_e32 v2, v17, v5
	v_fma_f32 v5, v14, v8, -v11
	v_fmac_f32_e32 v1, v18, v8
	v_fma_f32 v3, v15, v9, -v21
	v_fmac_f32_e32 v0, v19, v9
	s_cbranch_vccnz .LBB0_274
	v_mul_f32_e32 v10, 0x3d800000, v7
	v_bfe_u32 v8, v10, 16, 1
	v_mul_f32_e32 v12, 0x3d800000, v4
	v_add3_u32 v11, v10, v8, s47
	v_lshl_add_u64 v[8:9], v[74:75], 0, v[152:153]
	global_store_short_d16_hi v[8:9], v11, off offset:64
	v_bfe_u32 v11, v12, 16, 1
	v_add3_u32 v11, v12, v11, s47
	global_store_short_d16_hi v[8:9], v11, off offset:96
	v_cvt_f32_ubyte0_e32 v11, v217
	v_mul_f32_e32 v11, v137, v11
	v_mul_f32_e32 v11, 0x3fb8aa3b, v11
	v_exp_f32_e32 v13, v11
	v_mul_f32_e32 v11, 0x3d800000, v6
	v_mul_f32_e32 v16, 0x3d800000, v5
	v_bfe_u32 v15, v11, 16, 1
	v_bfe_u32 v18, v16, 16, 1
	v_mul_f32_e32 v19, 0x3d800000, v3
	v_mul_f32_e32 v14, 0x3d800000, v2
	v_add3_u32 v15, v11, v15, s47
	v_mul_f32_e32 v17, 0x3d800000, v1
	v_add3_u32 v18, v16, v18, s47
	v_bfe_u32 v21, v19, 16, 1
	global_store_short_d16_hi v[8:9], v15, off offset:576
	v_bfe_u32 v15, v14, 16, 1
	global_store_short_d16_hi v[8:9], v18, off offset:1088
	v_bfe_u32 v18, v17, 16, 1
	v_mul_f32_e32 v20, 0x3d800000, v0
	v_add3_u32 v21, v19, v21, s47
	v_add3_u32 v15, v14, v15, s47
	v_add3_u32 v18, v17, v18, s47
	global_store_short_d16_hi v[8:9], v21, off offset:1600
	v_bfe_u32 v21, v20, 16, 1
	global_store_short_d16_hi v[8:9], v15, off offset:608
	v_cvt_f32_ubyte0_e32 v15, v216
	global_store_short_d16_hi v[8:9], v18, off offset:1120
	v_cvt_f32_ubyte0_e32 v18, v139
	v_add3_u32 v21, v20, v21, s47
	v_mul_f32_e32 v15, v137, v15
	v_mul_f32_e32 v18, v137, v18
	global_store_short_d16_hi v[8:9], v21, off offset:1632
	v_mul_f32_e32 v8, v137, v138
	v_mul_f32_e32 v15, 0x3fb8aa3b, v15
	v_mul_f32_e32 v18, 0x3fb8aa3b, v18
	v_mul_f32_e32 v8, 0x3fb8aa3b, v8
	v_exp_f32_e32 v15, v15
	v_exp_f32_e32 v18, v18
	v_exp_f32_e32 v21, v8
	v_mul_f32_e32 v8, v13, v10
	v_mul_f32_e32 v9, v15, v11
	v_mul_f32_e32 v10, v18, v16
	v_mul_f32_e32 v11, v21, v19
	v_or_b32_e32 v128, v136, v65
	v_cvt_pk_bf16_f32 v8, v8, v9
	v_cvt_pk_bf16_f32 v9, v10, v11
	v_and_b32_e32 v128, -16, v128
	v_lshlrev_b64 v[10:11], 8, v[128:129]
	v_lshl_add_u64 v[10:11], s[20:21], 0, v[10:11]
	v_mov_b32_e32 v65, v153
	v_lshl_add_u64 v[10:11], v[10:11], 0, v[252:253]
	global_store_dwordx2 v[10:11], v[8:9], off offset:3584
	v_mul_f32_e32 v8, v13, v12
	v_mul_f32_e32 v9, v15, v14
	v_mul_f32_e32 v10, v18, v17
	v_mul_f32_e32 v11, v21, v20
	v_or_b32_e32 v128, v136, v68
	v_cvt_pk_bf16_f32 v8, v8, v9
	v_cvt_pk_bf16_f32 v9, v10, v11
	v_and_b32_e32 v128, -16, v128
	v_lshlrev_b64 v[10:11], 8, v[128:129]
	v_lshl_add_u64 v[10:11], s[20:21], 0, v[10:11]
	v_lshl_add_u64 v[10:11], v[10:11], 0, v[252:253]
	s_mov_b64 s[0:1], 0
	global_store_dwordx2 v[10:11], v[8:9], off offset:3584

.LBB0_330:
	v_mov_b32_e32 v40, v220
	s_add_u32 s0, s72, s4
	v_ashrrev_i32_e32 v24, 2, v40
	v_min_i32_e32 v0, 0x7f, v24
	v_lshlrev_b32_e32 v1, 4, v40
	v_and_b32_e32 v6, 48, v1
	v_ashrrev_i32_e32 v1, 31, v0
	v_add_u32_e32 v26, 64, v24
	v_lshlrev_b64 v[0:1], 9, v[0:1]
	v_ashrrev_i32_e32 v25, 31, v24
	v_min_i32_e32 v2, 0x7f, v26
	s_addc_u32 s1, s73, s5
	v_or_b32_e32 v0, v0, v6
	v_lshlrev_b64 v[4:5], 9, v[24:25]
	v_lshl_add_u64 v[0:1], s[0:1], 0, v[0:1]
	v_ashrrev_i32_e32 v3, 31, v2
	v_or_b32_e32 v4, v4, v6
	v_add_co_u32_e32 v0, vcc, s3, v0
	v_lshlrev_b64 v[2:3], 9, v[2:3]
	v_lshl_add_u64 v[4:5], s[0:1], 0, v[4:5]
	v_addc_co_u32_e32 v1, vcc, 0, v1, vcc
	v_or_b32_e32 v2, v2, v6
	v_lshl_add_u64 v[6:7], s[0:1], 0, v[2:3]
	v_add_co_u32_e32 v2, vcc, s22, v4
	global_load_dwordx4 v[8:11], v[0:1], off
	s_nop 0
	v_addc_co_u32_e32 v3, vcc, 0, v5, vcc
	v_add_co_u32_e32 v4, vcc, s23, v4
	global_load_dwordx4 v[12:15], v[2:3], off
	s_nop 0
	v_addc_co_u32_e32 v5, vcc, 0, v5, vcc
	v_add_co_u32_e32 v6, vcc, s3, v6
	global_load_dwordx4 v[16:19], v[4:5], off
	s_nop 0
	v_addc_co_u32_e32 v7, vcc, 0, v7, vcc
	global_load_dwordx4 v[20:23], v[6:7], off
	v_lshrrev_b32_e32 v41, 4, v40
	v_sub_u32_e32 v25, 0, v41
	v_xor_b32_e32 v25, v40, v25
	v_lshlrev_b32_e32 v25, 4, v25
	v_and_b32_e32 v25, 48, v25
	v_lshl_or_b32 v148, v24, 6, v25
	v_lshl_or_b32 v149, v26, 6, v25
	global_load_dwordx4 v[24:27], v[2:3], off offset:64
	global_load_dwordx4 v[28:31], v[4:5], off offset:64
	global_load_dwordx4 v[32:35], v[0:1], off offset:64
	global_load_dwordx4 v[36:39], v[6:7], off offset:64
	v_lshrrev_b32_e32 v42, 2, v40
	v_sub_u32_e32 v42, 0, v42
	v_xor_b32_e32 v41, v41, v42
	v_and_b32_e32 v42, 15, v40
	v_lshrrev_b32_e32 v43, 1, v40
	v_lshlrev_b32_e32 v41, 4, v41
	v_and_or_b32 v42, v43, s24, v42
	v_and_b32_e32 v41, 48, v41
	v_lshlrev_b32_e32 v40, 6, v40
	v_lshl_or_b32 v140, v42, 6, v41
	v_and_or_b32 v144, v40, s25, v41
	s_waitcnt vmcnt(7)
	ds_write_b128 v148, v[8:11]
	s_waitcnt vmcnt(6)
	ds_write_b128 v148, v[12:15] offset:16384
	s_waitcnt vmcnt(5)
	ds_write_b128 v149, v[16:19] offset:16384
	s_waitcnt vmcnt(4)
	ds_write_b128 v149, v[20:23]
	s_waitcnt lgkmcnt(0)
	s_barrier
	global_load_dwordx4 v[8:11], v[0:1], off offset:128
	global_load_dwordx4 v[12:15], v[6:7], off offset:128
	global_load_dwordx4 v[16:19], v[2:3], off offset:128
	global_load_dwordx4 v[20:23], v[4:5], off offset:128
	ds_read_b128 v[40:43], v140
	ds_read_b128 v[44:47], v140 offset:1024
	ds_read_b128 v[48:51], v144 offset:16384
	ds_read_b128 v[52:55], v144 offset:17408
	ds_read_b128 v[56:59], v140 offset:2048
	ds_read_b128 v[60:63], v140 offset:3072
	ds_read_b128 v[68:71], v144 offset:18432
	ds_read_b128 v[72:75], v144 offset:19456
	s_setprio 1
	s_waitcnt lgkmcnt(5)
	v_mfma_f32_16x16x32_bf16 v[76:79], v[48:51], v[40:43], 0
	s_waitcnt lgkmcnt(4)
	v_mfma_f32_16x16x32_bf16 v[80:83], v[52:55], v[40:43], 0
	s_waitcnt lgkmcnt(1)
	v_mfma_f32_16x16x32_bf16 v[84:87], v[68:71], v[40:43], 0
	s_waitcnt lgkmcnt(0)
	v_mfma_f32_16x16x32_bf16 v[40:43], v[72:75], v[40:43], 0
	v_mfma_f32_16x16x32_bf16 v[88:91], v[48:51], v[44:47], 0
	v_mfma_f32_16x16x32_bf16 v[92:95], v[52:55], v[44:47], 0
	v_mfma_f32_16x16x32_bf16 v[96:99], v[68:71], v[44:47], 0
	v_mfma_f32_16x16x32_bf16 v[44:47], v[72:75], v[44:47], 0
	v_mfma_f32_16x16x32_bf16 v[100:103], v[48:51], v[56:59], 0
	v_mfma_f32_16x16x32_bf16 v[104:107], v[52:55], v[56:59], 0
	v_mfma_f32_16x16x32_bf16 v[108:111], v[68:71], v[56:59], 0
	v_mfma_f32_16x16x32_bf16 v[56:59], v[72:75], v[56:59], 0
	v_mfma_f32_16x16x32_bf16 v[48:51], v[48:51], v[60:63], 0
	v_mfma_f32_16x16x32_bf16 v[52:55], v[52:55], v[60:63], 0
	v_mfma_f32_16x16x32_bf16 v[68:71], v[68:71], v[60:63], 0
	v_mfma_f32_16x16x32_bf16 v[60:63], v[72:75], v[60:63], 0
	s_setprio 0
	s_waitcnt vmcnt(5)
	ds_write_b128 v148, v[32:35] offset:8192
	s_waitcnt vmcnt(4)
	ds_write_b128 v148, v[36:39] offset:12288
	ds_write_b128 v148, v[24:27] offset:24576
	ds_write_b128 v148, v[28:31] offset:28672
	s_waitcnt lgkmcnt(0)
	s_barrier
	global_load_dwordx4 v[24:27], v[0:1], off offset:192
	global_load_dwordx4 v[28:31], v[6:7], off offset:192
	global_load_dwordx4 v[32:35], v[2:3], off offset:192
	global_load_dwordx4 v[36:39], v[4:5], off offset:192
	ds_read_b128 v[72:75], v140 offset:8192
	ds_read_b128 v[112:115], v144 offset:24576
	ds_read_b128 v[116:119], v140 offset:9216
	ds_read_b128 v[120:123], v144 offset:25600
	ds_read_b128 v[124:127], v140 offset:10240
	ds_read_b128 v[128:131], v144 offset:26624
	ds_read_b128 v[132:135], v140 offset:11264
	ds_read_b128 v[136:139], v144 offset:27648
	s_setprio 1
	s_waitcnt lgkmcnt(6)
	v_mfma_f32_16x16x32_bf16 v[76:79], v[112:115], v[72:75], v[76:79]
	s_waitcnt lgkmcnt(4)
	v_mfma_f32_16x16x32_bf16 v[80:83], v[120:123], v[72:75], v[80:83]
	s_waitcnt lgkmcnt(2)
	v_mfma_f32_16x16x32_bf16 v[84:87], v[128:131], v[72:75], v[84:87]
	s_waitcnt lgkmcnt(0)
	v_mfma_f32_16x16x32_bf16 v[40:43], v[136:139], v[72:75], v[40:43]
	v_mfma_f32_16x16x32_bf16 v[72:75], v[112:115], v[116:119], v[88:91]
	v_mfma_f32_16x16x32_bf16 v[88:91], v[120:123], v[116:119], v[92:95]
	v_mfma_f32_16x16x32_bf16 v[92:95], v[128:131], v[116:119], v[96:99]
	v_mfma_f32_16x16x32_bf16 v[44:47], v[136:139], v[116:119], v[44:47]
	v_mfma_f32_16x16x32_bf16 v[96:99], v[112:115], v[124:127], v[100:103]
	v_mfma_f32_16x16x32_bf16 v[100:103], v[120:123], v[124:127], v[104:107]
	v_mfma_f32_16x16x32_bf16 v[104:107], v[128:131], v[124:127], v[108:111]
	v_mfma_f32_16x16x32_bf16 v[56:59], v[136:139], v[124:127], v[56:59]
	v_mfma_f32_16x16x32_bf16 v[48:51], v[112:115], v[132:135], v[48:51]
	v_mfma_f32_16x16x32_bf16 v[52:55], v[120:123], v[132:135], v[52:55]
	v_mfma_f32_16x16x32_bf16 v[68:71], v[128:131], v[132:135], v[68:71]
	v_mfma_f32_16x16x32_bf16 v[60:63], v[136:139], v[132:135], v[60:63]
	s_setprio 0
	s_waitcnt vmcnt(7)
	ds_write_b128 v148, v[8:11]
	s_waitcnt vmcnt(6)
	ds_write_b128 v149, v[12:15]
	s_waitcnt vmcnt(5)
	ds_write_b128 v148, v[16:19] offset:16384
	s_waitcnt vmcnt(4)
	ds_write_b128 v149, v[20:23] offset:16384
	s_waitcnt lgkmcnt(0)
	s_barrier
	global_load_dwordx4 v[8:11], v[0:1], off offset:256
	global_load_dwordx4 v[12:15], v[6:7], off offset:256
	global_load_dwordx4 v[16:19], v[2:3], off offset:256
	global_load_dwordx4 v[20:23], v[4:5], off offset:256
	ds_read_b128 v[108:111], v140
	ds_read_b128 v[112:115], v144 offset:16384
	ds_read_b128 v[116:119], v140 offset:1024
	ds_read_b128 v[120:123], v144 offset:17408
	ds_read_b128 v[124:127], v140 offset:2048
	ds_read_b128 v[128:131], v144 offset:18432
	ds_read_b128 v[132:135], v140 offset:3072
	ds_read_b128 v[136:139], v144 offset:19456
	s_setprio 1
	s_waitcnt lgkmcnt(6)
	v_mfma_f32_16x16x32_bf16 v[76:79], v[112:115], v[108:111], v[76:79]
	s_waitcnt lgkmcnt(4)
	v_mfma_f32_16x16x32_bf16 v[80:83], v[120:123], v[108:111], v[80:83]
	s_waitcnt lgkmcnt(2)
	v_mfma_f32_16x16x32_bf16 v[84:87], v[128:131], v[108:111], v[84:87]
	s_waitcnt lgkmcnt(0)
	v_mfma_f32_16x16x32_bf16 v[40:43], v[136:139], v[108:111], v[40:43]
	v_mfma_f32_16x16x32_bf16 v[72:75], v[112:115], v[116:119], v[72:75]
	v_mfma_f32_16x16x32_bf16 v[88:91], v[120:123], v[116:119], v[88:91]
	v_mfma_f32_16x16x32_bf16 v[92:95], v[128:131], v[116:119], v[92:95]
	v_mfma_f32_16x16x32_bf16 v[44:47], v[136:139], v[116:119], v[44:47]
	v_mfma_f32_16x16x32_bf16 v[96:99], v[112:115], v[124:127], v[96:99]
	v_mfma_f32_16x16x32_bf16 v[100:103], v[120:123], v[124:127], v[100:103]
	v_mfma_f32_16x16x32_bf16 v[104:107], v[128:131], v[124:127], v[104:107]
	v_mfma_f32_16x16x32_bf16 v[56:59], v[136:139], v[124:127], v[56:59]
	v_mfma_f32_16x16x32_bf16 v[48:51], v[112:115], v[132:135], v[48:51]
	v_mfma_f32_16x16x32_bf16 v[52:55], v[120:123], v[132:135], v[52:55]
	v_mfma_f32_16x16x32_bf16 v[68:71], v[128:131], v[132:135], v[68:71]
	v_mfma_f32_16x16x32_bf16 v[60:63], v[136:139], v[132:135], v[60:63]
	s_setprio 0
	s_waitcnt vmcnt(7)
	ds_write_b128 v148, v[24:27] offset:8192
	s_waitcnt vmcnt(6)
	ds_write_b128 v148, v[28:31] offset:12288
	s_waitcnt vmcnt(5)
	ds_write_b128 v148, v[32:35] offset:24576
	s_waitcnt vmcnt(4)
	ds_write_b128 v148, v[36:39] offset:28672
	s_waitcnt lgkmcnt(0)
	s_barrier
	global_load_dwordx4 v[24:27], v[0:1], off offset:320
	global_load_dwordx4 v[28:31], v[6:7], off offset:320
	global_load_dwordx4 v[32:35], v[2:3], off offset:320
	global_load_dwordx4 v[36:39], v[4:5], off offset:320
	ds_read_b128 v[108:111], v140 offset:8192
	ds_read_b128 v[112:115], v144 offset:24576
	ds_read_b128 v[116:119], v140 offset:9216
	ds_read_b128 v[120:123], v144 offset:25600
	ds_read_b128 v[124:127], v140 offset:10240
	ds_read_b128 v[128:131], v144 offset:26624
	ds_read_b128 v[132:135], v140 offset:11264
	ds_read_b128 v[136:139], v144 offset:27648
	s_setprio 1
	s_waitcnt lgkmcnt(6)
	v_mfma_f32_16x16x32_bf16 v[76:79], v[112:115], v[108:111], v[76:79]
	s_waitcnt lgkmcnt(4)
	v_mfma_f32_16x16x32_bf16 v[80:83], v[120:123], v[108:111], v[80:83]
	s_waitcnt lgkmcnt(2)
	v_mfma_f32_16x16x32_bf16 v[84:87], v[128:131], v[108:111], v[84:87]
	s_waitcnt lgkmcnt(0)
	v_mfma_f32_16x16x32_bf16 v[40:43], v[136:139], v[108:111], v[40:43]
	v_mfma_f32_16x16x32_bf16 v[72:75], v[112:115], v[116:119], v[72:75]
	v_mfma_f32_16x16x32_bf16 v[88:91], v[120:123], v[116:119], v[88:91]
	v_mfma_f32_16x16x32_bf16 v[92:95], v[128:131], v[116:119], v[92:95]
	v_mfma_f32_16x16x32_bf16 v[44:47], v[136:139], v[116:119], v[44:47]
	v_mfma_f32_16x16x32_bf16 v[96:99], v[112:115], v[124:127], v[96:99]
	v_mfma_f32_16x16x32_bf16 v[100:103], v[120:123], v[124:127], v[100:103]
	v_mfma_f32_16x16x32_bf16 v[104:107], v[128:131], v[124:127], v[104:107]
	v_mfma_f32_16x16x32_bf16 v[56:59], v[136:139], v[124:127], v[56:59]
	v_mfma_f32_16x16x32_bf16 v[48:51], v[112:115], v[132:135], v[48:51]
	v_mfma_f32_16x16x32_bf16 v[52:55], v[120:123], v[132:135], v[52:55]
	v_mfma_f32_16x16x32_bf16 v[68:71], v[128:131], v[132:135], v[68:71]
	v_mfma_f32_16x16x32_bf16 v[60:63], v[136:139], v[132:135], v[60:63]
	s_setprio 0
	s_waitcnt vmcnt(7)
	ds_write_b128 v148, v[8:11]
	s_waitcnt vmcnt(6)
	ds_write_b128 v149, v[12:15]
	s_waitcnt vmcnt(5)
	ds_write_b128 v148, v[16:19] offset:16384
	s_waitcnt vmcnt(4)
	ds_write_b128 v149, v[20:23] offset:16384
	s_waitcnt lgkmcnt(0)
	s_barrier
	global_load_dwordx4 v[8:11], v[0:1], off offset:384
	global_load_dwordx4 v[12:15], v[6:7], off offset:384
	global_load_dwordx4 v[16:19], v[2:3], off offset:384
	global_load_dwordx4 v[20:23], v[4:5], off offset:384
	ds_read_b128 v[108:111], v140
	ds_read_b128 v[112:115], v144 offset:16384
	ds_read_b128 v[116:119], v140 offset:1024
	ds_read_b128 v[120:123], v144 offset:17408
	ds_read_b128 v[124:127], v140 offset:2048
	ds_read_b128 v[128:131], v144 offset:18432
	ds_read_b128 v[132:135], v140 offset:3072
	ds_read_b128 v[136:139], v144 offset:19456
	s_setprio 1
	s_waitcnt lgkmcnt(6)
	v_mfma_f32_16x16x32_bf16 v[76:79], v[112:115], v[108:111], v[76:79]
	s_waitcnt lgkmcnt(4)
	v_mfma_f32_16x16x32_bf16 v[80:83], v[120:123], v[108:111], v[80:83]
	s_waitcnt lgkmcnt(2)
	v_mfma_f32_16x16x32_bf16 v[84:87], v[128:131], v[108:111], v[84:87]
	s_waitcnt lgkmcnt(0)
	v_mfma_f32_16x16x32_bf16 v[40:43], v[136:139], v[108:111], v[40:43]
	v_mfma_f32_16x16x32_bf16 v[72:75], v[112:115], v[116:119], v[72:75]
	v_mfma_f32_16x16x32_bf16 v[88:91], v[120:123], v[116:119], v[88:91]
	v_mfma_f32_16x16x32_bf16 v[92:95], v[128:131], v[116:119], v[92:95]
	v_mfma_f32_16x16x32_bf16 v[44:47], v[136:139], v[116:119], v[44:47]
	v_mfma_f32_16x16x32_bf16 v[96:99], v[112:115], v[124:127], v[96:99]
	v_mfma_f32_16x16x32_bf16 v[100:103], v[120:123], v[124:127], v[100:103]
	v_mfma_f32_16x16x32_bf16 v[104:107], v[128:131], v[124:127], v[104:107]
	v_mfma_f32_16x16x32_bf16 v[56:59], v[136:139], v[124:127], v[56:59]
	v_mfma_f32_16x16x32_bf16 v[48:51], v[112:115], v[132:135], v[48:51]
	v_mfma_f32_16x16x32_bf16 v[52:55], v[120:123], v[132:135], v[52:55]
	v_mfma_f32_16x16x32_bf16 v[68:71], v[128:131], v[132:135], v[68:71]
	v_mfma_f32_16x16x32_bf16 v[60:63], v[136:139], v[132:135], v[60:63]
	s_setprio 0
	s_waitcnt vmcnt(7)
	ds_write_b128 v148, v[24:27] offset:8192
	s_waitcnt vmcnt(6)
	ds_write_b128 v148, v[28:31] offset:12288
	s_waitcnt vmcnt(5)
	ds_write_b128 v148, v[32:35] offset:24576
	s_waitcnt vmcnt(4)
	ds_write_b128 v148, v[36:39] offset:28672
	s_waitcnt lgkmcnt(0)
	s_barrier
	global_load_dwordx4 v[24:27], v[0:1], off offset:448
	global_load_dwordx4 v[28:31], v[6:7], off offset:448
	global_load_dwordx4 v[32:35], v[2:3], off offset:448
	global_load_dwordx4 v[36:39], v[4:5], off offset:448
	ds_read_b128 v[108:111], v140 offset:8192
	ds_read_b128 v[112:115], v144 offset:24576
	ds_read_b128 v[116:119], v140 offset:9216
	ds_read_b128 v[120:123], v144 offset:25600
	ds_read_b128 v[124:127], v140 offset:10240
	ds_read_b128 v[128:131], v144 offset:26624
	ds_read_b128 v[132:135], v140 offset:11264
	ds_read_b128 v[136:139], v144 offset:27648
	s_setprio 1
	s_waitcnt lgkmcnt(6)
	v_mfma_f32_16x16x32_bf16 v[76:79], v[112:115], v[108:111], v[76:79]
	s_waitcnt lgkmcnt(4)
	v_mfma_f32_16x16x32_bf16 v[80:83], v[120:123], v[108:111], v[80:83]
	s_waitcnt lgkmcnt(2)
	v_mfma_f32_16x16x32_bf16 v[84:87], v[128:131], v[108:111], v[84:87]
	s_waitcnt lgkmcnt(0)
	v_mfma_f32_16x16x32_bf16 v[40:43], v[136:139], v[108:111], v[40:43]
	v_mfma_f32_16x16x32_bf16 v[72:75], v[112:115], v[116:119], v[72:75]
	v_mfma_f32_16x16x32_bf16 v[88:91], v[120:123], v[116:119], v[88:91]
	v_mfma_f32_16x16x32_bf16 v[92:95], v[128:131], v[116:119], v[92:95]
	v_mfma_f32_16x16x32_bf16 v[44:47], v[136:139], v[116:119], v[44:47]
	v_mfma_f32_16x16x32_bf16 v[96:99], v[112:115], v[124:127], v[96:99]
	v_mfma_f32_16x16x32_bf16 v[100:103], v[120:123], v[124:127], v[100:103]
	v_mfma_f32_16x16x32_bf16 v[104:107], v[128:131], v[124:127], v[104:107]
	v_mfma_f32_16x16x32_bf16 v[56:59], v[136:139], v[124:127], v[56:59]
	v_mfma_f32_16x16x32_bf16 v[48:51], v[112:115], v[132:135], v[48:51]
	v_mfma_f32_16x16x32_bf16 v[52:55], v[120:123], v[132:135], v[52:55]
	v_mfma_f32_16x16x32_bf16 v[68:71], v[128:131], v[132:135], v[68:71]
	v_mfma_f32_16x16x32_bf16 v[60:63], v[136:139], v[132:135], v[60:63]
	s_setprio 0
	s_waitcnt vmcnt(7)
	ds_write_b128 v148, v[8:11]
	s_waitcnt vmcnt(6)
	ds_write_b128 v149, v[12:15]
	s_waitcnt vmcnt(5)
	ds_write_b128 v148, v[16:19] offset:16384
	s_waitcnt vmcnt(4)
	ds_write_b128 v149, v[20:23] offset:16384
	s_waitcnt lgkmcnt(0)
	s_barrier
	global_load_dwordx4 v[108:111], v[0:1], off offset:448
	global_load_dwordx4 v[112:115], v[6:7], off offset:448
	global_load_dwordx4 v[116:119], v[2:3], off offset:448
	global_load_dwordx4 v[120:123], v[4:5], off offset:448
	ds_read_b128 v[0:3], v140
	ds_read_b128 v[4:7], v144 offset:16384
	ds_read_b128 v[8:11], v140 offset:1024
	ds_read_b128 v[12:15], v144 offset:17408
	ds_read_b128 v[16:19], v140 offset:2048
	ds_read_b128 v[20:23], v144 offset:18432
	ds_read_b128 v[124:127], v140 offset:3072
	ds_read_b128 v[128:131], v144 offset:19456
	s_setprio 1
	s_waitcnt lgkmcnt(6)
	v_mfma_f32_16x16x32_bf16 v[76:79], v[4:7], v[0:3], v[76:79]
	s_waitcnt lgkmcnt(4)
	v_mfma_f32_16x16x32_bf16 v[80:83], v[12:15], v[0:3], v[80:83]
	s_waitcnt lgkmcnt(2)
	v_mfma_f32_16x16x32_bf16 v[84:87], v[20:23], v[0:3], v[84:87]
	s_waitcnt lgkmcnt(0)
	v_mfma_f32_16x16x32_bf16 v[0:3], v[128:131], v[0:3], v[40:43]
	v_mfma_f32_16x16x32_bf16 v[40:43], v[4:7], v[8:11], v[72:75]
	v_mfma_f32_16x16x32_bf16 v[72:75], v[12:15], v[8:11], v[88:91]
	v_mfma_f32_16x16x32_bf16 v[88:91], v[20:23], v[8:11], v[92:95]
	v_mfma_f32_16x16x32_bf16 v[8:11], v[128:131], v[8:11], v[44:47]
	v_mfma_f32_16x16x32_bf16 v[92:95], v[4:7], v[16:19], v[96:99]
	v_mfma_f32_16x16x32_bf16 v[96:99], v[12:15], v[16:19], v[100:103]
	v_mfma_f32_16x16x32_bf16 v[100:103], v[20:23], v[16:19], v[104:107]
	v_mfma_f32_16x16x32_bf16 v[16:19], v[128:131], v[16:19], v[56:59]
	v_mfma_f32_16x16x32_bf16 v[4:7], v[4:7], v[124:127], v[48:51]
	v_mfma_f32_16x16x32_bf16 v[104:107], v[12:15], v[124:127], v[52:55]
	v_mfma_f32_16x16x32_bf16 v[68:71], v[20:23], v[124:127], v[68:71]
	v_mfma_f32_16x16x32_bf16 v[60:63], v[128:131], v[124:127], v[60:63]
	s_setprio 0
	s_waitcnt vmcnt(7)
	ds_write_b128 v148, v[24:27] offset:8192
	s_waitcnt vmcnt(6)
	ds_write_b128 v148, v[28:31] offset:12288
	s_waitcnt vmcnt(5)
	ds_write_b128 v148, v[32:35] offset:24576
	s_waitcnt vmcnt(4)
	ds_write_b128 v148, v[36:39] offset:28672
	s_waitcnt lgkmcnt(0)
	s_barrier
	ds_read_b128 v[12:15], v140 offset:8192
	ds_read_b128 v[124:127], v144 offset:24576
	ds_read_b128 v[20:23], v140 offset:9216
	ds_read_b128 v[128:131], v144 offset:25600
	ds_read_b128 v[132:135], v140 offset:10240
	ds_read_b128 v[136:139], v144 offset:26624
	ds_read_b128 v[140:143], v140 offset:11264
	ds_read_b128 v[144:147], v144 offset:27648
	s_setprio 1
	s_waitcnt lgkmcnt(6)
	v_mfma_f32_16x16x32_bf16 v[76:79], v[124:127], v[12:15], v[76:79]
	s_waitcnt lgkmcnt(4)
	v_mfma_f32_16x16x32_bf16 v[56:59], v[128:131], v[12:15], v[80:83]
	s_waitcnt lgkmcnt(2)
	v_mfma_f32_16x16x32_bf16 v[52:55], v[136:139], v[12:15], v[84:87]
	s_waitcnt lgkmcnt(0)
	v_mfma_f32_16x16x32_bf16 v[48:51], v[144:147], v[12:15], v[0:3]
	v_mfma_f32_16x16x32_bf16 v[44:47], v[124:127], v[20:23], v[40:43]
	v_mfma_f32_16x16x32_bf16 v[40:43], v[128:131], v[20:23], v[72:75]
	v_mfma_f32_16x16x32_bf16 v[36:39], v[136:139], v[20:23], v[88:91]
	v_mfma_f32_16x16x32_bf16 v[32:35], v[144:147], v[20:23], v[8:11]
	v_mfma_f32_16x16x32_bf16 v[28:31], v[124:127], v[132:135], v[92:95]
	v_mfma_f32_16x16x32_bf16 v[24:27], v[128:131], v[132:135], v[96:99]
	v_mfma_f32_16x16x32_bf16 v[20:23], v[136:139], v[132:135], v[100:103]
	v_mfma_f32_16x16x32_bf16 v[16:19], v[144:147], v[132:135], v[16:19]
	v_mfma_f32_16x16x32_bf16 v[12:15], v[124:127], v[140:143], v[4:7]
	v_mfma_f32_16x16x32_bf16 v[8:11], v[128:131], v[140:143], v[104:107]
	v_mfma_f32_16x16x32_bf16 v[4:7], v[136:139], v[140:143], v[68:71]
	v_mfma_f32_16x16x32_bf16 v[0:3], v[144:147], v[140:143], v[60:63]
	s_setprio 0
	s_nop 1
	v_mov_b32_e32 v60, v220
	s_waitcnt vmcnt(3)
	ds_write_b128 v148, v[108:111]
	s_waitcnt vmcnt(2)
	ds_write_b128 v149, v[112:115]
	s_waitcnt vmcnt(1)
	ds_write_b128 v148, v[116:119] offset:16384
	s_waitcnt vmcnt(0)
	ds_write_b128 v149, v[120:123] offset:16384
	s_waitcnt lgkmcnt(0)
	s_barrier
	s_bfe_u32 s0, s35, 0x20007
	v_and_b32_e32 v62, 15, v60
	v_and_b32_e32 v61, 64, v60
	v_ashrrev_i32_e32 v63, 1, v60
	v_lshrrev_b32_e32 v60, 2, v60
	v_and_or_b32 v71, v60, 12, v61
	v_cvt_f32_ubyte0_e32 v60, s0
	v_sub_f32_e32 v60, 0xc0a00000, v60
	v_cmp_gt_f32_e32 vcc, s27, v60
	s_and_b64 s[0:1], vcc, exec
	s_cselect_b32 s0, 0xffffffc0, 0
	v_cndmask_b32_e32 v61, 0, v64, vcc
	v_add_f32_e32 v60, v60, v61
	v_exp_f32_e32 v60, v60
	v_and_or_b32 v72, v63, s26, v62
	v_lshlrev_b32_e32 v63, 7, v63
	v_lshlrev_b32_e32 v62, 7, v62
	v_ldexp_f32 v68, v60, s0
	v_sub_f32_e32 v69, 1.0, v68
	v_add_f32_e32 v60, -1.0, v69
	v_sub_f32_e32 v61, v60, v69
	v_add_f32_e32 v61, 1.0, v61
	v_sub_f32_e64 v60, -v68, v60
	v_add_f32_e32 v70, v60, v61
	v_frexp_mant_f32_e32 v60, v69
	v_cmp_gt_f32_e32 vcc, s28, v60
	v_cvt_f64_f32_e32 v[60:61], v69
	v_frexp_exp_i32_f64_e32 v60, v[60:61]
	v_subbrev_co_u32_e32 v60, vcc, 0, v60, vcc
	v_sub_u32_e32 v61, 0, v60
	v_ldexp_f32 v69, v69, v61
	v_ldexp_f32 v61, v70, v61
	v_add_f32_e32 v70, -1.0, v69
	v_add_f32_e32 v73, 1.0, v70
	v_sub_f32_e32 v73, v69, v73
	v_add_f32_e32 v73, v61, v73
	v_add_f32_e32 v74, v70, v73
	v_sub_f32_e32 v70, v74, v70
	v_sub_f32_e32 v70, v73, v70
	v_add_f32_e32 v73, 1.0, v69
	v_add_f32_e32 v75, -1.0, v73
	v_sub_f32_e32 v69, v69, v75
	v_add_f32_e32 v61, v61, v69
	v_add_f32_e32 v69, v73, v61
	v_sub_f32_e32 v73, v69, v73
	v_sub_f32_e32 v61, v61, v73
	v_rcp_f32_e32 v73, v69
	v_cvt_f32_i32_e32 v60, v60
	v_cmp_nlt_f32_e32 vcc, 1.0, v68
	v_cmp_gt_i32_e64 s[0:1], v72, v71
	v_mul_f32_e32 v75, v74, v73
	v_mul_f32_e32 v80, v69, v75
	v_fma_f32 v81, v75, v69, -v80
	v_fmac_f32_e32 v81, v75, v61
	v_add_f32_e32 v82, v80, v81
	v_sub_f32_e32 v83, v74, v82
	v_sub_f32_e32 v74, v74, v83
	v_sub_f32_e32 v80, v82, v80
	v_sub_f32_e32 v74, v74, v82
	v_add_f32_e32 v70, v70, v74
	v_sub_f32_e32 v74, v80, v81
	v_add_f32_e32 v70, v74, v70
	v_add_f32_e32 v74, v83, v70
	v_mul_f32_e32 v80, v73, v74
	v_mul_f32_e32 v81, v69, v80
	v_fma_f32 v69, v80, v69, -v81
	v_fmac_f32_e32 v69, v80, v61
	v_sub_f32_e32 v61, v83, v74
	v_add_f32_e32 v61, v70, v61
	v_add_f32_e32 v70, v81, v69
	v_sub_f32_e32 v82, v74, v70
	v_sub_f32_e32 v74, v74, v82
	v_sub_f32_e32 v81, v70, v81
	v_sub_f32_e32 v70, v74, v70
	v_add_f32_e32 v61, v61, v70
	v_sub_f32_e32 v69, v81, v69
	v_add_f32_e32 v61, v69, v61
	v_add_f32_e32 v69, v75, v80
	v_add_f32_e32 v61, v82, v61
	v_sub_f32_e32 v70, v69, v75
	v_mul_f32_e32 v61, v73, v61
	v_sub_f32_e32 v70, v80, v70
	v_add_f32_e32 v61, v70, v61
	v_mul_f32_e32 v75, 0x3f317218, v60
	v_add_f32_e32 v70, v69, v61
	v_fma_f32 v80, v60, s29, -v75
	v_mul_f32_e32 v73, v70, v70
	v_fmac_f32_e32 v80, 0xb102e308, v60
	v_sub_f32_e32 v60, v70, v69
	v_fmamk_f32 v74, v73, 0x3e9b6dac, v65
	v_sub_f32_e32 v60, v61, v60
	v_add_f32_e32 v61, v75, v80
	v_fmaak_f32 v74, v73, v74, 0x3f2aaada
	v_sub_f32_e32 v69, v61, v75
	v_ldexp_f32 v75, v70, 1
	v_mul_f32_e32 v70, v70, v73
	v_mul_f32_e32 v70, v70, v74
	v_add_f32_e32 v73, v75, v70
	v_sub_f32_e32 v74, v73, v75
	v_ldexp_f32 v60, v60, 1
	v_sub_f32_e32 v70, v70, v74
	v_add_f32_e32 v60, v60, v70
	v_add_f32_e32 v70, v73, v60
	v_sub_f32_e32 v73, v70, v73
	v_sub_f32_e32 v60, v60, v73
	v_add_f32_e32 v73, v61, v70
	v_sub_f32_e32 v74, v73, v61
	v_sub_f32_e32 v75, v73, v74
	v_sub_f32_e32 v69, v80, v69
	v_sub_f32_e32 v61, v61, v75
	v_sub_f32_e32 v70, v70, v74
	v_add_f32_e32 v61, v70, v61
	v_add_f32_e32 v70, v69, v60
	v_sub_f32_e32 v74, v70, v69
	v_sub_f32_e32 v75, v70, v74
	v_sub_f32_e32 v69, v69, v75
	v_sub_f32_e32 v60, v60, v74
	v_add_f32_e32 v61, v70, v61
	v_add_f32_e32 v60, v60, v69
	v_add_f32_e32 v69, v73, v61
	v_sub_f32_e32 v70, v69, v73
	v_sub_f32_e32 v61, v61, v70
	v_add_f32_e32 v60, v60, v61
	v_add_f32_e32 v60, v69, v60
	v_cndmask_b32_e32 v60, v66, v60, vcc
	v_cmp_neq_f32_e32 vcc, 1.0, v68
	v_or_b32_e32 v75, 1, v71
	v_sub_u32_e32 v61, v72, v75
	v_cndmask_b32_e32 v60, v67, v60, vcc
	v_cmp_gt_f32_e32 vcc, s30, v68
	v_or_b32_e32 v73, 2, v71
	v_cvt_f32_i32_e32 v61, v61
	v_cndmask_b32_e64 v68, v60, -v68, vcc
	v_sub_u32_e32 v60, v72, v71
	v_cvt_f32_i32_e32 v60, v60
	v_sub_u32_e32 v70, v72, v73
	v_or_b32_e32 v74, 3, v71
	v_cvt_f32_i32_e32 v70, v70
	v_mul_f32_e32 v60, v68, v60
	v_mul_f32_e32 v60, 0x3fb8aa3b, v60
	v_exp_f32_e32 v69, v60
	v_mul_f32_e32 v61, v68, v61
	v_mul_f32_e32 v61, 0x3fb8aa3b, v61
	v_mul_f32_e32 v70, v68, v70
	v_mul_f32_e32 v60, v76, v69
	v_sub_u32_e32 v76, v72, v74
	v_cvt_f32_i32_e32 v76, v76
	v_exp_f32_e32 v61, v61
	v_mul_f32_e32 v70, 0x3fb8aa3b, v70
	v_exp_f32_e32 v70, v70
	v_mul_f32_e32 v76, v68, v76
	v_mul_f32_e32 v76, 0x3fb8aa3b, v76
	v_exp_f32_e32 v76, v76
	v_mul_f32_e32 v61, v77, v61
	v_cndmask_b32_e64 v61, 0, v61, s[0:1]
	v_mul_f32_e32 v70, v78, v70
	v_cmp_ge_i32_e64 s[0:1], v72, v73
	v_cmp_lt_i32_e32 vcc, v72, v71
	v_mul_f32_e32 v76, v79, v76
	v_cndmask_b32_e64 v70, 0, v70, s[0:1]
	v_cmp_ge_i32_e64 s[0:1], v72, v74
	v_and_b32_e32 v62, s31, v63
	v_cndmask_b32_e64 v60, v60, 0, vcc
	v_cndmask_b32_e64 v76, 0, v76, s[0:1]
	v_ashrrev_i32_e32 v63, 31, v62
	v_cvt_pk_bf16_f32 v60, v60, v61
	v_cvt_pk_bf16_f32 v61, v70, v76
	v_lshlrev_b64 v[62:63], 1, v[62:63]
	v_and_b32_e32 v76, 64, v71
	v_lshlrev_b32_e32 v76, 5, v76
	v_and_b32_e32 v253, 8, v71
	v_lshl_or_b32 v76, v253, 5, v76
	v_and_b32_e32 v253, 4, v71
	v_lshl_or_b32 v76, v253, 1, v76
	v_and_b32_e32 v253, 15, v72
	v_lshl_or_b32 v76, v253, 4, v76
	s_add_u32 s20, s72, s14
	v_or_b32_e32 v62, v62, v76
	s_addc_u32 s21, s73, s15
	v_lshl_add_u64 v[62:63], s[20:21], 0, v[62:63]
	v_add_co_u32_e64 v62, s[0:1], s34, v62
	v_or_b32_e32 v70, 16, v71
	s_nop 0
	v_addc_co_u32_e64 v63, s[0:1], 0, v63, s[0:1]
	global_store_dwordx2 v[62:63], v[60:61], off
	v_sub_u32_e32 v60, v72, v70
	v_cvt_f32_i32_e32 v60, v60
	v_or_b32_e32 v61, 17, v71
	v_cmp_ge_i32_e64 s[0:1], v72, v70
	v_mul_f32_e32 v40, v40, v69
	v_mul_f32_e32 v60, v68, v60
	v_mul_f32_e32 v60, 0x3fb8aa3b, v60
	v_exp_f32_e32 v60, v60
	v_cndmask_b32_e64 v40, v40, 0, vcc
	v_mul_f32_e32 v20, v20, v69
	v_cndmask_b32_e64 v20, v20, 0, vcc
	v_mul_f32_e32 v56, v56, v60
	v_sub_u32_e32 v60, v72, v61
	v_cvt_f32_i32_e32 v60, v60
	v_cndmask_b32_e64 v56, 0, v56, s[0:1]
	v_cmp_ge_i32_e64 s[0:1], v72, v61
	s_add_i32 s35, s35, s74
	v_mul_f32_e32 v60, v68, v60
	v_mul_f32_e32 v60, 0x3fb8aa3b, v60
	v_exp_f32_e32 v60, v60
	s_add_u32 s4, s4, s8
	v_mul_f32_e32 v0, v0, v69
	s_addc_u32 s5, s5, s9
	v_mul_f32_e32 v57, v57, v60
	v_or_b32_e32 v60, 18, v71
	v_sub_u32_e32 v77, v72, v60
	v_cvt_f32_i32_e32 v77, v77
	v_cndmask_b32_e64 v57, 0, v57, s[0:1]
	v_cmp_ge_i32_e64 s[0:1], v72, v60
	v_cvt_pk_bf16_f32 v56, v56, v57
	v_mul_f32_e32 v77, v68, v77
	v_mul_f32_e32 v77, 0x3fb8aa3b, v77
	v_exp_f32_e32 v77, v77
	v_cndmask_b32_e64 v0, v0, 0, vcc
	s_add_u32 s14, s14, s16
	s_addc_u32 s15, s15, s17
	v_mul_f32_e32 v58, v58, v77
	v_cndmask_b32_e64 v77, 0, v58, s[0:1]
	v_or_b32_e32 v58, 19, v71
	v_sub_u32_e32 v78, v72, v58
	v_cvt_f32_i32_e32 v78, v78
	v_cmp_ge_i32_e64 s[0:1], v72, v58
	s_cmpk_lt_i32 s35, 0x400
	v_mul_f32_e32 v78, v68, v78
	v_mul_f32_e32 v78, 0x3fb8aa3b, v78
	v_exp_f32_e32 v78, v78
	s_nop 0
	v_mul_f32_e32 v59, v59, v78
	v_cndmask_b32_e64 v59, 0, v59, s[0:1]
	v_cvt_pk_bf16_f32 v57, v77, v59
	global_store_dwordx2 v[62:63], v[56:57], off offset:512
	v_or_b32_e32 v57, 32, v71
	v_sub_u32_e32 v56, v72, v57
	v_cvt_f32_i32_e32 v56, v56
	v_cmp_ge_i32_e64 s[0:1], v72, v57
	v_mul_f32_e32 v56, v68, v56
	v_mul_f32_e32 v56, 0x3fb8aa3b, v56
	v_exp_f32_e32 v56, v56
	s_nop 0
	v_mul_f32_e32 v52, v52, v56
	v_or_b32_e32 v56, 33, v71
	v_cndmask_b32_e64 v59, 0, v52, s[0:1]
	v_sub_u32_e32 v52, v72, v56
	v_cvt_f32_i32_e32 v52, v52
	v_cmp_ge_i32_e64 s[0:1], v72, v56
	v_mul_f32_e32 v52, v68, v52
	v_mul_f32_e32 v52, 0x3fb8aa3b, v52
	v_exp_f32_e32 v52, v52
	s_nop 0
	v_mul_f32_e32 v52, v53, v52
	v_or_b32_e32 v53, 34, v71
	v_cndmask_b32_e64 v77, 0, v52, s[0:1]
	v_sub_u32_e32 v52, v72, v53
	v_cvt_f32_i32_e32 v52, v52
	v_cmp_ge_i32_e64 s[0:1], v72, v53
	v_mul_f32_e32 v52, v68, v52
	v_mul_f32_e32 v52, 0x3fb8aa3b, v52
	v_exp_f32_e32 v52, v52
	s_nop 0
	v_mul_f32_e32 v52, v54, v52
	v_cndmask_b32_e64 v78, 0, v52, s[0:1]
	v_or_b32_e32 v52, 35, v71
	v_sub_u32_e32 v54, v72, v52
	v_cvt_f32_i32_e32 v54, v54
	v_cmp_ge_i32_e64 s[0:1], v72, v52
	v_mul_f32_e32 v54, v68, v54
	v_mul_f32_e32 v54, 0x3fb8aa3b, v54
	v_exp_f32_e32 v54, v54
	s_nop 0
	v_mul_f32_e32 v54, v55, v54
	v_cndmask_b32_e64 v55, 0, v54, s[0:1]
	v_cvt_pk_bf16_f32 v55, v78, v55
	v_cvt_pk_bf16_f32 v54, v59, v77
	global_store_dwordx2 v[62:63], v[54:55], off offset:1024
	v_or_b32_e32 v55, 48, v71
	v_sub_u32_e32 v54, v72, v55
	v_cvt_f32_i32_e32 v54, v54
	v_cmp_ge_i32_e64 s[0:1], v72, v55
	v_mul_f32_e32 v54, v68, v54
	v_mul_f32_e32 v54, 0x3fb8aa3b, v54
	v_exp_f32_e32 v54, v54
	s_nop 0
	v_mul_f32_e32 v48, v48, v54
	v_or_b32_e32 v54, 49, v71
	v_cndmask_b32_e64 v59, 0, v48, s[0:1]
	v_sub_u32_e32 v48, v72, v54
	v_cvt_f32_i32_e32 v48, v48
	v_cmp_ge_i32_e64 s[0:1], v72, v54
	v_mul_f32_e32 v48, v68, v48
	v_mul_f32_e32 v48, 0x3fb8aa3b, v48
	v_exp_f32_e32 v48, v48
	s_nop 0
	v_mul_f32_e32 v48, v49, v48
	v_or_b32_e32 v49, 50, v71
	v_cndmask_b32_e64 v77, 0, v48, s[0:1]
	v_sub_u32_e32 v48, v72, v49
	v_cvt_f32_i32_e32 v48, v48
	v_cmp_ge_i32_e64 s[0:1], v72, v49
	v_mul_f32_e32 v48, v68, v48
	v_mul_f32_e32 v48, 0x3fb8aa3b, v48
	v_exp_f32_e32 v48, v48
	s_nop 0
	v_mul_f32_e32 v48, v50, v48
	v_cndmask_b32_e64 v78, 0, v48, s[0:1]
	v_or_b32_e32 v48, 51, v71
	v_sub_u32_e32 v50, v72, v48
	v_cvt_f32_i32_e32 v50, v50
	v_cmp_ge_i32_e64 s[0:1], v72, v48
	v_mul_f32_e32 v50, v68, v50
	v_mul_f32_e32 v50, 0x3fb8aa3b, v50
	v_exp_f32_e32 v50, v50
	s_nop 0
	v_mul_f32_e32 v50, v51, v50
	v_cndmask_b32_e64 v51, 0, v50, s[0:1]
	v_cvt_pk_bf16_f32 v50, v59, v77
	v_cvt_pk_bf16_f32 v51, v78, v51
	global_store_dwordx2 v[62:63], v[50:51], off offset:1536
	v_or_b32_e32 v50, 16, v72
	v_sub_u32_e32 v51, v50, v71
	v_cvt_f32_i32_e32 v51, v51
	v_cmp_ge_i32_e64 s[0:1], v50, v71
	v_mul_f32_e32 v51, v68, v51
	v_mul_f32_e32 v51, 0x3fb8aa3b, v51
	v_exp_f32_e32 v51, v51
	s_nop 0
	v_mul_f32_e32 v44, v44, v51
	v_sub_u32_e32 v51, v50, v75
	v_cvt_f32_i32_e32 v51, v51
	v_cndmask_b32_e64 v44, 0, v44, s[0:1]
	v_cmp_gt_i32_e64 s[0:1], v50, v71
	v_mul_f32_e32 v51, v68, v51
	v_mul_f32_e32 v51, 0x3fb8aa3b, v51
	v_exp_f32_e32 v51, v51
	s_nop 0
	v_mul_f32_e32 v45, v45, v51
	v_sub_u32_e32 v51, v50, v73
	v_cvt_f32_i32_e32 v51, v51
	v_cndmask_b32_e64 v45, 0, v45, s[0:1]
	v_cmp_ge_i32_e64 s[0:1], v50, v73
	v_cvt_pk_bf16_f32 v44, v44, v45
	v_mul_f32_e32 v51, v68, v51
	v_mul_f32_e32 v51, 0x3fb8aa3b, v51
	v_exp_f32_e32 v51, v51
	s_nop 0
	v_mul_f32_e32 v46, v46, v51
	v_sub_u32_e32 v51, v50, v74
	v_cvt_f32_i32_e32 v51, v51
	v_cndmask_b32_e64 v46, 0, v46, s[0:1]
	v_cmp_ge_i32_e64 s[0:1], v50, v74
	v_mul_f32_e32 v51, v68, v51
	v_mul_f32_e32 v51, 0x3fb8aa3b, v51
	v_exp_f32_e32 v51, v51
	s_nop 0
	v_mul_f32_e32 v47, v47, v51
	v_cndmask_b32_e64 v47, 0, v47, s[0:1]
	v_cvt_pk_bf16_f32 v45, v46, v47
	v_lshlrev_b32_e32 v46, 7, v50
	v_and_b32_e32 v46, 0xfffff87f, v46
	v_ashrrev_i32_e32 v47, 31, v46
	v_lshlrev_b64 v[46:47], 1, v[46:47]
	v_or_b32_e32 v46, v46, v76
	v_lshl_add_u64 v[46:47], s[20:21], 0, v[46:47]
	v_add_co_u32_e64 v46, s[0:1], s34, v46
	s_nop 1
	v_addc_co_u32_e64 v47, s[0:1], 0, v47, s[0:1]
	global_store_dwordx2 v[46:47], v[44:45], off
	v_sub_u32_e32 v44, v50, v61
	v_cvt_f32_i32_e32 v44, v44
	v_cmp_ge_i32_e64 s[0:1], v50, v61
	v_mul_f32_e32 v44, v68, v44
	v_mul_f32_e32 v44, 0x3fb8aa3b, v44
	v_exp_f32_e32 v44, v44
	s_nop 0
	v_mul_f32_e32 v41, v41, v44
	v_sub_u32_e32 v44, v50, v60
	v_cvt_f32_i32_e32 v44, v44
	v_cndmask_b32_e64 v41, 0, v41, s[0:1]
	v_cmp_ge_i32_e64 s[0:1], v50, v60
	v_cvt_pk_bf16_f32 v40, v40, v41
	v_mul_f32_e32 v44, v68, v44
	v_mul_f32_e32 v44, 0x3fb8aa3b, v44
	v_exp_f32_e32 v44, v44
	s_nop 0
	v_mul_f32_e32 v42, v42, v44
	v_sub_u32_e32 v44, v50, v58
	v_cvt_f32_i32_e32 v44, v44
	v_cndmask_b32_e64 v42, 0, v42, s[0:1]
	v_cmp_ge_i32_e64 s[0:1], v50, v58
	v_mul_f32_e32 v44, v68, v44
	v_mul_f32_e32 v44, 0x3fb8aa3b, v44
	v_exp_f32_e32 v44, v44
	s_nop 0
	v_mul_f32_e32 v43, v43, v44
	v_cndmask_b32_e64 v43, 0, v43, s[0:1]
	v_cvt_pk_bf16_f32 v41, v42, v43
	global_store_dwordx2 v[46:47], v[40:41], off offset:512
	v_sub_u32_e32 v40, v50, v57
	v_cvt_f32_i32_e32 v40, v40
	v_cmp_ge_i32_e64 s[0:1], v50, v57
	v_mul_f32_e32 v40, v68, v40
	v_mul_f32_e32 v40, 0x3fb8aa3b, v40
	v_exp_f32_e32 v40, v40
	s_nop 0
	v_mul_f32_e32 v36, v36, v40
	v_sub_u32_e32 v40, v50, v56
	v_cvt_f32_i32_e32 v40, v40
	v_cndmask_b32_e64 v36, 0, v36, s[0:1]
	v_cmp_ge_i32_e64 s[0:1], v50, v56
	v_mul_f32_e32 v40, v68, v40
	v_mul_f32_e32 v40, 0x3fb8aa3b, v40
	v_exp_f32_e32 v40, v40
	s_nop 0
	v_mul_f32_e32 v37, v37, v40
	v_sub_u32_e32 v40, v50, v53
	v_cvt_f32_i32_e32 v40, v40
	v_cndmask_b32_e64 v37, 0, v37, s[0:1]
	v_cmp_ge_i32_e64 s[0:1], v50, v53
	v_cvt_pk_bf16_f32 v36, v36, v37
	v_mul_f32_e32 v40, v68, v40
	v_mul_f32_e32 v40, 0x3fb8aa3b, v40
	v_exp_f32_e32 v40, v40
	s_nop 0
	v_mul_f32_e32 v38, v38, v40
	v_sub_u32_e32 v40, v50, v52
	v_cvt_f32_i32_e32 v40, v40
	v_cndmask_b32_e64 v38, 0, v38, s[0:1]
	v_cmp_ge_i32_e64 s[0:1], v50, v52
	v_mul_f32_e32 v40, v68, v40
	v_mul_f32_e32 v40, 0x3fb8aa3b, v40
	v_exp_f32_e32 v40, v40
	s_nop 0
	v_mul_f32_e32 v39, v39, v40
	v_cndmask_b32_e64 v39, 0, v39, s[0:1]
	v_cvt_pk_bf16_f32 v37, v38, v39
	global_store_dwordx2 v[46:47], v[36:37], off offset:1024
	v_sub_u32_e32 v36, v50, v55
	v_cvt_f32_i32_e32 v36, v36
	v_cmp_ge_i32_e64 s[0:1], v50, v55
	v_mul_f32_e32 v36, v68, v36
	v_mul_f32_e32 v36, 0x3fb8aa3b, v36
	v_exp_f32_e32 v36, v36
	s_nop 0
	v_mul_f32_e32 v32, v32, v36
	v_sub_u32_e32 v36, v50, v54
	v_cvt_f32_i32_e32 v36, v36
	v_cndmask_b32_e64 v32, 0, v32, s[0:1]
	v_cmp_ge_i32_e64 s[0:1], v50, v54
	v_mul_f32_e32 v36, v68, v36
	v_mul_f32_e32 v36, 0x3fb8aa3b, v36
	v_exp_f32_e32 v36, v36
	s_nop 0
	v_mul_f32_e32 v33, v33, v36
	v_sub_u32_e32 v36, v50, v49
	v_cvt_f32_i32_e32 v36, v36
	v_cndmask_b32_e64 v33, 0, v33, s[0:1]
	v_cmp_ge_i32_e64 s[0:1], v50, v49
	v_cvt_pk_bf16_f32 v32, v32, v33
	v_mul_f32_e32 v36, v68, v36
	v_mul_f32_e32 v36, 0x3fb8aa3b, v36
	v_exp_f32_e32 v36, v36
	s_nop 0
	v_mul_f32_e32 v34, v34, v36
	v_sub_u32_e32 v36, v50, v48
	v_cvt_f32_i32_e32 v36, v36
	v_cndmask_b32_e64 v34, 0, v34, s[0:1]
	v_cmp_ge_i32_e64 s[0:1], v50, v48
	v_mul_f32_e32 v36, v68, v36
	v_mul_f32_e32 v36, 0x3fb8aa3b, v36
	v_exp_f32_e32 v36, v36
	s_nop 0
	v_mul_f32_e32 v35, v35, v36
	v_cndmask_b32_e64 v35, 0, v35, s[0:1]
	v_cvt_pk_bf16_f32 v33, v34, v35
	global_store_dwordx2 v[46:47], v[32:33], off offset:1536
	v_or_b32_e32 v32, 32, v72
	v_sub_u32_e32 v33, v32, v71
	v_cvt_f32_i32_e32 v33, v33
	v_cmp_ge_i32_e64 s[0:1], v32, v71
	v_mul_f32_e32 v33, v68, v33
	v_mul_f32_e32 v33, 0x3fb8aa3b, v33
	v_exp_f32_e32 v33, v33
	s_nop 0
	v_mul_f32_e32 v28, v28, v33
	v_sub_u32_e32 v33, v32, v75
	v_cvt_f32_i32_e32 v33, v33
	v_cndmask_b32_e64 v28, 0, v28, s[0:1]
	v_cmp_gt_i32_e64 s[0:1], v32, v71
	v_mul_f32_e32 v33, v68, v33
	v_mul_f32_e32 v33, 0x3fb8aa3b, v33
	v_exp_f32_e32 v33, v33
	s_nop 0
	v_mul_f32_e32 v29, v29, v33
	v_sub_u32_e32 v33, v32, v73
	v_cvt_f32_i32_e32 v33, v33
	v_cndmask_b32_e64 v29, 0, v29, s[0:1]
	v_cmp_ge_i32_e64 s[0:1], v32, v73
	v_cvt_pk_bf16_f32 v28, v28, v29
	v_mul_f32_e32 v33, v68, v33
	v_mul_f32_e32 v33, 0x3fb8aa3b, v33
	v_exp_f32_e32 v33, v33
	s_nop 0
	v_mul_f32_e32 v30, v30, v33
	v_sub_u32_e32 v33, v32, v74
	v_cvt_f32_i32_e32 v33, v33
	v_cndmask_b32_e64 v30, 0, v30, s[0:1]
	v_cmp_ge_i32_e64 s[0:1], v32, v74
	v_mul_f32_e32 v33, v68, v33
	v_mul_f32_e32 v33, 0x3fb8aa3b, v33
	v_exp_f32_e32 v33, v33
	s_nop 0
	v_mul_f32_e32 v31, v31, v33
	v_cndmask_b32_e64 v31, 0, v31, s[0:1]
	v_cvt_pk_bf16_f32 v29, v30, v31
	v_lshlrev_b32_e32 v30, 7, v32
	v_and_b32_e32 v30, 0xfffff87f, v30
	v_ashrrev_i32_e32 v31, 31, v30
	v_lshlrev_b64 v[30:31], 1, v[30:31]
	v_or_b32_e32 v30, v30, v76
	v_lshl_add_u64 v[30:31], s[20:21], 0, v[30:31]
	v_add_co_u32_e64 v30, s[0:1], s34, v30
	s_nop 1
	v_addc_co_u32_e64 v31, s[0:1], 0, v31, s[0:1]
	global_store_dwordx2 v[30:31], v[28:29], off
	v_sub_u32_e32 v28, v32, v70
	v_cvt_f32_i32_e32 v28, v28
	v_cmp_ge_i32_e64 s[0:1], v32, v70
	v_mul_f32_e32 v28, v68, v28
	v_mul_f32_e32 v28, 0x3fb8aa3b, v28
	v_exp_f32_e32 v28, v28
	s_nop 0
	v_mul_f32_e32 v24, v24, v28
	v_sub_u32_e32 v28, v32, v61
	v_cvt_f32_i32_e32 v28, v28
	v_cndmask_b32_e64 v24, 0, v24, s[0:1]
	v_cmp_ge_i32_e64 s[0:1], v32, v61
	v_mul_f32_e32 v28, v68, v28
	v_mul_f32_e32 v28, 0x3fb8aa3b, v28
	v_exp_f32_e32 v28, v28
	s_nop 0
	v_mul_f32_e32 v25, v25, v28
	v_sub_u32_e32 v28, v32, v60
	v_cvt_f32_i32_e32 v28, v28
	v_cndmask_b32_e64 v25, 0, v25, s[0:1]
	v_cmp_ge_i32_e64 s[0:1], v32, v60
	v_cvt_pk_bf16_f32 v24, v24, v25
	v_mul_f32_e32 v28, v68, v28
	v_mul_f32_e32 v28, 0x3fb8aa3b, v28
	v_exp_f32_e32 v28, v28
	s_nop 0
	v_mul_f32_e32 v26, v26, v28
	v_sub_u32_e32 v28, v32, v58
	v_cvt_f32_i32_e32 v28, v28
	v_cndmask_b32_e64 v26, 0, v26, s[0:1]
	v_cmp_ge_i32_e64 s[0:1], v32, v58
	v_mul_f32_e32 v28, v68, v28
	v_mul_f32_e32 v28, 0x3fb8aa3b, v28
	v_exp_f32_e32 v28, v28
	s_nop 0
	v_mul_f32_e32 v27, v27, v28
	v_cndmask_b32_e64 v27, 0, v27, s[0:1]
	v_cvt_pk_bf16_f32 v25, v26, v27
	global_store_dwordx2 v[30:31], v[24:25], off offset:512
	v_sub_u32_e32 v24, v32, v56
	v_cvt_f32_i32_e32 v24, v24
	v_cmp_ge_i32_e64 s[0:1], v32, v56
	v_mul_f32_e32 v24, v68, v24
	v_mul_f32_e32 v24, 0x3fb8aa3b, v24
	v_exp_f32_e32 v24, v24
	s_nop 0
	v_mul_f32_e32 v21, v21, v24
	v_sub_u32_e32 v24, v32, v53
	v_cvt_f32_i32_e32 v24, v24
	v_cndmask_b32_e64 v21, 0, v21, s[0:1]
	v_cmp_ge_i32_e64 s[0:1], v32, v53
	v_cvt_pk_bf16_f32 v20, v20, v21
	v_mul_f32_e32 v24, v68, v24
	v_mul_f32_e32 v24, 0x3fb8aa3b, v24
	v_exp_f32_e32 v24, v24
	s_nop 0
	v_mul_f32_e32 v22, v22, v24
	v_sub_u32_e32 v24, v32, v52
	v_cvt_f32_i32_e32 v24, v24
	v_cndmask_b32_e64 v22, 0, v22, s[0:1]
	v_cmp_ge_i32_e64 s[0:1], v32, v52
	v_mul_f32_e32 v24, v68, v24
	v_mul_f32_e32 v24, 0x3fb8aa3b, v24
	v_exp_f32_e32 v24, v24
	s_nop 0
	v_mul_f32_e32 v23, v23, v24
	v_cndmask_b32_e64 v23, 0, v23, s[0:1]
	v_cvt_pk_bf16_f32 v21, v22, v23
	global_store_dwordx2 v[30:31], v[20:21], off offset:1024
	v_sub_u32_e32 v20, v32, v55
	v_cvt_f32_i32_e32 v20, v20
	v_cmp_ge_i32_e64 s[0:1], v32, v55
	v_mul_f32_e32 v20, v68, v20
	v_mul_f32_e32 v20, 0x3fb8aa3b, v20
	v_exp_f32_e32 v20, v20
	s_nop 0
	v_mul_f32_e32 v16, v16, v20
	v_sub_u32_e32 v20, v32, v54
	v_cvt_f32_i32_e32 v20, v20
	v_cndmask_b32_e64 v16, 0, v16, s[0:1]
	v_cmp_ge_i32_e64 s[0:1], v32, v54
	v_mul_f32_e32 v20, v68, v20
	v_mul_f32_e32 v20, 0x3fb8aa3b, v20
	v_exp_f32_e32 v20, v20
	s_nop 0
	v_mul_f32_e32 v17, v17, v20
	v_sub_u32_e32 v20, v32, v49
	v_cvt_f32_i32_e32 v20, v20
	v_cndmask_b32_e64 v17, 0, v17, s[0:1]
	v_cmp_ge_i32_e64 s[0:1], v32, v49
	v_cvt_pk_bf16_f32 v16, v16, v17
	v_mul_f32_e32 v20, v68, v20
	v_mul_f32_e32 v20, 0x3fb8aa3b, v20
	v_exp_f32_e32 v20, v20
	s_nop 0
	v_mul_f32_e32 v18, v18, v20
	v_sub_u32_e32 v20, v32, v48
	v_cvt_f32_i32_e32 v20, v20
	v_cndmask_b32_e64 v18, 0, v18, s[0:1]
	v_cmp_ge_i32_e64 s[0:1], v32, v48
	v_mul_f32_e32 v20, v68, v20
	v_mul_f32_e32 v20, 0x3fb8aa3b, v20
	v_exp_f32_e32 v20, v20
	s_nop 0
	v_mul_f32_e32 v19, v19, v20
	v_cndmask_b32_e64 v19, 0, v19, s[0:1]
	v_cvt_pk_bf16_f32 v17, v18, v19
	global_store_dwordx2 v[30:31], v[16:17], off offset:1536
	v_or_b32_e32 v16, 48, v72
	v_sub_u32_e32 v17, v16, v71
	v_cvt_f32_i32_e32 v17, v17
	v_cmp_ge_i32_e64 s[0:1], v16, v71
	v_cmp_ge_i32_e32 vcc, v16, v54
	v_mul_f32_e32 v17, v68, v17
	v_mul_f32_e32 v17, 0x3fb8aa3b, v17
	v_exp_f32_e32 v17, v17
	s_nop 0
	v_mul_f32_e32 v12, v12, v17
	v_sub_u32_e32 v17, v16, v75
	v_cvt_f32_i32_e32 v17, v17
	v_cndmask_b32_e64 v12, 0, v12, s[0:1]
	v_cmp_gt_i32_e64 s[0:1], v16, v71
	v_mul_f32_e32 v17, v68, v17
	v_mul_f32_e32 v17, 0x3fb8aa3b, v17
	v_exp_f32_e32 v17, v17
	s_nop 0
	v_mul_f32_e32 v13, v13, v17
	v_sub_u32_e32 v17, v16, v73
	v_cvt_f32_i32_e32 v17, v17
	v_cndmask_b32_e64 v13, 0, v13, s[0:1]
	v_cmp_ge_i32_e64 s[0:1], v16, v73
	v_mul_f32_e32 v17, v68, v17
	v_mul_f32_e32 v17, 0x3fb8aa3b, v17
	v_exp_f32_e32 v17, v17
	s_nop 0
	v_mul_f32_e32 v14, v14, v17
	v_cndmask_b32_e64 v17, 0, v14, s[0:1]
	v_sub_u32_e32 v14, v16, v74
	v_cvt_f32_i32_e32 v14, v14
	v_cmp_ge_i32_e64 s[0:1], v16, v74
	v_mul_f32_e32 v14, v68, v14
	v_mul_f32_e32 v14, 0x3fb8aa3b, v14
	v_exp_f32_e32 v14, v14
	s_nop 0
	v_mul_f32_e32 v14, v15, v14
	v_cndmask_b32_e64 v15, 0, v14, s[0:1]
	v_cvt_pk_bf16_f32 v14, v12, v13
	v_lshlrev_b32_e32 v12, 7, v16
	v_and_b32_e32 v12, 0xfffff87f, v12
	v_ashrrev_i32_e32 v13, 31, v12
	v_lshlrev_b64 v[12:13], 1, v[12:13]
	v_or_b32_e32 v12, v12, v76
	v_lshl_add_u64 v[12:13], s[20:21], 0, v[12:13]
	v_add_co_u32_e64 v12, s[0:1], s34, v12
	v_cvt_pk_bf16_f32 v15, v17, v15
	s_nop 1
	v_addc_co_u32_e64 v13, s[0:1], 0, v13, s[0:1]
	global_store_dwordx2 v[12:13], v[14:15], off
	v_sub_u32_e32 v14, v16, v70
	v_cvt_f32_i32_e32 v14, v14
	v_cmp_ge_i32_e64 s[0:1], v16, v70
	v_mul_f32_e32 v14, v68, v14
	v_mul_f32_e32 v14, 0x3fb8aa3b, v14
	v_exp_f32_e32 v14, v14
	s_nop 0
	v_mul_f32_e32 v8, v8, v14
	v_sub_u32_e32 v14, v16, v61
	v_cvt_f32_i32_e32 v14, v14
	v_cndmask_b32_e64 v8, 0, v8, s[0:1]
	v_cmp_ge_i32_e64 s[0:1], v16, v61
	v_mul_f32_e32 v14, v68, v14
	v_mul_f32_e32 v14, 0x3fb8aa3b, v14
	v_exp_f32_e32 v14, v14
	s_nop 0
	v_mul_f32_e32 v9, v9, v14
	v_sub_u32_e32 v14, v16, v60
	v_cvt_f32_i32_e32 v14, v14
	v_cndmask_b32_e64 v9, 0, v9, s[0:1]
	v_cmp_ge_i32_e64 s[0:1], v16, v60
	v_cvt_pk_bf16_f32 v8, v8, v9
	v_mul_f32_e32 v14, v68, v14
	v_mul_f32_e32 v14, 0x3fb8aa3b, v14
	v_exp_f32_e32 v14, v14
	s_nop 0
	v_mul_f32_e32 v10, v10, v14
	v_sub_u32_e32 v14, v16, v58
	v_cvt_f32_i32_e32 v14, v14
	v_cndmask_b32_e64 v10, 0, v10, s[0:1]
	v_cmp_ge_i32_e64 s[0:1], v16, v58
	v_mul_f32_e32 v14, v68, v14
	v_mul_f32_e32 v14, 0x3fb8aa3b, v14
	v_exp_f32_e32 v14, v14
	s_nop 0
	v_mul_f32_e32 v11, v11, v14
	v_cndmask_b32_e64 v11, 0, v11, s[0:1]
	v_cvt_pk_bf16_f32 v9, v10, v11
	global_store_dwordx2 v[12:13], v[8:9], off offset:512
	v_sub_u32_e32 v8, v16, v57
	v_cvt_f32_i32_e32 v8, v8
	v_cmp_ge_i32_e64 s[0:1], v16, v57
	v_mul_f32_e32 v8, v68, v8
	v_mul_f32_e32 v8, 0x3fb8aa3b, v8
	v_exp_f32_e32 v8, v8
	s_nop 0
	v_mul_f32_e32 v4, v4, v8
	v_sub_u32_e32 v8, v16, v56
	v_cvt_f32_i32_e32 v8, v8
	v_cndmask_b32_e64 v4, 0, v4, s[0:1]
	v_cmp_ge_i32_e64 s[0:1], v16, v56
	v_mul_f32_e32 v8, v68, v8
	v_mul_f32_e32 v8, 0x3fb8aa3b, v8
	v_exp_f32_e32 v8, v8
	s_nop 0
	v_mul_f32_e32 v5, v5, v8
	v_sub_u32_e32 v8, v16, v53
	v_cvt_f32_i32_e32 v8, v8
	v_cndmask_b32_e64 v5, 0, v5, s[0:1]
	v_cmp_ge_i32_e64 s[0:1], v16, v53
	v_cvt_pk_bf16_f32 v4, v4, v5
	v_mul_f32_e32 v8, v68, v8
	v_mul_f32_e32 v8, 0x3fb8aa3b, v8
	v_exp_f32_e32 v8, v8
	s_nop 0
	v_mul_f32_e32 v6, v6, v8
	v_sub_u32_e32 v8, v16, v52
	v_cvt_f32_i32_e32 v8, v8
	v_cndmask_b32_e64 v6, 0, v6, s[0:1]
	v_cmp_ge_i32_e64 s[0:1], v16, v52
	v_mul_f32_e32 v8, v68, v8
	v_mul_f32_e32 v8, 0x3fb8aa3b, v8
	v_exp_f32_e32 v8, v8
	s_nop 0
	v_mul_f32_e32 v7, v7, v8
	v_cndmask_b32_e64 v7, 0, v7, s[0:1]
	v_cvt_pk_bf16_f32 v5, v6, v7
	global_store_dwordx2 v[12:13], v[4:5], off offset:1024
	v_sub_u32_e32 v4, v16, v54
	v_cvt_f32_i32_e32 v4, v4
	v_mul_f32_e32 v4, v68, v4
	v_mul_f32_e32 v4, 0x3fb8aa3b, v4
	v_exp_f32_e32 v4, v4
	s_nop 0
	v_mul_f32_e32 v1, v1, v4
	v_sub_u32_e32 v4, v16, v49
	v_cvt_f32_i32_e32 v4, v4
	v_cndmask_b32_e32 v1, 0, v1, vcc
	v_cmp_ge_i32_e32 vcc, v16, v49
	v_cvt_pk_bf16_f32 v0, v0, v1
	v_mul_f32_e32 v4, v68, v4
	v_mul_f32_e32 v4, 0x3fb8aa3b, v4
	v_exp_f32_e32 v4, v4
	s_nop 0
	v_mul_f32_e32 v2, v2, v4
	v_sub_u32_e32 v4, v16, v48
	v_cvt_f32_i32_e32 v4, v4
	v_cndmask_b32_e32 v2, 0, v2, vcc
	v_cmp_ge_i32_e32 vcc, v16, v48
	v_mul_f32_e32 v4, v68, v4
	v_mul_f32_e32 v4, 0x3fb8aa3b, v4
	v_exp_f32_e32 v4, v4
	s_nop 0
	v_mul_f32_e32 v3, v3, v4
	v_cndmask_b32_e32 v3, 0, v3, vcc
	v_cvt_pk_bf16_f32 v1, v2, v3
	global_store_dwordx2 v[12:13], v[0:1], off offset:1536
	s_cbranch_scc1 .LBB0_330

.LBB0_388:
	s_or_b64 exec, exec, s[4:5]
	s_and_b32 s43, s42, 3
	v_cvt_f32_ubyte0_e32 v0, s43
	v_sub_f32_e32 v0, 0xc0a00000, v0
	v_cmp_gt_f32_e32 vcc, s29, v0
	s_and_b32 s4, s40, 3
	s_lshl_b32 s9, s4, 10
	v_cndmask_b32_e32 v2, 0, v222, vcc
	s_and_b32 s4, s25, -16
	v_add_f32_e32 v0, v0, v2
	s_and_b32 s0, s41, 4
	s_ashr_i32 s5, s4, 31
	v_exp_f32_e32 v2, v0
	s_lshl_b32 s0, s0, 24
	s_lshl_b64 s[4:5], s[4:5], 1
	s_and_b32 s33, s42, 7
	s_lshl_b32 s46, s42, 1
	s_and_b64 s[44:45], vcc, exec
	s_cselect_b32 s43, 0xffffffc0, 0
	s_waitcnt vmcnt(48)
	v_ldexp_f32 v4, v2, s43
	v_sub_f32_e32 v5, 1.0, v4
	v_add_f32_e32 v2, -1.0, v5
	v_sub_f32_e32 v3, v2, v5
	v_add_f32_e32 v3, 1.0, v3
	v_sub_f32_e64 v2, -v4, v2
	v_add_f32_e32 v6, v2, v3
	v_frexp_mant_f32_e32 v7, v5
	v_cvt_f64_f32_e32 v[2:3], v5
	v_frexp_exp_i32_f64_e32 v2, v[2:3]
	v_cmp_gt_f32_e32 vcc, s30, v7
	s_lshl_b32 s43, s33, 23
	s_lshl_b32 s44, s33, 24
	v_subbrev_co_u32_e32 v2, vcc, 0, v2, vcc
	v_sub_u32_e32 v3, 0, v2
	v_ldexp_f32 v5, v5, v3
	v_ldexp_f32 v3, v6, v3
	v_add_f32_e32 v6, -1.0, v5
	v_add_f32_e32 v9, 1.0, v5
	v_add_f32_e32 v7, 1.0, v6
	v_add_f32_e32 v10, -1.0, v9
	v_sub_f32_e32 v7, v5, v7
	v_sub_f32_e32 v5, v5, v10
	v_add_f32_e32 v7, v3, v7
	v_add_f32_e32 v3, v3, v5
	v_add_f32_e32 v5, v9, v3
	v_rcp_f32_e32 v10, v5
	v_add_f32_e32 v8, v6, v7
	v_sub_f32_e32 v6, v8, v6
	v_sub_f32_e32 v6, v7, v6
	v_sub_f32_e32 v7, v5, v9
	v_sub_f32_e32 v3, v3, v7
	v_mul_f32_e32 v7, v8, v10
	v_mul_f32_e32 v9, v5, v7
	v_fma_f32 v11, v7, v5, -v9
	v_fmac_f32_e32 v11, v7, v3
	v_add_f32_e32 v12, v9, v11
	v_sub_f32_e32 v13, v8, v12
	v_sub_f32_e32 v8, v8, v13
	v_sub_f32_e32 v9, v12, v9
	v_sub_f32_e32 v8, v8, v12
	v_add_f32_e32 v6, v6, v8
	v_sub_f32_e32 v8, v9, v11
	v_add_f32_e32 v6, v8, v6
	v_add_f32_e32 v8, v13, v6
	v_mul_f32_e32 v9, v10, v8
	v_mul_f32_e32 v11, v5, v9
	v_fma_f32 v5, v9, v5, -v11
	v_fmac_f32_e32 v5, v9, v3
	v_sub_f32_e32 v3, v13, v8
	v_add_f32_e32 v3, v6, v3
	v_add_f32_e32 v6, v11, v5
	v_sub_f32_e32 v12, v8, v6
	v_sub_f32_e32 v8, v8, v12
	v_sub_f32_e32 v11, v6, v11
	v_sub_f32_e32 v6, v8, v6
	v_add_f32_e32 v3, v3, v6
	v_sub_f32_e32 v5, v11, v5
	v_cvt_f32_i32_e32 v2, v2
	v_add_f32_e32 v3, v5, v3
	v_add_f32_e32 v5, v7, v9
	v_add_f32_e32 v3, v12, v3
	v_sub_f32_e32 v6, v5, v7
	v_mul_f32_e32 v3, v10, v3
	v_sub_f32_e32 v6, v9, v6
	v_add_f32_e32 v3, v6, v3
	v_mul_f32_e32 v9, 0x3f317218, v2
	v_add_f32_e32 v6, v5, v3
	v_fma_f32 v10, v2, s31, -v9
	v_mul_f32_e32 v7, v6, v6
	v_fmac_f32_e32 v10, 0xb102e308, v2
	v_sub_f32_e32 v2, v6, v5
	v_fmamk_f32 v8, v7, 0x3e9b6dac, v223
	v_sub_f32_e32 v2, v3, v2
	v_add_f32_e32 v3, v9, v10
	v_fmaak_f32 v8, v7, v8, 0x3f2aaada
	v_sub_f32_e32 v5, v3, v9
	v_ldexp_f32 v9, v6, 1
	v_mul_f32_e32 v6, v6, v7
	v_mul_f32_e32 v6, v6, v8
	v_add_f32_e32 v7, v9, v6
	v_sub_f32_e32 v8, v7, v9
	v_ldexp_f32 v2, v2, 1
	v_sub_f32_e32 v6, v6, v8
	v_add_f32_e32 v2, v2, v6
	v_add_f32_e32 v6, v7, v2
	v_sub_f32_e32 v7, v6, v7
	v_sub_f32_e32 v2, v2, v7
	v_add_f32_e32 v7, v3, v6
	v_sub_f32_e32 v8, v7, v3
	v_sub_f32_e32 v9, v7, v8
	v_sub_f32_e32 v5, v10, v5
	v_sub_f32_e32 v3, v3, v9
	v_sub_f32_e32 v6, v6, v8
	v_add_f32_e32 v3, v6, v3
	v_add_f32_e32 v6, v5, v2
	v_sub_f32_e32 v8, v6, v5
	v_sub_f32_e32 v9, v6, v8
	v_sub_f32_e32 v5, v5, v9
	v_sub_f32_e32 v2, v2, v8
	v_add_f32_e32 v3, v6, v3
	v_add_f32_e32 v2, v2, v5
	v_add_f32_e32 v5, v7, v3
	v_sub_f32_e32 v6, v5, v7
	v_sub_f32_e32 v3, v3, v6
	v_add_f32_e32 v2, v2, v3
	v_add_f32_e32 v2, v5, v2
	v_cmp_nlt_f32_e32 vcc, 1.0, v4
	s_add_u32 s44, s15, s44
	s_addc_u32 s45, s16, 0
	v_cndmask_b32_e32 v2, v224, v2, vcc
	v_cmp_neq_f32_e32 vcc, 1.0, v4
	s_lshl_b32 s33, s33, 22
	v_and_b32_e32 v181, 15, v1
	v_cndmask_b32_e32 v2, v225, v2, vcc
	v_cmp_gt_f32_e32 vcc, s34, v4
	v_bfe_u32 v182, v1, 4, 2
	v_lshlrev_b32_e32 v192, 4, v182
	v_lshlrev_b32_e32 v255, 8, v182
	v_lshl_or_b32 v255, v181, 4, v255
	v_cndmask_b32_e64 v183, v2, -v4, vcc
	v_mul_f32_e32 v2, 0x43000000, v183
	v_mul_f32_e32 v2, 0x3fb8aa3b, v2
	v_exp_f32_e32 v194, v2
	s_and_b32 s100, s46, -16
	s_lshl_b32 s100, s100, 8
	v_add_u32_e32 v2, s100, v255
	v_mov_b32_e32 v3, 0
	v_lshl_add_u64 v[2:3], s[44:45], 0, v[2:3]
	s_add_u32 s44, s17, s43
	s_addc_u32 s45, s22, 0
	s_add_u32 s46, s3, s43
	v_ashrrev_i32_e32 v4, 1, v1
	s_addc_u32 s47, s14, 0
	s_waitcnt vmcnt(44)
	v_and_b32_e32 v20, 0xffffffe0, v4
	s_add_u32 s48, s23, s33
	s_addc_u32 s49, s24, 0
	v_ashrrev_i32_e32 v199, 31, v20
	v_or_b32_e32 v198, v20, v181
	v_lshl_or_b32 v180, v182, 2, v20
	v_mov_b64_e32 v[196:197], v[2:3]
	v_mov_b32_e32 v2, v255
	v_mov_b32_e32 v3, 0
	v_lshl_add_u64 v[200:201], s[48:49], 0, v[2:3]
	v_and_b32_e32 v2, -16, v198
	v_mov_b32_e32 v3, 0
	v_lshlrev_b64 v[2:3], 8, v[2:3]
	v_or_b32_e32 v4, 1, v180
	v_lshl_add_u64 v[2:3], v[200:201], 0, v[2:3]
	s_waitcnt vmcnt(36)
	v_ashrrev_i32_e32 v25, 31, v198
	v_mov_b32_e32 v24, v198
	s_waitcnt lgkmcnt(0)
	s_barrier
	v_cvt_f32_i32_e32 v184, v4
	global_load_dwordx4 v[16:19], v[196:197], off
	global_load_dwordx4 v[12:15], v[196:197], off offset:1024
	global_load_dwordx4 v[8:11], v[196:197], off offset:2048
	global_load_dwordx4 v[4:7], v[196:197], off offset:3072
	v_lshl_add_u64 v[202:203], s[44:45], 0, v[192:193]
	global_load_dwordx4 v[136:139], v[2:3], off
	global_load_dwordx4 v[52:55], v[2:3], off offset:1024
	global_load_dwordx4 v[32:35], v[2:3], off offset:2048
	global_load_dwordx4 v[20:23], v[2:3], off offset:3072
	v_lshlrev_b64 v[24:25], 9, v[24:25]
	v_add_co_u32_e32 v2, vcc, s35, v2
	v_lshl_add_u64 v[24:25], v[202:203], 0, v[24:25]
	s_nop 0
	v_addc_co_u32_e32 v3, vcc, 0, v3, vcc
	global_load_dwordx4 v[60:63], v[24:25], off
	global_load_dwordx4 v[56:59], v[24:25], off offset:64
	global_load_dwordx4 v[48:51], v[24:25], off offset:128
	global_load_dwordx4 v[44:47], v[24:25], off offset:192
	global_load_dwordx4 v[40:43], v[24:25], off offset:256
	global_load_dwordx4 v[36:39], v[24:25], off offset:320
	global_load_dwordx4 v[28:31], v[24:25], off offset:384
	s_nop 0
	global_load_dwordx4 v[24:27], v[24:25], off offset:448
	s_nop 0
	global_load_dwordx4 v[164:167], v[2:3], off
	global_load_dwordx4 v[92:95], v[2:3], off offset:1024
	global_load_dwordx4 v[68:71], v[2:3], off offset:2048
	global_load_dwordx4 v[64:67], v[2:3], off offset:3072
	v_or_b32_e32 v2, 16, v198
	v_ashrrev_i32_e32 v3, 31, v2
	s_waitcnt vmcnt(28)
	v_lshlrev_b32_e32 v144, 7, v1
	v_lshlrev_b64 v[2:3], 9, v[2:3]
	v_and_b32_e32 v206, 0xffffe000, v144
	v_lshl_add_u64 v[2:3], v[202:203], 0, v[2:3]
	v_mov_b32_e32 v205, s47
	v_add_co_u32_e32 v204, vcc, s46, v255
	s_nop 1
	v_addc_co_u32_e32 v205, vcc, 0, v205, vcc
	v_ashrrev_i32_e32 v207, 31, v206
	v_or_b32_e32 v208, 0x800, v206
	global_load_dwordx4 v[104:107], v[2:3], off
	global_load_dwordx4 v[100:103], v[2:3], off offset:64
	global_load_dwordx4 v[96:99], v[2:3], off offset:128
	global_load_dwordx4 v[88:91], v[2:3], off offset:192
	global_load_dwordx4 v[84:87], v[2:3], off offset:256
	global_load_dwordx4 v[80:83], v[2:3], off offset:320
	global_load_dwordx4 v[76:79], v[2:3], off offset:384
	global_load_dwordx4 v[72:75], v[2:3], off offset:448
	v_lshl_add_u64 v[2:3], v[206:207], 1, v[204:205]
	v_ashrrev_i32_e32 v209, 31, v208
	v_or_b32_e32 v210, 0x1000, v206
	global_load_dwordx4 v[176:179], v[2:3], off
	global_load_dwordx4 v[120:123], v[2:3], off offset:1024
	global_load_dwordx4 v[112:115], v[2:3], off offset:2048
	global_load_dwordx4 v[108:111], v[2:3], off offset:3072
	v_lshl_add_u64 v[2:3], v[208:209], 1, v[204:205]
	v_ashrrev_i32_e32 v211, 31, v210
	v_or_b32_e32 v212, 0x1800, v206
	global_load_dwordx4 v[172:175], v[2:3], off
	global_load_dwordx4 v[132:135], v[2:3], off offset:1024
	global_load_dwordx4 v[124:127], v[2:3], off offset:2048
	global_load_dwordx4 v[116:119], v[2:3], off offset:3072
	v_lshl_add_u64 v[2:3], v[210:211], 1, v[204:205]
	v_ashrrev_i32_e32 v213, 31, v212
	global_load_dwordx4 v[168:171], v[2:3], off
	global_load_dwordx4 v[148:151], v[2:3], off offset:1024
	global_load_dwordx4 v[140:143], v[2:3], off offset:2048
	global_load_dwordx4 v[128:131], v[2:3], off offset:3072
	v_lshl_add_u64 v[2:3], v[212:213], 1, v[204:205]
	global_load_dwordx4 v[160:163], v[2:3], off
	global_load_dwordx4 v[156:159], v[2:3], off offset:1024
	global_load_dwordx4 v[152:155], v[2:3], off offset:2048
	global_load_dwordx4 v[144:147], v[2:3], off offset:3072
	v_or_b32_e32 v2, 2, v180
	v_cvt_f32_i32_e32 v2, v2
	v_mul_f32_e32 v3, v183, v184
	v_mul_f32_e32 v3, 0x3fb8aa3b, v3
	v_exp_f32_e32 v227, v3
	v_mul_f32_e32 v2, v183, v2
	v_mul_f32_e32 v2, 0x3fb8aa3b, v2
	v_exp_f32_e32 v228, v2
	v_add_u32_e32 v2, 4, v180
	v_or_b32_e32 v3, 3, v180
	v_cvt_f32_i32_e32 v2, v2
	v_cvt_f32_i32_e32 v3, v3
	s_add_u32 s4, s4, s9
	s_addc_u32 s5, s5, 0
	v_mul_f32_e32 v2, v183, v2
	v_mul_f32_e32 v3, v183, v3
	v_mul_f32_e32 v2, 0x3fb8aa3b, v2
	v_mul_f32_e32 v3, 0x3fb8aa3b, v3
	v_exp_f32_e32 v230, v2
	v_or_b32_e32 v2, 18, v180
	v_exp_f32_e32 v229, v3
	v_or_b32_e32 v3, 17, v180
	v_cvt_f32_i32_e32 v2, v2
	v_cvt_f32_i32_e32 v3, v3
	s_add_u32 s4, s4, s0
	v_and_b32_e32 v1, 0x7fffffc0, v1
	v_mul_f32_e32 v2, v183, v2
	v_mul_f32_e32 v3, v183, v3
	v_mul_f32_e32 v2, 0x3fb8aa3b, v2
	v_mul_f32_e32 v3, 0x3fb8aa3b, v3
	v_exp_f32_e32 v232, v2
	v_add_u32_e32 v2, 20, v180
	v_exp_f32_e32 v231, v3
	v_or_b32_e32 v3, 19, v180
	v_cvt_f32_i32_e32 v2, v2
	v_cvt_f32_i32_e32 v3, v3
	s_addc_u32 s5, s5, 0
	v_lshlrev_b32_e32 v1, 1, v1
	v_mul_f32_e32 v2, v183, v2
	v_mul_f32_e32 v3, v183, v3
	v_mul_f32_e32 v2, 0x3fb8aa3b, v2
	v_mul_f32_e32 v3, 0x3fb8aa3b, v3
	v_exp_f32_e32 v234, v2
	v_or_b32_e32 v2, 16, v180
	v_exp_f32_e32 v233, v3
	v_ashrrev_i32_e32 v3, 31, v2
	v_lshlrev_b64 v[2:3], 12, v[2:3]
	v_lshl_add_u64 v[2:3], s[4:5], 0, v[2:3]
	v_lshlrev_b32_e32 v184, 1, v181
	v_mul_u32_u24_e32 v183, 0x210, v181
	v_mad_u32_u24 v1, v181, s36, v1
	v_or_b32_e32 v2, v2, v184
	v_ashrrev_i32_e32 v181, 31, v180
	v_lshl_add_u64 v[216:217], s[70:71], 0, v[2:3]
	v_lshlrev_b64 v[2:3], 12, v[180:181]
	v_lshl_add_u64 v[2:3], s[4:5], 0, v[2:3]
	v_mov_b32_e32 v0, 0
	v_lshlrev_b32_e32 v182, 3, v182
	v_or_b32_e32 v2, v2, v184
	s_mov_b32 s8, 1
	v_mov_b32_e32 v214, v194
	v_mov_b32_e32 v215, v194
	v_lshl_add_u64 v[218:219], s[70:71], 0, v[2:3]
	s_mov_b64 s[4:5], 0
	v_add_u32_e32 v192, v183, v192
	v_add_u32_e32 v235, v1, v182
	v_mov_b32_e32 v1, v0
	v_mov_b32_e32 v2, v0
	v_mov_b32_e32 v3, v0
	v_mov_b32_e32 v188, v0
	v_mov_b32_e32 v189, v0
	v_mov_b32_e32 v190, v0
	v_mov_b32_e32 v191, v0
	v_mov_b32_e32 v184, v0
	v_mov_b32_e32 v185, v0
	v_mov_b32_e32 v186, v0
	v_mov_b32_e32 v187, v0
	v_mov_b32_e32 v180, v0
	v_mov_b32_e32 v181, v0
	v_mov_b32_e32 v182, v0
	v_mov_b32_e32 v183, v0
.LBB0_389:
	v_mov_b32_e32 v195, v194
	s_waitcnt vmcnt(39)
	v_mfma_f32_16x16x32_bf16 v[136:139], v[136:139], v[16:19], 0
	v_mul_f32_e64 v0, v214, v0
	v_mul_f32_e64 v1, v215, v1
	v_pk_mul_f32 v[2:3], v[194:195], v[2:3]
	s_waitcnt vmcnt(27)
	v_mfma_f32_16x16x32_bf16 v[164:167], v[164:167], v[16:19], 0
	s_waitcnt vmcnt(15)
	v_mfma_f32_16x16x32_bf16 v[0:3], v[176:179], v[16:19], v[0:3]
	v_mul_f32_e64 v176, v214, v188
	v_mul_f32_e64 v177, v215, v189
	v_pk_mul_f32 v[178:179], v[194:195], v[190:191]
	v_mfma_f32_16x16x32_bf16 v[52:55], v[52:55], v[12:15], v[136:139]
	s_waitcnt vmcnt(11)
	v_mfma_f32_16x16x32_bf16 v[172:175], v[172:175], v[16:19], v[176:179]
	s_nop 2
	v_mul_f32_e64 v176, v214, v184
	v_mul_f32_e64 v177, v215, v185
	v_pk_mul_f32 v[178:179], v[194:195], v[186:187]
	v_mfma_f32_16x16x32_bf16 v[92:95], v[92:95], v[12:15], v[164:167]
	s_waitcnt vmcnt(7)
	v_mfma_f32_16x16x32_bf16 v[168:171], v[168:171], v[16:19], v[176:179]
	s_nop 2
	v_mul_f32_e64 v176, v214, v180
	v_mul_f32_e64 v177, v215, v181
	v_pk_mul_f32 v[178:179], v[194:195], v[182:183]
	v_mfma_f32_16x16x32_bf16 v[0:3], v[120:123], v[12:15], v[0:3]
	s_waitcnt vmcnt(3)
	v_mfma_f32_16x16x32_bf16 v[16:19], v[160:163], v[16:19], v[176:179]
	ds_read_b128 v[136:139], v192
	ds_read_b128 v[160:163], v192 offset:64
	s_waitcnt lgkmcnt(1)
	v_mfma_f32_16x16x32_bf16 v[60:63], v[60:63], v[136:139], 0
	v_mfma_f32_16x16x32_bf16 v[104:107], v[104:107], v[136:139], 0
	v_mfma_f32_16x16x32_bf16 v[120:123], v[132:135], v[12:15], v[172:175]
	v_mfma_f32_16x16x32_bf16 v[132:135], v[148:151], v[12:15], v[168:171]
	s_waitcnt vmcnt(2)
	v_mfma_f32_16x16x32_bf16 v[12:15], v[156:159], v[12:15], v[16:19]
	v_mfma_f32_16x16x32_bf16 v[16:19], v[32:35], v[8:11], v[52:55]
	v_mfma_f32_16x16x32_bf16 v[32:35], v[68:71], v[8:11], v[92:95]
	s_waitcnt lgkmcnt(0)
	v_mfma_f32_16x16x32_bf16 v[52:55], v[56:59], v[160:163], v[60:63]
	v_mfma_f32_16x16x32_bf16 v[56:59], v[100:103], v[160:163], v[104:107]
	v_mfma_f32_16x16x32_bf16 v[0:3], v[112:115], v[8:11], v[0:3]
	v_mfma_f32_16x16x32_bf16 v[60:63], v[124:127], v[8:11], v[120:123]
	v_mfma_f32_16x16x32_bf16 v[68:71], v[140:143], v[8:11], v[132:135]
	s_waitcnt vmcnt(1)
	v_mfma_f32_16x16x32_bf16 v[8:11], v[152:155], v[8:11], v[12:15]
	v_mfma_f32_16x16x32_bf16 v[236:239], v[20:23], v[4:7], v[16:19]
	s_nop 1
	ds_read_b128 v[12:15], v192 offset:128
	ds_read_b128 v[16:19], v192 offset:192
	s_waitcnt lgkmcnt(1)
	v_mfma_f32_16x16x32_bf16 v[20:23], v[48:51], v[12:15], v[52:55]
	v_mfma_f32_16x16x32_bf16 v[12:15], v[96:99], v[12:15], v[56:59]
	v_mfma_f32_16x16x32_bf16 v[240:243], v[64:67], v[4:7], v[32:35]
	v_mfma_f32_16x16x32_bf16 v[0:3], v[108:111], v[4:7], v[0:3]
	v_mfma_f32_16x16x32_bf16 v[188:191], v[116:119], v[4:7], v[60:63]
	v_mfma_f32_16x16x32_bf16 v[184:187], v[128:131], v[4:7], v[68:71]
	s_waitcnt vmcnt(0)
	v_mfma_f32_16x16x32_bf16 v[180:183], v[144:147], v[4:7], v[8:11]
	s_waitcnt lgkmcnt(0)
	v_mfma_f32_16x16x32_bf16 v[4:7], v[44:47], v[16:19], v[20:23]
	v_mfma_f32_16x16x32_bf16 v[8:11], v[88:91], v[16:19], v[12:15]
	s_nop 2
	ds_read_b128 v[12:15], v192 offset:256
	ds_read_b128 v[16:19], v192 offset:320
	s_waitcnt lgkmcnt(1)
	v_mfma_f32_16x16x32_bf16 v[4:7], v[40:43], v[12:15], v[4:7]
	v_mfma_f32_16x16x32_bf16 v[8:11], v[84:87], v[12:15], v[8:11]
	s_waitcnt lgkmcnt(0)
	v_mfma_f32_16x16x32_bf16 v[4:7], v[36:39], v[16:19], v[4:7]
	v_mfma_f32_16x16x32_bf16 v[8:11], v[80:83], v[16:19], v[8:11]
	ds_read_b128 v[12:15], v192 offset:384
	ds_read_b128 v[16:19], v192 offset:448
	s_waitcnt lgkmcnt(1)
	v_mfma_f32_16x16x32_bf16 v[4:7], v[28:31], v[12:15], v[4:7]
	v_mfma_f32_16x16x32_bf16 v[8:11], v[76:79], v[12:15], v[8:11]
	s_waitcnt lgkmcnt(0)
	v_mfma_f32_16x16x32_bf16 v[244:247], v[24:27], v[16:19], v[4:7]
	v_mfma_f32_16x16x32_bf16 v[248:251], v[72:75], v[16:19], v[8:11]
	s_min_i32 s9, s8, 0x7f
	s_lshl_b32 s0, s9, 17
	s_nop 1
	v_lshl_add_u64 v[4:5], v[196:197], 0, s[0:1]
	s_lshl_b32 s0, s9, 7
	v_add_u32_e32 v72, s0, v198
	v_and_b32_e32 v20, -16, v198
	v_mov_b32_e32 v21, 0
	v_lshl_add_u64 v[20:21], v[20:21], 0, s[0:1]
	v_ashrrev_i32_e32 v73, 31, v72
	v_lshlrev_b64 v[20:21], 8, v[20:21]
	v_lshlrev_b64 v[24:25], 9, v[72:73]
	v_or_b32_e32 v72, 16, v72
	v_lshl_add_u64 v[64:65], v[200:201], 0, v[20:21]
	v_ashrrev_i32_e32 v73, 31, v72
	global_load_dwordx4 v[16:19], v[4:5], off
	global_load_dwordx4 v[12:15], v[4:5], off offset:1024
	global_load_dwordx4 v[8:11], v[4:5], off offset:2048
	s_nop 0
	global_load_dwordx4 v[4:7], v[4:5], off offset:3072
	s_nop 0
	global_load_dwordx4 v[136:139], v[64:65], off
	global_load_dwordx4 v[52:55], v[64:65], off offset:1024
	global_load_dwordx4 v[32:35], v[64:65], off offset:2048
	global_load_dwordx4 v[20:23], v[64:65], off offset:3072
	v_add_co_u32_e32 v64, vcc, s35, v64
	v_lshlrev_b64 v[72:73], 9, v[72:73]
	v_lshl_add_u64 v[24:25], v[202:203], 0, v[24:25]
	v_addc_co_u32_e32 v65, vcc, 0, v65, vcc
	v_lshl_add_u64 v[72:73], v[202:203], 0, v[72:73]
	global_load_dwordx4 v[60:63], v[24:25], off
	global_load_dwordx4 v[56:59], v[24:25], off offset:64
	global_load_dwordx4 v[48:51], v[24:25], off offset:128
	global_load_dwordx4 v[44:47], v[24:25], off offset:192
	global_load_dwordx4 v[40:43], v[24:25], off offset:256
	global_load_dwordx4 v[36:39], v[24:25], off offset:320
	global_load_dwordx4 v[28:31], v[24:25], off offset:384
	s_nop 0
	global_load_dwordx4 v[24:27], v[24:25], off offset:448
	s_nop 0
	global_load_dwordx4 v[164:167], v[64:65], off
	global_load_dwordx4 v[92:95], v[64:65], off offset:1024
	global_load_dwordx4 v[68:71], v[64:65], off offset:2048
	s_nop 0
	global_load_dwordx4 v[64:67], v[64:65], off offset:3072
	s_nop 0
	global_load_dwordx4 v[104:107], v[72:73], off
	global_load_dwordx4 v[100:103], v[72:73], off offset:64
	global_load_dwordx4 v[96:99], v[72:73], off offset:128
	global_load_dwordx4 v[88:91], v[72:73], off offset:192
	global_load_dwordx4 v[84:87], v[72:73], off offset:256
	global_load_dwordx4 v[80:83], v[72:73], off offset:320
	global_load_dwordx4 v[76:79], v[72:73], off offset:384
	s_nop 0
	global_load_dwordx4 v[72:75], v[72:73], off offset:448
	s_lshl_b32 s0, s9, 16
	v_lshl_add_u64 v[144:145], v[204:205], 0, s[0:1]
	v_lshl_add_u64 v[108:109], v[206:207], 1, v[144:145]
	v_lshl_add_u64 v[116:117], v[208:209], 1, v[144:145]
	v_lshl_add_u64 v[128:129], v[210:211], 1, v[144:145]
	v_lshl_add_u64 v[144:145], v[212:213], 1, v[144:145]
	global_load_dwordx4 v[176:179], v[108:109], off
	global_load_dwordx4 v[120:123], v[108:109], off offset:1024
	global_load_dwordx4 v[112:115], v[108:109], off offset:2048
	s_nop 0
	global_load_dwordx4 v[108:111], v[108:109], off offset:3072
	s_nop 0
	global_load_dwordx4 v[172:175], v[116:117], off
	global_load_dwordx4 v[132:135], v[116:117], off offset:1024
	global_load_dwordx4 v[124:127], v[116:117], off offset:2048
	s_nop 0
	global_load_dwordx4 v[116:119], v[116:117], off offset:3072
	s_nop 0
	global_load_dwordx4 v[168:171], v[128:129], off
	global_load_dwordx4 v[148:151], v[128:129], off offset:1024
	global_load_dwordx4 v[140:143], v[128:129], off offset:2048
	s_nop 0
	global_load_dwordx4 v[128:131], v[128:129], off offset:3072
	s_nop 0
	global_load_dwordx4 v[160:163], v[144:145], off
	global_load_dwordx4 v[156:159], v[144:145], off offset:1024
	global_load_dwordx4 v[152:155], v[144:145], off offset:2048
	s_nop 0
	global_load_dwordx4 v[144:147], v[144:145], off offset:3072
	v_fma_f32 v195, v227, v244, v236
	v_bfe_u32 v236, v195, 16, 1
	v_add3_u32 v195, v195, v236, s37
	v_lshl_add_u64 v[252:253], v[218:219], 0, s[4:5]
	global_store_short_d16_hi v[252:253], v195, off
	v_fma_f32 v195, v228, v245, v237
	v_bfe_u32 v236, v195, 16, 1
	v_add3_u32 v195, v195, v236, s37
	v_add_co_u32_e32 v236, vcc, s38, v252
	v_fmac_f32_e32 v239, v230, v247
	s_nop 0
	v_addc_co_u32_e32 v237, vcc, 0, v253, vcc
	global_store_short_d16_hi v[236:237], v195, off offset:-4096
	v_fma_f32 v195, v229, v246, v238
	v_bfe_u32 v238, v195, 16, 1
	v_add3_u32 v195, v195, v238, s37
	global_store_short_d16_hi v[236:237], v195, off
	v_bfe_u32 v195, v239, 16, 1
	v_add_co_u32_e32 v236, vcc, s39, v252
	v_add3_u32 v195, v239, v195, s37
	s_nop 0
	v_addc_co_u32_e32 v237, vcc, 0, v253, vcc
	global_store_short_d16_hi v[236:237], v195, off
	v_fma_f32 v195, v231, v248, v240
	v_bfe_u32 v236, v195, 16, 1
	v_add3_u32 v195, v195, v236, s37
	v_lshl_add_u64 v[236:237], v[216:217], 0, s[4:5]
	global_store_short_d16_hi v[236:237], v195, off
	v_fma_f32 v195, v232, v249, v241
	v_bfe_u32 v238, v195, 16, 1
	v_add3_u32 v195, v195, v238, s37
	v_add_co_u32_e32 v238, vcc, s38, v236
	v_fmac_f32_e32 v243, v234, v251
	s_nop 0
	v_addc_co_u32_e32 v239, vcc, 0, v237, vcc
	global_store_short_d16_hi v[238:239], v195, off offset:-4096
	v_fma_f32 v195, v233, v250, v242
	v_bfe_u32 v240, v195, 16, 1
	v_add3_u32 v195, v195, v240, s37
	global_store_short_d16_hi v[238:239], v195, off
	v_bfe_u32 v195, v243, 16, 1
	v_add_co_u32_e32 v236, vcc, s39, v236
	v_add3_u32 v195, v243, v195, s37
	s_nop 0
	v_addc_co_u32_e32 v237, vcc, 0, v237, vcc
	global_store_short_d16_hi v[236:237], v195, off
	v_and_b32_sdwa v237, v3, v226 dst_sel:DWORD dst_unused:UNUSED_PAD src0_sel:WORD_1 src1_sel:DWORD
	v_and_b32_sdwa v238, v1, v226 dst_sel:DWORD dst_unused:UNUSED_PAD src0_sel:WORD_1 src1_sel:DWORD
	v_and_b32_sdwa v195, v2, v226 dst_sel:DWORD dst_unused:UNUSED_PAD src0_sel:WORD_1 src1_sel:DWORD
	v_and_b32_sdwa v236, v0, v226 dst_sel:DWORD dst_unused:UNUSED_PAD src0_sel:WORD_1 src1_sel:DWORD
	v_add3_u32 v237, v3, v237, s37
	v_add3_u32 v238, v1, v238, s37
	v_add3_u32 v236, v0, v236, s37
	v_add3_u32 v195, v2, v195, s37
	v_and_b32_e32 v237, 0xffff0000, v237
	v_and_b32_e32 v238, 0xffff0000, v238
	v_and_b32_sdwa v239, v191, v226 dst_sel:DWORD dst_unused:UNUSED_PAD src0_sel:WORD_1 src1_sel:DWORD
	v_and_b32_sdwa v240, v189, v226 dst_sel:DWORD dst_unused:UNUSED_PAD src0_sel:WORD_1 src1_sel:DWORD
	v_or_b32_sdwa v237, v237, v195 dst_sel:DWORD dst_unused:UNUSED_PAD src0_sel:DWORD src1_sel:WORD_1
	v_or_b32_sdwa v236, v238, v236 dst_sel:DWORD dst_unused:UNUSED_PAD src0_sel:DWORD src1_sel:WORD_1
	v_and_b32_sdwa v195, v190, v226 dst_sel:DWORD dst_unused:UNUSED_PAD src0_sel:WORD_1 src1_sel:DWORD
	v_and_b32_sdwa v238, v188, v226 dst_sel:DWORD dst_unused:UNUSED_PAD src0_sel:WORD_1 src1_sel:DWORD
	v_add3_u32 v239, v191, v239, s37
	v_add3_u32 v240, v189, v240, s37
	v_add3_u32 v238, v188, v238, s37
	v_add3_u32 v195, v190, v195, s37
	v_and_b32_e32 v239, 0xffff0000, v239
	v_and_b32_e32 v240, 0xffff0000, v240
	v_or_b32_sdwa v239, v239, v195 dst_sel:DWORD dst_unused:UNUSED_PAD src0_sel:DWORD src1_sel:WORD_1
	v_or_b32_sdwa v238, v240, v238 dst_sel:DWORD dst_unused:UNUSED_PAD src0_sel:DWORD src1_sel:WORD_1
	s_waitcnt lgkmcnt(0)
	s_barrier
	ds_write2_b64 v235, v[236:237], v[238:239] offset1:4
	v_and_b32_sdwa v237, v187, v226 dst_sel:DWORD dst_unused:UNUSED_PAD src0_sel:WORD_1 src1_sel:DWORD
	v_and_b32_sdwa v238, v185, v226 dst_sel:DWORD dst_unused:UNUSED_PAD src0_sel:WORD_1 src1_sel:DWORD
	v_and_b32_sdwa v195, v186, v226 dst_sel:DWORD dst_unused:UNUSED_PAD src0_sel:WORD_1 src1_sel:DWORD
	v_and_b32_sdwa v236, v184, v226 dst_sel:DWORD dst_unused:UNUSED_PAD src0_sel:WORD_1 src1_sel:DWORD
	v_add3_u32 v237, v187, v237, s37
	v_add3_u32 v238, v185, v238, s37
	v_add3_u32 v236, v184, v236, s37
	v_add3_u32 v195, v186, v195, s37
	v_and_b32_e32 v237, 0xffff0000, v237
	v_and_b32_e32 v238, 0xffff0000, v238
	v_and_b32_sdwa v239, v183, v226 dst_sel:DWORD dst_unused:UNUSED_PAD src0_sel:WORD_1 src1_sel:DWORD
	v_and_b32_sdwa v240, v181, v226 dst_sel:DWORD dst_unused:UNUSED_PAD src0_sel:WORD_1 src1_sel:DWORD
	v_or_b32_sdwa v237, v237, v195 dst_sel:DWORD dst_unused:UNUSED_PAD src0_sel:DWORD src1_sel:WORD_1
	v_or_b32_sdwa v236, v238, v236 dst_sel:DWORD dst_unused:UNUSED_PAD src0_sel:DWORD src1_sel:WORD_1
	v_and_b32_sdwa v195, v182, v226 dst_sel:DWORD dst_unused:UNUSED_PAD src0_sel:WORD_1 src1_sel:DWORD
	v_and_b32_sdwa v238, v180, v226 dst_sel:DWORD dst_unused:UNUSED_PAD src0_sel:WORD_1 src1_sel:DWORD
	v_add3_u32 v239, v183, v239, s37
	v_add3_u32 v240, v181, v240, s37
	v_add3_u32 v238, v180, v238, s37
	v_add3_u32 v195, v182, v195, s37
	v_and_b32_e32 v239, 0xffff0000, v239
	v_and_b32_e32 v240, 0xffff0000, v240
	v_or_b32_sdwa v239, v239, v195 dst_sel:DWORD dst_unused:UNUSED_PAD src0_sel:DWORD src1_sel:WORD_1
	v_or_b32_sdwa v238, v240, v238 dst_sel:DWORD dst_unused:UNUSED_PAD src0_sel:DWORD src1_sel:WORD_1
	ds_write2_b64 v235, v[236:237], v[238:239] offset0:8 offset1:12
	s_waitcnt lgkmcnt(0)
	s_barrier
	s_add_u32 s4, s4, 0x80000
	s_addc_u32 s5, s5, 0
	s_add_i32 s8, s8, 1
	s_cmp_lg_u32 s4, 0x4000000
	s_cbranch_scc1 .LBB0_389
	s_add_i32 s42, s42, s74
	s_add_i32 s41, s41, s74
	s_add_i32 s40, s40, s74
	s_add_i32 s25, s25, s26
	s_cmpk_lt_i32 s42, 0x100
	s_cbranch_scc1 .LBB0_385

	.amdhsa_kernel _Z6k_mega6Params
		.amdhsa_group_segment_fixed_size 67088
		.amdhsa_private_segment_fixed_size 0
		.amdhsa_kernarg_size 440
		.amdhsa_user_sgpr_count 2
		.amdhsa_user_sgpr_dispatch_ptr 0
		.amdhsa_user_sgpr_queue_ptr 0
		.amdhsa_user_sgpr_kernarg_segment_ptr 1
		.amdhsa_user_sgpr_dispatch_id 0
		.amdhsa_user_sgpr_kernarg_preload_length 0
		.amdhsa_user_sgpr_kernarg_preload_offset 0
		.amdhsa_user_sgpr_private_segment_size 0
		.amdhsa_uses_dynamic_stack 0
		.amdhsa_enable_private_segment 0
		.amdhsa_system_sgpr_workgroup_id_x 1
		.amdhsa_system_sgpr_workgroup_id_y 0
		.amdhsa_system_sgpr_workgroup_id_z 0
		.amdhsa_system_sgpr_workgroup_info 0
		.amdhsa_system_vgpr_workitem_id 2
		.amdhsa_next_free_vgpr 256
		.amdhsa_next_free_sgpr 102
		.amdhsa_accum_offset 256
		.amdhsa_reserve_vcc 1
		.amdhsa_float_round_mode_32 0
		.amdhsa_float_round_mode_16_64 0
		.amdhsa_float_denorm_mode_32 3
		.amdhsa_float_denorm_mode_16_64 3
		.amdhsa_dx10_clamp 1
		.amdhsa_ieee_mode 1
		.amdhsa_fp16_overflow 0
		.amdhsa_tg_split 0
		.amdhsa_exception_fp_ieee_invalid_op 0
		.amdhsa_exception_fp_denorm_src 0
		.amdhsa_exception_fp_ieee_div_zero 0
		.amdhsa_exception_fp_ieee_overflow 0
		.amdhsa_exception_fp_ieee_underflow 0
		.amdhsa_exception_fp_ieee_inexact 0
		.amdhsa_exception_int_div_zero 0
	.end_amdhsa_kernel

amdhsa.kernels:
  - .agpr_count:     0
    .args:
      - .offset:         0
        .size:           184
        .value_kind:     by_value
      - .offset:         184
        .size:           4
        .value_kind:     hidden_block_count_x
      - .offset:         188
        .size:           4
        .value_kind:     hidden_block_count_y
      - .offset:         192
        .size:           4
        .value_kind:     hidden_block_count_z
      - .offset:         196
        .size:           2
        .value_kind:     hidden_group_size_x
      - .offset:         198
        .size:           2
        .value_kind:     hidden_group_size_y
      - .offset:         200
        .size:           2
        .value_kind:     hidden_group_size_z
      - .offset:         202
        .size:           2
        .value_kind:     hidden_remainder_x
      - .offset:         204
        .size:           2
        .value_kind:     hidden_remainder_y
      - .offset:         206
        .size:           2
        .value_kind:     hidden_remainder_z
      - .offset:         224
        .size:           8
        .value_kind:     hidden_global_offset_x
      - .offset:         232
        .size:           8
        .value_kind:     hidden_global_offset_y
      - .offset:         240
        .size:           8
        .value_kind:     hidden_global_offset_z
      - .offset:         248
        .size:           2
        .value_kind:     hidden_grid_dims
      - .offset:         272
        .size:           8
        .value_kind:     hidden_multigrid_sync_arg
    .group_segment_fixed_size: 67088
    .kernarg_segment_align: 8
    .kernarg_segment_size: 440
    .language:       OpenCL C
    .language_version:
      - 2
      - 0
    .max_flat_workgroup_size: 256
    .name:           _Z6k_mega6Params
    .private_segment_fixed_size: 0
    .sgpr_count:     108
    .sgpr_spill_count: 37
    .symbol:         _Z6k_mega6Params.kd
    .uniform_work_group_size: 1
    .uses_dynamic_stack: false
    .vgpr_count:     256
    .vgpr_spill_count: 0
    .wavefront_size: 64
